# step-1 LDS-DMA prefetch with per-piece counted waits (vmcnt 11..8 per quad instead of 8 per group)
# baseline (speedup 1.0000x reference)
;     __device__ __forceinline__ void fused(f32x4 (&acc)[2][2][4][2], const Unit& u, int wr, int wc, int fr, int fq, PG8_LAS unsigned char* lds, int wid, int lane) const {
;     ...
;         const int col0 = u.pn * BM + wc * 32 + 4 * fq;
;         f32x4 gv[2][2];
; #pragma unroll
;         for (int bj = 0; bj < 2; ++bj)
; #pragma unroll
;             for (int n = 0; n < 2; ++n) gv[bj][n] = *(const f32x4*)(g1 + col0 + bj * HALF + n * 16);
; #pragma unroll
;         for (int ai = 0; ai < 2; ++ai)
; #pragma unroll
;             for (int m = 0; m < 4; ++m) { const int r = ai * HALF + wr * 64 + m * 16 + fr; const size_t off = (size_t)(u.pm * BM + r) * 1024 + col0;
;                 float s0 = 0.f, s1 = 0.f, s2 = 0.f, s3 = 0.f;
; #pragma unroll
;                 for (int bj = 0; bj < 2; ++bj)
; #pragma unroll
;                     for (int n = 0; n < 2; ++n) { const f32x4 bs = *(const f32x4*)(base + off + bj * HALF + n * 16), a = acc[ai][bj][m][n], ag = a * gv[bj][n];
;                         s0 += (a[0] * a[0] + a[1] * a[1]) + (a[2] * a[2] + a[3] * a[3]); s1 += (bs[0] * bs[0] + bs[1] * bs[1]) + (bs[2] * bs[2] + bs[3] * bs[3]);
;                         s2 += (bs[0] * ag[0] + bs[1] * ag[1]) + (bs[2] * ag[2] + bs[3] * ag[3]); s3 += (ag[0] * ag[0] + ag[1] * ag[1]) + (ag[2] * ag[2] + ag[3] * ag[3]); }
;                 s0 += __shfl_xor(s0, 16); s0 += __shfl_xor(s0, 32); s1 += __shfl_xor(s1, 16); s1 += __shfl_xor(s1, 32);
;                 s2 += __shfl_xor(s2, 16); s2 += __shfl_xor(s2, 32); s3 += __shfl_xor(s3, 16); s3 += __shfl_xor(s3, 32);
;                 if (fq == 0) P[r * 4 + wc] = (f32x4){s0, s1, s2, s3};
.LBB0_831:
	s_ashr_i32 s17, s16, 31
	s_lshl_b64 s[4:5], s[16:17], 14
	s_add_u32 s28, s28, s4
	s_addc_u32 s29, s29, s5
	s_lshl_b32 s4, s25, 5
	s_lshl_b32 s5, s24, 8
	s_or_b32 s4, s5, s4
	v_lshrrev_b32_e32 v33, 2, v195
	v_and_or_b32 v34, v33, 12, s4
	v_ashrrev_i32_e32 v35, 31, v34
	v_lshlrev_b64 v[148:149], 2, v[34:35]
	v_lshl_add_u64 v[92:93], s[28:29], 0, v[148:149]
	s_mov_b64 s[4:5], 0x1000
	v_lshl_add_u64 v[94:95], v[92:93], 0, s[4:5]
	s_movk_i32 s4, 0x1000
	v_add_co_u32_e32 v92, vcc, s4, v92
	v_and_b32_e32 v150, 64, v233
	s_nop 0
	v_addc_co_u32_e32 v93, vcc, 0, v93, vcc
	v_xor_b32_e32 v33, 16, v233
	v_add_u32_e32 v150, 64, v150
	s_lshl_b32 s17, s18, 8
	v_cmp_lt_i32_e32 vcc, v33, v150
	v_add_u32_e32 v166, s17, v237
	v_ashrrev_i32_e32 v167, 31, v166
	v_cndmask_b32_e32 v33, v233, v33, vcc
	v_lshlrev_b32_e32 v240, 2, v33
	v_xor_b32_e32 v33, 32, v233
	v_cmp_lt_i32_e32 vcc, v33, v150
	v_lshlrev_b64 v[150:151], 12, v[166:167]
	v_lshl_add_u64 v[150:151], s[26:27], 0, v[150:151]
	v_lshl_add_u64 v[164:165], v[150:151], 0, v[148:149]
	s_barrier
	global_load_dwordx4 v[116:119], v[92:93], off
	global_load_dwordx4 v[104:107], v[94:95], off offset:64
	global_load_dwordx4 v[100:103], v[94:95], off offset:512
	s_nop 0
	global_load_dwordx4 v[92:95], v[94:95], off offset:576
	v_pk_mul_f32 v[152:153], v[146:147], v[146:147]
	v_readfirstlane_b32 s72, v228
	s_nop 3
	s_lshr_b32 s72, s72, 6
	s_mul_i32 s72, s72, 0x3000
	s_add_i32 s72, s72, 0x5000
	s_mov_b64 s[98:99], 0x0
	v_lshl_add_u64 v[160:161], v[164:165], 0, s[98:99]
	s_add_i32 m0, s72, 0x0
	s_nop 0
	global_load_lds_dwordx4 v[160:161], off
	s_mov_b64 s[98:99], 0x40
	v_lshl_add_u64 v[160:161], v[164:165], 0, s[98:99]
	s_add_i32 m0, s72, 0x400
	s_nop 0
	global_load_lds_dwordx4 v[160:161], off
	s_mov_b64 s[98:99], 0x200
	v_lshl_add_u64 v[160:161], v[164:165], 0, s[98:99]
	s_add_i32 m0, s72, 0x800
	s_nop 0
	global_load_lds_dwordx4 v[160:161], off
	s_mov_b64 s[98:99], 0x240
	v_lshl_add_u64 v[160:161], v[164:165], 0, s[98:99]
	s_add_i32 m0, s72, 0xc00
	s_nop 0
	global_load_lds_dwordx4 v[160:161], off
	s_mov_b64 s[98:99], 0x10000
	v_lshl_add_u64 v[160:161], v[164:165], 0, s[98:99]
	s_add_i32 m0, s72, 0x1000
	s_nop 0
	global_load_lds_dwordx4 v[160:161], off
	s_mov_b64 s[98:99], 0x10040
	v_lshl_add_u64 v[160:161], v[164:165], 0, s[98:99]
	s_add_i32 m0, s72, 0x1400
	s_nop 0
	global_load_lds_dwordx4 v[160:161], off
	s_mov_b64 s[98:99], 0x10200
	v_lshl_add_u64 v[160:161], v[164:165], 0, s[98:99]
	s_add_i32 m0, s72, 0x1800
	s_nop 0
	global_load_lds_dwordx4 v[160:161], off
	s_mov_b64 s[98:99], 0x10240
	v_lshl_add_u64 v[160:161], v[164:165], 0, s[98:99]
	s_add_i32 m0, s72, 0x1c00
	s_nop 0
	global_load_lds_dwordx4 v[160:161], off
	s_mov_b64 s[98:99], 0x20000
	v_lshl_add_u64 v[160:161], v[164:165], 0, s[98:99]
	s_add_i32 m0, s72, 0x2000
	s_nop 0
	global_load_lds_dwordx4 v[160:161], off
	s_mov_b64 s[98:99], 0x20040
	v_lshl_add_u64 v[160:161], v[164:165], 0, s[98:99]
	s_add_i32 m0, s72, 0x2400
	s_nop 0
	global_load_lds_dwordx4 v[160:161], off
	s_mov_b64 s[98:99], 0x20200
	v_lshl_add_u64 v[160:161], v[164:165], 0, s[98:99]
	s_add_i32 m0, s72, 0x2800
	s_nop 0
	global_load_lds_dwordx4 v[160:161], off
	s_mov_b64 s[98:99], 0x20240
	v_lshl_add_u64 v[160:161], v[164:165], 0, s[98:99]
	s_add_i32 m0, s72, 0x2c00
	s_nop 0
	global_load_lds_dwordx4 v[160:161], off
	s_add_i32 s98, s72, 0x0
	s_waitcnt vmcnt(11)
	v_and_b32_e32 v148, 63, v228
	v_lshl_add_u32 v148, v148, 4, s98
	ds_read_b128 v[148:151], v148
	v_pk_mul_f32 v[154:155], v[144:145], v[144:145]
	v_pk_mul_f32 v[158:159], v[140:141], v[140:141]
	v_pk_mov_b32 v[156:157], v[154:155], v[152:153] op_sel:[1,0]
	v_mov_b32_e32 v155, v153
	v_pk_add_f32 v[172:173], v[156:157], v[154:155]
	v_cndmask_b32_e32 v33, v233, v33, vcc
	v_pk_add_f32 v[172:173], v[172:173], v[172:173] op_sel:[0,1] op_sel_hi:[1,0]
	v_lshlrev_b32_e32 v239, 2, v33
	v_and_b32_e32 v238, 63, v195
	s_lshl_b32 s4, s25, 4
	v_cmp_gt_u32_e32 vcc, 16, v238
	s_add_i32 s19, s4, 0
	s_waitcnt lgkmcnt(0)
	v_pk_mul_f32 v[170:171], v[144:145], v[116:117]
	v_pk_mul_f32 v[176:177], v[142:143], v[106:107]
	v_pk_mul_f32 v[178:179], v[140:141], v[104:105]
	v_pk_mul_f32 v[168:169], v[146:147], v[118:119]
	v_mul_f32_e32 v193, v178, v178
	v_pk_mul_f32 v[152:153], v[150:151], v[150:151]
	v_pk_mul_f32 v[154:155], v[148:149], v[148:149]
	v_mul_f32_e32 v33, v179, v179
	v_pk_mov_b32 v[156:157], v[154:155], v[152:153] op_sel:[1,0]
	v_mov_b32_e32 v155, v153
	v_pk_add_f32 v[152:153], v[156:157], v[154:155]
	v_pk_mul_f32 v[156:157], v[142:143], v[142:143]
	v_pk_add_f32 v[190:191], v[152:153], v[152:153] op_sel_hi:[0,1]
	s_waitcnt vmcnt(10)
	v_and_b32_e32 v152, 63, v228
	v_lshl_add_u32 v152, v152, 4, s98
	ds_read_b128 v[152:155], v152 offset:1024
	v_pk_mov_b32 v[160:161], v[158:159], v[156:157] op_sel:[1,0]
	v_mov_b32_e32 v159, v157
	v_pk_add_f32 v[180:181], v[160:161], v[158:159]
	v_mul_f32_e32 v190, v132, v132
	v_pk_add_f32 v[180:181], v[180:181], v[180:181] op_sel:[0,1] op_sel_hi:[1,0]
	v_pk_mul_f32 v[184:185], v[136:137], v[100:101]
	v_pk_mul_f32 v[182:183], v[138:139], v[102:103]
	v_pk_mul_f32 v[188:189], v[132:133], v[92:93]
	v_pk_mul_f32 v[186:187], v[134:135], v[94:95]
	s_waitcnt lgkmcnt(0)
	v_pk_mul_f32 v[156:157], v[154:155], v[154:155]
	v_pk_mul_f32 v[158:159], v[152:153], v[152:153]
	s_nop 0
	v_pk_mov_b32 v[160:161], v[158:159], v[156:157] op_sel:[1,0]
	v_mov_b32_e32 v159, v157
	v_pk_add_f32 v[156:157], v[160:161], v[158:159]
	s_nop 0
	v_pk_add_f32 v[204:205], v[156:157], v[156:157] op_sel_hi:[0,1]
	v_mul_f32_e32 v156, v176, v176
	v_pk_fma_f32 v[174:175], v[176:177], v[176:177], v[156:157] op_sel_hi:[1,1,0]
	s_waitcnt vmcnt(9)
;     __device__ __forceinline__ void fused(f32x4 (&acc)[2][2][4][2], const Unit& u, int wr, int wc, int fr, int fq, PG8_LAS unsigned char* lds, int wid, int lane) const {
;     ...
;                     for (int n = 0; n < 2; ++n) { const f32x4 bs = *(const f32x4*)(base + off + bj * HALF + n * 16), a = acc[ai][bj][m][n], ag = a * gv[bj][n];
;                         s0 += (a[0] * a[0] + a[1] * a[1]) + (a[2] * a[2] + a[3] * a[3]); s1 += (bs[0] * bs[0] + bs[1] * bs[1]) + (bs[2] * bs[2] + bs[3] * bs[3]);
;                         s2 += (bs[0] * ag[0] + bs[1] * ag[1]) + (bs[2] * ag[2] + bs[3] * ag[3]); s3 += (ag[0] * ag[0] + ag[1] * ag[1]) + (ag[2] * ag[2] + ag[3] * ag[3]); }
;                 s0 += __shfl_xor(s0, 16); s0 += __shfl_xor(s0, 32); s1 += __shfl_xor(s1, 16); s1 += __shfl_xor(s1, 32);
;                 s2 += __shfl_xor(s2, 16); s2 += __shfl_xor(s2, 32); s3 += __shfl_xor(s3, 16); s3 += __shfl_xor(s3, 32);
;                 if (fq == 0) P[r * 4 + wc] = (f32x4){s0, s1, s2, s3};
	v_and_b32_e32 v156, 63, v228
	v_lshl_add_u32 v156, v156, 4, s98
	ds_read_b128 v[156:159], v156 offset:2048
	v_mul_f32_e32 v204, v133, v133
	v_pk_add_f32 v[190:191], v[190:191], v[204:205]
	v_mul_f32_e32 v174, v137, v137
	s_waitcnt lgkmcnt(0)
	v_mul_f32_e32 v160, v156, v156
	v_pk_fma_f32 v[206:207], v[156:157], v[156:157], v[160:161] op_sel_hi:[1,1,0]
	v_mul_f32_e32 v160, v158, v158
	v_pk_fma_f32 v[208:209], v[158:159], v[158:159], v[160:161] op_sel_hi:[1,1,0]
	s_waitcnt vmcnt(8)
	v_and_b32_e32 v160, 63, v228
	v_lshl_add_u32 v160, v160, 4, s98
	ds_read_b128 v[160:163], v160 offset:3072
	v_mul_f32_e32 v206, v134, v134
	v_mul_f32_e32 v208, v135, v135
	v_pk_add_f32 v[204:205], v[206:207], v[208:209]
	s_waitcnt lgkmcnt(0)
	v_mul_f32_e32 v210, v160, v160
	v_pk_add_f32 v[190:191], v[190:191], v[204:205]
	v_pk_fma_f32 v[204:205], v[136:137], v[136:137], v[174:175] op_sel_hi:[1,1,0]
	v_mul_f32_e32 v174, v139, v139
	v_mul_f32_e32 v211, v161, v161
	v_mul_f32_e32 v212, v162, v162
	v_mul_f32_e32 v213, v163, v163
	v_pk_fma_f32 v[206:207], v[138:139], v[138:139], v[174:175] op_sel_hi:[1,1,0]
	v_mov_b32_e32 v205, v210
	v_mov_b32_e32 v207, v211
	v_mov_b32_e32 v181, v212
	v_mov_b32_e32 v173, v213
	v_pk_add_f32 v[204:205], v[204:205], v[206:207]
	v_pk_add_f32 v[172:173], v[180:181], v[172:173]
	s_nop 0
	v_pk_add_f32 v[172:173], v[204:205], v[172:173]
	v_mov_b32_e32 v204, v152
	v_pk_add_f32 v[172:173], v[190:191], v[172:173]
	v_mov_b32_e32 v190, v178
	v_mov_b32_e32 v178, v179
	v_mov_b32_e32 v179, v171
	v_mov_b32_e32 v152, v153
	v_mov_b32_e32 v153, v171
	v_mov_b32_e32 v191, v170
	v_mov_b32_e32 v205, v170
	v_pk_mul_f32 v[152:153], v[178:179], v[152:153]
	v_mov_b32_e32 v178, v176
	v_pk_fma_f32 v[152:153], v[190:191], v[204:205], v[152:153]
	v_mov_b32_e32 v190, v154
	v_mov_b32_e32 v176, v177
	v_mov_b32_e32 v177, v169
	v_mov_b32_e32 v154, v155
	v_mov_b32_e32 v155, v169
	v_mov_b32_e32 v179, v168
	v_mov_b32_e32 v191, v168
	v_pk_mul_f32 v[154:155], v[176:177], v[154:155]
	ds_bpermute_b32 v180, v240, v172
	v_pk_fma_f32 v[154:155], v[178:179], v[190:191], v[154:155]
	ds_bpermute_b32 v181, v240, v173
	v_pk_add_f32 v[152:153], v[152:153], v[154:155]
	v_mul_f32_e32 v154, v171, v149
	v_pk_fma_f32 v[148:149], v[170:171], v[148:149], v[154:155] op_sel_hi:[1,1,0]
	v_mul_f32_e32 v154, v169, v151
	v_pk_fma_f32 v[150:151], v[168:169], v[150:151], v[154:155] op_sel_hi:[1,1,0]
	v_mov_b32_e32 v149, v193
	v_mov_b32_e32 v151, v33
	v_pk_add_f32 v[148:149], v[148:149], v[150:151]
	v_mov_b32_e32 v33, v175
	v_pk_add_f32 v[148:149], v[148:149], v[32:33]
	v_pk_mov_b32 v[150:151], v[156:157], v[184:185] op_sel:[1,0]
	v_mov_b32_e32 v157, v185
	v_pk_add_f32 v[148:149], v[152:153], v[148:149]
	v_pk_mul_f32 v[152:153], v[184:185], v[156:157]
	s_waitcnt lgkmcnt(0)
	v_pk_add_f32 v[172:173], v[172:173], v[180:181]
	v_pk_fma_f32 v[150:151], v[184:185], v[150:151], v[152:153] op_sel:[1,0,0] op_sel_hi:[0,1,1]
	v_pk_mov_b32 v[152:153], v[158:159], v[182:183] op_sel:[1,0]
	v_mov_b32_e32 v159, v183
	v_pk_mul_f32 v[154:155], v[182:183], v[158:159]
	ds_bpermute_b32 v180, v239, v172
	v_pk_fma_f32 v[152:153], v[182:183], v[152:153], v[154:155] op_sel:[1,0,0] op_sel_hi:[0,1,1]
	v_pk_add_f32 v[150:151], v[150:151], v[152:153]
	ds_bpermute_b32 v181, v239, v173
	v_pk_add_f32 v[148:149], v[148:149], v[150:151]
	v_pk_mov_b32 v[150:151], v[160:161], v[188:189] op_sel:[1,0]
	v_mov_b32_e32 v161, v189
	v_pk_mul_f32 v[152:153], v[188:189], v[160:161]
	s_nop 0
	v_pk_fma_f32 v[150:151], v[188:189], v[150:151], v[152:153] op_sel:[1,0,0] op_sel_hi:[0,1,1]
	v_pk_mov_b32 v[152:153], v[162:163], v[186:187] op_sel:[1,0]
	v_mov_b32_e32 v163, v187
	v_pk_mul_f32 v[154:155], v[186:187], v[162:163]
	s_nop 0
	v_pk_fma_f32 v[152:153], v[186:187], v[152:153], v[154:155] op_sel:[1,0,0] op_sel_hi:[0,1,1]
	v_pk_add_f32 v[150:151], v[150:151], v[152:153]
	s_nop 0
	v_pk_add_f32 v[148:149], v[148:149], v[150:151]
	ds_bpermute_b32 v150, v240, v148
	ds_bpermute_b32 v151, v240, v149
	s_waitcnt lgkmcnt(0)
	v_pk_add_f32 v[148:149], v[148:149], v[150:151]
	ds_bpermute_b32 v150, v239, v148
	ds_bpermute_b32 v151, v239, v149
	s_and_saveexec_b64 s[6:7], vcc
	v_readlane_b32 s56, v255, 4
	v_readlane_b32 s58, v255, 6
	v_readlane_b32 s52, v255, 8
	v_readlane_b32 s57, v255, 5
	v_readlane_b32 s59, v255, 7
	v_readlane_b32 s53, v255, 9
	v_readlane_b32 s55, v255, 10
	s_cbranch_execz .LBB0_833
	v_add_u32_e32 v33, s19, v192
	s_waitcnt lgkmcnt(0)
	v_pk_add_f32 v[150:151], v[148:149], v[150:151]
	v_pk_add_f32 v[148:149], v[172:173], v[180:181]
	ds_write_b128 v33, v[148:151]
;     __device__ __forceinline__ void fused(f32x4 (&acc)[2][2][4][2], const Unit& u, int wr, int wc, int fr, int fq, PG8_LAS unsigned char* lds, int wid, int lane) const {
;     ...
;             for (int m = 0; m < 4; ++m) { const int r = ai * HALF + wr * 64 + m * 16 + fr; const size_t off = (size_t)(u.pm * BM + r) * 1024 + col0;
;                 float s0 = 0.f, s1 = 0.f, s2 = 0.f, s3 = 0.f;
; #pragma unroll
;                 for (int bj = 0; bj < 2; ++bj)
; #pragma unroll
;                     for (int n = 0; n < 2; ++n) { const f32x4 bs = *(const f32x4*)(base + off + bj * HALF + n * 16), a = acc[ai][bj][m][n], ag = a * gv[bj][n];
;                         s0 += (a[0] * a[0] + a[1] * a[1]) + (a[2] * a[2] + a[3] * a[3]); s1 += (bs[0] * bs[0] + bs[1] * bs[1]) + (bs[2] * bs[2] + bs[3] * bs[3]);
;                         s2 += (bs[0] * ag[0] + bs[1] * ag[1]) + (bs[2] * ag[2] + bs[3] * ag[3]); s3 += (ag[0] * ag[0] + ag[1] * ag[1]) + (ag[2] * ag[2] + ag[3] * ag[3]); }
;                 s0 += __shfl_xor(s0, 16); s0 += __shfl_xor(s0, 32); s1 += __shfl_xor(s1, 16); s1 += __shfl_xor(s1, 32);
;                 s2 += __shfl_xor(s2, 16); s2 += __shfl_xor(s2, 32); s3 += __shfl_xor(s3, 16); s3 += __shfl_xor(s3, 32);
;                 if (fq == 0) P[r * 4 + wc] = (f32x4){s0, s1, s2, s3};
.LBB0_833:
	s_or_b64 exec, exec, s[6:7]
	s_mov_b64 s[98:99], 0x30000
	v_lshl_add_u64 v[160:161], v[164:165], 0, s[98:99]
	s_add_i32 m0, s72, 0x0
	s_nop 0
	global_load_lds_dwordx4 v[160:161], off
	s_mov_b64 s[98:99], 0x30040
	v_lshl_add_u64 v[160:161], v[164:165], 0, s[98:99]
	s_add_i32 m0, s72, 0x400
	s_nop 0
	global_load_lds_dwordx4 v[160:161], off
	s_mov_b64 s[98:99], 0x30200
	v_lshl_add_u64 v[160:161], v[164:165], 0, s[98:99]
	s_add_i32 m0, s72, 0x800
	s_nop 0
	global_load_lds_dwordx4 v[160:161], off
	s_mov_b64 s[98:99], 0x30240
	v_lshl_add_u64 v[160:161], v[164:165], 0, s[98:99]
	s_add_i32 m0, s72, 0xc00
	s_nop 0
	global_load_lds_dwordx4 v[160:161], off
	v_or_b32_e32 v204, 16, v237
	v_add_u32_e32 v170, s17, v204
	v_ashrrev_i32_e32 v171, 31, v170
	v_lshlrev_b64 v[148:149], 12, v[170:171]
	v_lshl_add_u64 v[148:149], s[26:27], 0, v[148:149]
	v_lshl_add_u64 v[168:169], v[34:35], 2, v[148:149]
	s_waitcnt lgkmcnt(0)
	s_add_i32 s98, s72, 0x1000
	s_waitcnt vmcnt(11)
	v_and_b32_e32 v148, 63, v228
	v_lshl_add_u32 v148, v148, 4, s98
	ds_read_b128 v[148:151], v148
	s_waitcnt vmcnt(10)
	v_and_b32_e32 v160, 63, v228
	v_lshl_add_u32 v160, v160, 4, s98
	ds_read_b128 v[160:163], v160 offset:1024
	v_pk_mul_f32 v[152:153], v[130:131], v[130:131]
	v_pk_mul_f32 v[154:155], v[128:129], v[128:129]
	v_pk_mul_f32 v[186:187], v[126:127], v[106:107]
	v_pk_mov_b32 v[156:157], v[154:155], v[152:153] op_sel:[1,0]
	v_mov_b32_e32 v155, v153
	v_pk_add_f32 v[188:189], v[156:157], v[154:155]
	v_pk_mul_f32 v[174:175], v[128:129], v[116:117]
	v_pk_add_f32 v[188:189], v[188:189], v[188:189] op_sel:[0,1] op_sel_hi:[1,0]
	v_pk_mul_f32 v[192:193], v[124:125], v[104:105]
	v_pk_mul_f32 v[172:173], v[130:131], v[118:119]
	v_mul_f32_e32 v205, v192, v192
	v_mul_f32_e32 v33, v193, v193
	v_pk_mul_f32 v[180:181], v[120:121], v[100:101]
	v_pk_mul_f32 v[178:179], v[122:123], v[102:103]
	v_pk_mul_f32 v[184:185], v[112:113], v[92:93]
	v_pk_mul_f32 v[182:183], v[114:115], v[94:95]
	s_waitcnt lgkmcnt(1)
	v_pk_mul_f32 v[152:153], v[150:151], v[150:151]
	v_pk_mul_f32 v[154:155], v[148:149], v[148:149]
	s_nop 0
	v_pk_mov_b32 v[156:157], v[154:155], v[152:153] op_sel:[1,0]
	v_mov_b32_e32 v155, v153
	v_pk_add_f32 v[152:153], v[156:157], v[154:155]
	v_pk_mul_f32 v[154:155], v[124:125], v[124:125]
	v_pk_add_f32 v[206:207], v[152:153], v[152:153] op_sel_hi:[0,1]
	v_pk_mul_f32 v[152:153], v[126:127], v[126:127]
	v_mul_f32_e32 v206, v112, v112
	v_pk_mov_b32 v[156:157], v[154:155], v[152:153] op_sel:[1,0]
	v_mov_b32_e32 v155, v153
	v_pk_add_f32 v[190:191], v[156:157], v[154:155]
	s_waitcnt lgkmcnt(0)
	v_pk_mul_f32 v[152:153], v[162:163], v[162:163]
	v_pk_mul_f32 v[154:155], v[160:161], v[160:161]
	v_pk_add_f32 v[190:191], v[190:191], v[190:191] op_sel:[0,1] op_sel_hi:[1,0]
	v_pk_mov_b32 v[156:157], v[154:155], v[152:153] op_sel:[1,0]
	v_mov_b32_e32 v155, v153
	v_pk_add_f32 v[152:153], v[156:157], v[154:155]
	s_nop 0
	v_pk_add_f32 v[208:209], v[152:153], v[152:153] op_sel_hi:[0,1]
	v_mul_f32_e32 v152, v186, v186
	v_pk_fma_f32 v[176:177], v[186:187], v[186:187], v[152:153] op_sel_hi:[1,1,0]
	s_waitcnt vmcnt(9)
	v_and_b32_e32 v152, 63, v228
	v_lshl_add_u32 v152, v152, 4, s98
	ds_read_b128 v[152:155], v152 offset:2048
	v_mul_f32_e32 v208, v113, v113
	v_pk_add_f32 v[206:207], v[206:207], v[208:209]
	v_mul_f32_e32 v176, v121, v121
	s_waitcnt lgkmcnt(0)
	v_mul_f32_e32 v156, v152, v152
	v_pk_fma_f32 v[210:211], v[152:153], v[152:153], v[156:157] op_sel_hi:[1,1,0]
	v_mul_f32_e32 v156, v154, v154
	v_pk_fma_f32 v[212:213], v[154:155], v[154:155], v[156:157] op_sel_hi:[1,1,0]
	s_waitcnt vmcnt(8)
	v_and_b32_e32 v156, 63, v228
	v_lshl_add_u32 v156, v156, 4, s98
	ds_read_b128 v[156:159], v156 offset:3072
	v_mul_f32_e32 v210, v114, v114
	v_mul_f32_e32 v212, v115, v115
	v_pk_add_f32 v[208:209], v[210:211], v[212:213]
	s_waitcnt lgkmcnt(0)
	v_mul_f32_e32 v214, v156, v156
	v_pk_add_f32 v[206:207], v[206:207], v[208:209]
	v_pk_fma_f32 v[208:209], v[120:121], v[120:121], v[176:177] op_sel_hi:[1,1,0]
	v_mul_f32_e32 v176, v123, v123
	v_mul_f32_e32 v215, v157, v157
	v_mul_f32_e32 v216, v158, v158
	v_mul_f32_e32 v217, v159, v159
	v_pk_fma_f32 v[210:211], v[122:123], v[122:123], v[176:177] op_sel_hi:[1,1,0]
	v_mov_b32_e32 v209, v214
	v_mov_b32_e32 v211, v215
	v_mov_b32_e32 v191, v216
	v_mov_b32_e32 v189, v217
	v_pk_add_f32 v[208:209], v[208:209], v[210:211]
	v_pk_add_f32 v[188:189], v[190:191], v[188:189]
	s_nop 0
	v_pk_add_f32 v[188:189], v[208:209], v[188:189]
	v_mov_b32_e32 v208, v160
	v_pk_add_f32 v[188:189], v[206:207], v[188:189]
	v_mov_b32_e32 v206, v192
	v_mov_b32_e32 v192, v193
	v_mov_b32_e32 v193, v175
	v_mov_b32_e32 v160, v161
	v_mov_b32_e32 v161, v175
	v_mov_b32_e32 v207, v174
	v_mov_b32_e32 v209, v174
	v_pk_mul_f32 v[160:161], v[192:193], v[160:161]
	v_mov_b32_e32 v192, v186
	v_pk_fma_f32 v[160:161], v[206:207], v[208:209], v[160:161]
	v_mov_b32_e32 v206, v162
	v_mov_b32_e32 v186, v187
	v_mov_b32_e32 v187, v173
	v_mov_b32_e32 v162, v163
	v_mov_b32_e32 v163, v173
	v_mov_b32_e32 v193, v172
	v_mov_b32_e32 v207, v172
	v_pk_mul_f32 v[162:163], v[186:187], v[162:163]
	ds_bpermute_b32 v190, v240, v188
	v_pk_fma_f32 v[162:163], v[192:193], v[206:207], v[162:163]
	ds_bpermute_b32 v191, v240, v189
	v_pk_add_f32 v[160:161], v[160:161], v[162:163]
	v_mul_f32_e32 v162, v175, v149
	v_pk_fma_f32 v[148:149], v[174:175], v[148:149], v[162:163] op_sel_hi:[1,1,0]
	v_mul_f32_e32 v162, v173, v151
	v_pk_fma_f32 v[150:151], v[172:173], v[150:151], v[162:163] op_sel_hi:[1,1,0]
	v_mov_b32_e32 v149, v205
	v_mov_b32_e32 v151, v33
	v_pk_add_f32 v[148:149], v[148:149], v[150:151]
	v_pk_mov_b32 v[150:151], v[152:153], v[180:181] op_sel:[1,0]
	v_mov_b32_e32 v153, v181
	v_pk_mul_f32 v[152:153], v[180:181], v[152:153]
	v_mov_b32_e32 v33, v177
	v_pk_fma_f32 v[150:151], v[180:181], v[150:151], v[152:153] op_sel:[1,0,0] op_sel_hi:[0,1,1]
	v_pk_mov_b32 v[152:153], v[154:155], v[178:179] op_sel:[1,0]
	v_mov_b32_e32 v155, v179
	v_pk_mul_f32 v[154:155], v[178:179], v[154:155]
	v_pk_add_f32 v[148:149], v[148:149], v[32:33]
	v_pk_fma_f32 v[152:153], v[178:179], v[152:153], v[154:155] op_sel:[1,0,0] op_sel_hi:[0,1,1]
	v_pk_add_f32 v[148:149], v[160:161], v[148:149]
	v_pk_add_f32 v[150:151], v[150:151], v[152:153]
	s_waitcnt lgkmcnt(0)
;     __device__ __forceinline__ void fused(f32x4 (&acc)[2][2][4][2], const Unit& u, int wr, int wc, int fr, int fq, PG8_LAS unsigned char* lds, int wid, int lane) const {
;     ...
;             for (int m = 0; m < 4; ++m) { const int r = ai * HALF + wr * 64 + m * 16 + fr; const size_t off = (size_t)(u.pm * BM + r) * 1024 + col0;
;                 float s0 = 0.f, s1 = 0.f, s2 = 0.f, s3 = 0.f;
; #pragma unroll
;                 for (int bj = 0; bj < 2; ++bj)
; #pragma unroll
;                     for (int n = 0; n < 2; ++n) { const f32x4 bs = *(const f32x4*)(base + off + bj * HALF + n * 16), a = acc[ai][bj][m][n], ag = a * gv[bj][n];
;                         s0 += (a[0] * a[0] + a[1] * a[1]) + (a[2] * a[2] + a[3] * a[3]); s1 += (bs[0] * bs[0] + bs[1] * bs[1]) + (bs[2] * bs[2] + bs[3] * bs[3]);
;                         s2 += (bs[0] * ag[0] + bs[1] * ag[1]) + (bs[2] * ag[2] + bs[3] * ag[3]); s3 += (ag[0] * ag[0] + ag[1] * ag[1]) + (ag[2] * ag[2] + ag[3] * ag[3]); }
;                 s0 += __shfl_xor(s0, 16); s0 += __shfl_xor(s0, 32); s1 += __shfl_xor(s1, 16); s1 += __shfl_xor(s1, 32);
;                 s2 += __shfl_xor(s2, 16); s2 += __shfl_xor(s2, 32); s3 += __shfl_xor(s3, 16); s3 += __shfl_xor(s3, 32);
;                 if (fq == 0) P[r * 4 + wc] = (f32x4){s0, s1, s2, s3};
	v_pk_add_f32 v[188:189], v[188:189], v[190:191]
	v_pk_add_f32 v[148:149], v[148:149], v[150:151]
	v_pk_mov_b32 v[150:151], v[156:157], v[184:185] op_sel:[1,0]
	v_mov_b32_e32 v157, v185
	v_pk_mul_f32 v[152:153], v[184:185], v[156:157]
	ds_bpermute_b32 v190, v239, v188
	v_pk_fma_f32 v[150:151], v[184:185], v[150:151], v[152:153] op_sel:[1,0,0] op_sel_hi:[0,1,1]
	v_pk_mov_b32 v[152:153], v[158:159], v[182:183] op_sel:[1,0]
	v_mov_b32_e32 v159, v183
	v_pk_mul_f32 v[154:155], v[182:183], v[158:159]
	ds_bpermute_b32 v191, v239, v189
	v_pk_fma_f32 v[152:153], v[182:183], v[152:153], v[154:155] op_sel:[1,0,0] op_sel_hi:[0,1,1]
	v_pk_add_f32 v[150:151], v[150:151], v[152:153]
	s_nop 0
	v_pk_add_f32 v[148:149], v[148:149], v[150:151]
	ds_bpermute_b32 v150, v240, v148
	ds_bpermute_b32 v151, v240, v149
	s_waitcnt lgkmcnt(0)
	v_pk_add_f32 v[148:149], v[148:149], v[150:151]
	ds_bpermute_b32 v150, v239, v148
	ds_bpermute_b32 v151, v239, v149
	s_and_saveexec_b64 s[6:7], vcc
	s_cbranch_execz .LBB0_835
	v_lshl_add_u32 v33, v204, 6, s19
	s_waitcnt lgkmcnt(0)
	v_pk_add_f32 v[150:151], v[148:149], v[150:151]
	v_pk_add_f32 v[148:149], v[188:189], v[190:191]
	ds_write_b128 v33, v[148:151]
.LBB0_835:
	s_or_b64 exec, exec, s[6:7]
	s_mov_b64 s[98:99], 0x80000
	v_lshl_add_u64 v[160:161], v[164:165], 0, s[98:99]
	s_add_i32 m0, s72, 0x1000
	s_nop 0
	global_load_lds_dwordx4 v[160:161], off
	s_mov_b64 s[98:99], 0x80040
	v_lshl_add_u64 v[160:161], v[164:165], 0, s[98:99]
	s_add_i32 m0, s72, 0x1400
	s_nop 0
	global_load_lds_dwordx4 v[160:161], off
	s_mov_b64 s[98:99], 0x80200
	v_lshl_add_u64 v[160:161], v[164:165], 0, s[98:99]
	s_add_i32 m0, s72, 0x1800
	s_nop 0
	global_load_lds_dwordx4 v[160:161], off
	s_mov_b64 s[98:99], 0x80240
	v_lshl_add_u64 v[160:161], v[164:165], 0, s[98:99]
	s_add_i32 m0, s72, 0x1c00
	s_nop 0
	global_load_lds_dwordx4 v[160:161], off
	v_or_b32_e32 v208, 32, v237
	v_add_u32_e32 v174, s17, v208
	v_ashrrev_i32_e32 v175, 31, v174
	v_lshlrev_b64 v[148:149], 12, v[174:175]
	v_lshl_add_u64 v[148:149], s[26:27], 0, v[148:149]
	v_lshl_add_u64 v[172:173], v[34:35], 2, v[148:149]
	s_waitcnt lgkmcnt(0)
	s_add_i32 s98, s72, 0x2000
	s_waitcnt vmcnt(11)
	v_and_b32_e32 v148, 63, v228
	v_lshl_add_u32 v148, v148, 4, s98
	ds_read_b128 v[148:151], v148
	s_waitcnt vmcnt(10)
	v_and_b32_e32 v160, 63, v228
	v_lshl_add_u32 v160, v160, 4, s98
	ds_read_b128 v[160:163], v160 offset:1024
	v_pk_mul_f32 v[152:153], v[110:111], v[110:111]
	v_pk_mul_f32 v[154:155], v[108:109], v[108:109]
	v_pk_mul_f32 v[190:191], v[98:99], v[106:107]
	v_pk_mov_b32 v[156:157], v[154:155], v[152:153] op_sel:[1,0]
	v_mov_b32_e32 v155, v153
	v_pk_add_f32 v[192:193], v[156:157], v[154:155]
	v_pk_mul_f32 v[178:179], v[108:109], v[116:117]
	v_pk_add_f32 v[192:193], v[192:193], v[192:193] op_sel:[0,1] op_sel_hi:[1,0]
	v_pk_mul_f32 v[206:207], v[96:97], v[104:105]
	v_pk_mul_f32 v[176:177], v[110:111], v[118:119]
	v_mul_f32_e32 v209, v206, v206
	v_mul_f32_e32 v33, v207, v207
	v_pk_mul_f32 v[184:185], v[88:89], v[100:101]
	v_pk_mul_f32 v[182:183], v[90:91], v[102:103]
	v_pk_mul_f32 v[188:189], v[84:85], v[92:93]
	v_pk_mul_f32 v[186:187], v[86:87], v[94:95]
	s_waitcnt lgkmcnt(1)
	v_pk_mul_f32 v[152:153], v[150:151], v[150:151]
	v_pk_mul_f32 v[154:155], v[148:149], v[148:149]
	s_nop 0
	v_pk_mov_b32 v[156:157], v[154:155], v[152:153] op_sel:[1,0]
	v_mov_b32_e32 v155, v153
	v_pk_add_f32 v[152:153], v[156:157], v[154:155]
	v_pk_mul_f32 v[154:155], v[96:97], v[96:97]
	v_pk_add_f32 v[210:211], v[152:153], v[152:153] op_sel_hi:[0,1]
	v_pk_mul_f32 v[152:153], v[98:99], v[98:99]
	v_mul_f32_e32 v210, v84, v84
	v_pk_mov_b32 v[156:157], v[154:155], v[152:153] op_sel:[1,0]
	v_mov_b32_e32 v155, v153
	v_pk_add_f32 v[204:205], v[156:157], v[154:155]
	s_waitcnt lgkmcnt(0)
	v_pk_mul_f32 v[152:153], v[162:163], v[162:163]
	v_pk_mul_f32 v[154:155], v[160:161], v[160:161]
	v_pk_add_f32 v[204:205], v[204:205], v[204:205] op_sel:[0,1] op_sel_hi:[1,0]
	v_pk_mov_b32 v[156:157], v[154:155], v[152:153] op_sel:[1,0]
	v_mov_b32_e32 v155, v153
	v_pk_add_f32 v[152:153], v[156:157], v[154:155]
	s_nop 0
	v_pk_add_f32 v[212:213], v[152:153], v[152:153] op_sel_hi:[0,1]
	v_mul_f32_e32 v152, v190, v190
	v_pk_fma_f32 v[180:181], v[190:191], v[190:191], v[152:153] op_sel_hi:[1,1,0]
	s_waitcnt vmcnt(9)
	v_and_b32_e32 v152, 63, v228
	v_lshl_add_u32 v152, v152, 4, s98
	ds_read_b128 v[152:155], v152 offset:2048
	v_mul_f32_e32 v212, v85, v85
	v_pk_add_f32 v[210:211], v[210:211], v[212:213]
	v_mul_f32_e32 v180, v89, v89
	s_waitcnt lgkmcnt(0)
	v_mul_f32_e32 v156, v152, v152
	v_pk_fma_f32 v[214:215], v[152:153], v[152:153], v[156:157] op_sel_hi:[1,1,0]
	v_mul_f32_e32 v156, v154, v154
	v_pk_fma_f32 v[216:217], v[154:155], v[154:155], v[156:157] op_sel_hi:[1,1,0]
	s_waitcnt vmcnt(8)
	v_and_b32_e32 v156, 63, v228
	v_lshl_add_u32 v156, v156, 4, s98
	ds_read_b128 v[156:159], v156 offset:3072
	v_mul_f32_e32 v214, v86, v86
	v_mul_f32_e32 v216, v87, v87
	v_pk_add_f32 v[212:213], v[214:215], v[216:217]
	s_waitcnt lgkmcnt(0)
;     __device__ __forceinline__ void fused(f32x4 (&acc)[2][2][4][2], const Unit& u, int wr, int wc, int fr, int fq, PG8_LAS unsigned char* lds, int wid, int lane) const {
;     ...
;             for (int m = 0; m < 4; ++m) { const int r = ai * HALF + wr * 64 + m * 16 + fr; const size_t off = (size_t)(u.pm * BM + r) * 1024 + col0;
;                 float s0 = 0.f, s1 = 0.f, s2 = 0.f, s3 = 0.f;
; #pragma unroll
;                 for (int bj = 0; bj < 2; ++bj)
; #pragma unroll
;                     for (int n = 0; n < 2; ++n) { const f32x4 bs = *(const f32x4*)(base + off + bj * HALF + n * 16), a = acc[ai][bj][m][n], ag = a * gv[bj][n];
;                         s0 += (a[0] * a[0] + a[1] * a[1]) + (a[2] * a[2] + a[3] * a[3]); s1 += (bs[0] * bs[0] + bs[1] * bs[1]) + (bs[2] * bs[2] + bs[3] * bs[3]);
;                         s2 += (bs[0] * ag[0] + bs[1] * ag[1]) + (bs[2] * ag[2] + bs[3] * ag[3]); s3 += (ag[0] * ag[0] + ag[1] * ag[1]) + (ag[2] * ag[2] + ag[3] * ag[3]); }
;                 s0 += __shfl_xor(s0, 16); s0 += __shfl_xor(s0, 32); s1 += __shfl_xor(s1, 16); s1 += __shfl_xor(s1, 32);
;                 s2 += __shfl_xor(s2, 16); s2 += __shfl_xor(s2, 32); s3 += __shfl_xor(s3, 16); s3 += __shfl_xor(s3, 32);
;                 if (fq == 0) P[r * 4 + wc] = (f32x4){s0, s1, s2, s3};
	v_mul_f32_e32 v218, v156, v156
	v_pk_add_f32 v[210:211], v[210:211], v[212:213]
	v_pk_fma_f32 v[212:213], v[88:89], v[88:89], v[180:181] op_sel_hi:[1,1,0]
	v_mul_f32_e32 v180, v91, v91
	v_mul_f32_e32 v219, v157, v157
	v_mul_f32_e32 v220, v158, v158
	v_mul_f32_e32 v221, v159, v159
	v_pk_fma_f32 v[214:215], v[90:91], v[90:91], v[180:181] op_sel_hi:[1,1,0]
	v_mov_b32_e32 v213, v218
	v_mov_b32_e32 v215, v219
	v_mov_b32_e32 v205, v220
	v_mov_b32_e32 v193, v221
	v_pk_add_f32 v[212:213], v[212:213], v[214:215]
	v_pk_add_f32 v[192:193], v[204:205], v[192:193]
	s_nop 0
	v_pk_add_f32 v[192:193], v[212:213], v[192:193]
	v_mov_b32_e32 v212, v160
	v_pk_add_f32 v[192:193], v[210:211], v[192:193]
	v_mov_b32_e32 v210, v206
	v_mov_b32_e32 v206, v207
	v_mov_b32_e32 v207, v179
	v_mov_b32_e32 v160, v161
	v_mov_b32_e32 v161, v179
	v_mov_b32_e32 v211, v178
	v_mov_b32_e32 v213, v178
	v_pk_mul_f32 v[160:161], v[206:207], v[160:161]
	v_mov_b32_e32 v206, v190
	v_pk_fma_f32 v[160:161], v[210:211], v[212:213], v[160:161]
	v_mov_b32_e32 v210, v162
	v_mov_b32_e32 v190, v191
	v_mov_b32_e32 v191, v177
	v_mov_b32_e32 v162, v163
	v_mov_b32_e32 v163, v177
	v_mov_b32_e32 v207, v176
	v_mov_b32_e32 v211, v176
	v_pk_mul_f32 v[162:163], v[190:191], v[162:163]
	ds_bpermute_b32 v204, v240, v192
	v_pk_fma_f32 v[162:163], v[206:207], v[210:211], v[162:163]
	ds_bpermute_b32 v205, v240, v193
	v_pk_add_f32 v[160:161], v[160:161], v[162:163]
	v_mul_f32_e32 v162, v179, v149
	v_pk_fma_f32 v[148:149], v[178:179], v[148:149], v[162:163] op_sel_hi:[1,1,0]
	v_mul_f32_e32 v162, v177, v151
	v_pk_fma_f32 v[150:151], v[176:177], v[150:151], v[162:163] op_sel_hi:[1,1,0]
	v_mov_b32_e32 v149, v209
	v_mov_b32_e32 v151, v33
	v_pk_add_f32 v[148:149], v[148:149], v[150:151]
	v_pk_mov_b32 v[150:151], v[152:153], v[184:185] op_sel:[1,0]
	v_mov_b32_e32 v153, v185
	v_pk_mul_f32 v[152:153], v[184:185], v[152:153]
	v_mov_b32_e32 v33, v181
	v_pk_fma_f32 v[150:151], v[184:185], v[150:151], v[152:153] op_sel:[1,0,0] op_sel_hi:[0,1,1]
	v_pk_mov_b32 v[152:153], v[154:155], v[182:183] op_sel:[1,0]
	v_mov_b32_e32 v155, v183
	v_pk_mul_f32 v[154:155], v[182:183], v[154:155]
	v_pk_add_f32 v[148:149], v[148:149], v[32:33]
	v_pk_fma_f32 v[152:153], v[182:183], v[152:153], v[154:155] op_sel:[1,0,0] op_sel_hi:[0,1,1]
	v_pk_add_f32 v[148:149], v[160:161], v[148:149]
	v_pk_add_f32 v[150:151], v[150:151], v[152:153]
	s_waitcnt lgkmcnt(0)
	v_pk_add_f32 v[192:193], v[192:193], v[204:205]
	v_pk_add_f32 v[148:149], v[148:149], v[150:151]
	v_pk_mov_b32 v[150:151], v[156:157], v[188:189] op_sel:[1,0]
	v_mov_b32_e32 v157, v189
	v_pk_mul_f32 v[152:153], v[188:189], v[156:157]
	ds_bpermute_b32 v204, v239, v192
	v_pk_fma_f32 v[150:151], v[188:189], v[150:151], v[152:153] op_sel:[1,0,0] op_sel_hi:[0,1,1]
	v_pk_mov_b32 v[152:153], v[158:159], v[186:187] op_sel:[1,0]
	v_mov_b32_e32 v159, v187
	v_pk_mul_f32 v[154:155], v[186:187], v[158:159]
	ds_bpermute_b32 v205, v239, v193
	v_pk_fma_f32 v[152:153], v[186:187], v[152:153], v[154:155] op_sel:[1,0,0] op_sel_hi:[0,1,1]
	v_pk_add_f32 v[150:151], v[150:151], v[152:153]
	s_nop 0
	v_pk_add_f32 v[148:149], v[148:149], v[150:151]
	ds_bpermute_b32 v150, v240, v148
	ds_bpermute_b32 v151, v240, v149
	s_waitcnt lgkmcnt(0)
	v_pk_add_f32 v[148:149], v[148:149], v[150:151]
	ds_bpermute_b32 v150, v239, v148
	ds_bpermute_b32 v151, v239, v149
	s_and_saveexec_b64 s[6:7], vcc
	s_cbranch_execz .LBB0_837
	v_lshl_add_u32 v33, v208, 6, s19
	s_waitcnt lgkmcnt(0)
	v_pk_add_f32 v[150:151], v[148:149], v[150:151]
	v_pk_add_f32 v[148:149], v[192:193], v[204:205]
	ds_write_b128 v33, v[148:151]
.LBB0_837:
	s_or_b64 exec, exec, s[6:7]
	s_mov_b64 s[98:99], 0x90000
	v_lshl_add_u64 v[160:161], v[164:165], 0, s[98:99]
	s_add_i32 m0, s72, 0x2000
	s_nop 0
	global_load_lds_dwordx4 v[160:161], off
	s_mov_b64 s[98:99], 0x90040
	v_lshl_add_u64 v[160:161], v[164:165], 0, s[98:99]
	s_add_i32 m0, s72, 0x2400
	s_nop 0
	global_load_lds_dwordx4 v[160:161], off
	s_mov_b64 s[98:99], 0x90200
	v_lshl_add_u64 v[160:161], v[164:165], 0, s[98:99]
	s_add_i32 m0, s72, 0x2800
	s_nop 0
	global_load_lds_dwordx4 v[160:161], off
	s_mov_b64 s[98:99], 0x90240
	v_lshl_add_u64 v[160:161], v[164:165], 0, s[98:99]
	s_add_i32 m0, s72, 0x2c00
	s_nop 0
	global_load_lds_dwordx4 v[160:161], off
	v_or_b32_e32 v212, 48, v237
	v_add_u32_e32 v178, s17, v212
	v_ashrrev_i32_e32 v179, 31, v178
	v_lshlrev_b64 v[148:149], 12, v[178:179]
	v_lshl_add_u64 v[148:149], s[26:27], 0, v[148:149]
	v_lshl_add_u64 v[176:177], v[34:35], 2, v[148:149]
	s_waitcnt lgkmcnt(0)
	s_add_i32 s98, s72, 0x0
	s_waitcnt vmcnt(11)
	v_and_b32_e32 v148, 63, v228
	v_lshl_add_u32 v148, v148, 4, s98
	ds_read_b128 v[148:151], v148
	s_waitcnt vmcnt(10)
	v_and_b32_e32 v160, 63, v228
	v_lshl_add_u32 v160, v160, 4, s98
	ds_read_b128 v[160:163], v160 offset:1024
	v_pk_mul_f32 v[152:153], v[82:83], v[82:83]
	v_pk_mul_f32 v[154:155], v[80:81], v[80:81]
	v_pk_mul_f32 v[204:205], v[78:79], v[106:107]
	v_pk_mov_b32 v[156:157], v[154:155], v[152:153] op_sel:[1,0]
	v_mov_b32_e32 v155, v153
	v_pk_add_f32 v[206:207], v[156:157], v[154:155]
	v_pk_mul_f32 v[182:183], v[80:81], v[116:117]
	v_pk_add_f32 v[206:207], v[206:207], v[206:207] op_sel:[0,1] op_sel_hi:[1,0]
	v_pk_mul_f32 v[210:211], v[76:77], v[104:105]
	v_pk_mul_f32 v[180:181], v[82:83], v[118:119]
	v_mul_f32_e32 v213, v210, v210
	v_mul_f32_e32 v33, v211, v211
	v_pk_mul_f32 v[188:189], v[72:73], v[100:101]
	v_pk_mul_f32 v[186:187], v[74:75], v[102:103]
	v_pk_mul_f32 v[192:193], v[68:69], v[92:93]
	v_pk_mul_f32 v[190:191], v[70:71], v[94:95]
	s_waitcnt lgkmcnt(1)
;     __device__ __forceinline__ void fused(f32x4 (&acc)[2][2][4][2], const Unit& u, int wr, int wc, int fr, int fq, PG8_LAS unsigned char* lds, int wid, int lane) const {
;     ...
;                     for (int n = 0; n < 2; ++n) { const f32x4 bs = *(const f32x4*)(base + off + bj * HALF + n * 16), a = acc[ai][bj][m][n], ag = a * gv[bj][n];
;                         s0 += (a[0] * a[0] + a[1] * a[1]) + (a[2] * a[2] + a[3] * a[3]); s1 += (bs[0] * bs[0] + bs[1] * bs[1]) + (bs[2] * bs[2] + bs[3] * bs[3]);
;                         s2 += (bs[0] * ag[0] + bs[1] * ag[1]) + (bs[2] * ag[2] + bs[3] * ag[3]); s3 += (ag[0] * ag[0] + ag[1] * ag[1]) + (ag[2] * ag[2] + ag[3] * ag[3]); }
;                 s0 += __shfl_xor(s0, 16); s0 += __shfl_xor(s0, 32); s1 += __shfl_xor(s1, 16); s1 += __shfl_xor(s1, 32);
;                 s2 += __shfl_xor(s2, 16); s2 += __shfl_xor(s2, 32); s3 += __shfl_xor(s3, 16); s3 += __shfl_xor(s3, 32);
;                 if (fq == 0) P[r * 4 + wc] = (f32x4){s0, s1, s2, s3};
	v_pk_mul_f32 v[152:153], v[150:151], v[150:151]
	v_pk_mul_f32 v[154:155], v[148:149], v[148:149]
	s_nop 0
	v_pk_mov_b32 v[156:157], v[154:155], v[152:153] op_sel:[1,0]
	v_mov_b32_e32 v155, v153
	v_pk_add_f32 v[152:153], v[156:157], v[154:155]
	v_pk_mul_f32 v[154:155], v[76:77], v[76:77]
	v_pk_add_f32 v[214:215], v[152:153], v[152:153] op_sel_hi:[0,1]
	v_pk_mul_f32 v[152:153], v[78:79], v[78:79]
	v_mul_f32_e32 v214, v68, v68
	v_pk_mov_b32 v[156:157], v[154:155], v[152:153] op_sel:[1,0]
	v_mov_b32_e32 v155, v153
	v_pk_add_f32 v[208:209], v[156:157], v[154:155]
	s_waitcnt lgkmcnt(0)
	v_pk_mul_f32 v[152:153], v[162:163], v[162:163]
	v_pk_mul_f32 v[154:155], v[160:161], v[160:161]
	v_pk_add_f32 v[208:209], v[208:209], v[208:209] op_sel:[0,1] op_sel_hi:[1,0]
	v_pk_mov_b32 v[156:157], v[154:155], v[152:153] op_sel:[1,0]
	v_mov_b32_e32 v155, v153
	v_pk_add_f32 v[152:153], v[156:157], v[154:155]
	s_nop 0
	v_pk_add_f32 v[216:217], v[152:153], v[152:153] op_sel_hi:[0,1]
	v_mul_f32_e32 v152, v204, v204
	v_pk_fma_f32 v[184:185], v[204:205], v[204:205], v[152:153] op_sel_hi:[1,1,0]
	s_waitcnt vmcnt(9)
	v_and_b32_e32 v152, 63, v228
	v_lshl_add_u32 v152, v152, 4, s98
	ds_read_b128 v[152:155], v152 offset:2048
	v_mul_f32_e32 v216, v69, v69
	v_pk_add_f32 v[214:215], v[214:215], v[216:217]
	v_mul_f32_e32 v184, v73, v73
	s_waitcnt lgkmcnt(0)
	v_mul_f32_e32 v156, v152, v152
	v_pk_fma_f32 v[218:219], v[152:153], v[152:153], v[156:157] op_sel_hi:[1,1,0]
	v_mul_f32_e32 v156, v154, v154
	v_pk_fma_f32 v[220:221], v[154:155], v[154:155], v[156:157] op_sel_hi:[1,1,0]
	s_waitcnt vmcnt(8)
	v_and_b32_e32 v156, 63, v228
	v_lshl_add_u32 v156, v156, 4, s98
	ds_read_b128 v[156:159], v156 offset:3072
	v_mul_f32_e32 v218, v70, v70
	v_mul_f32_e32 v220, v71, v71
	v_pk_add_f32 v[216:217], v[218:219], v[220:221]
	s_waitcnt lgkmcnt(0)
	v_mul_f32_e32 v222, v156, v156
	v_pk_add_f32 v[214:215], v[214:215], v[216:217]
	v_pk_fma_f32 v[216:217], v[72:73], v[72:73], v[184:185] op_sel_hi:[1,1,0]
	v_mul_f32_e32 v184, v75, v75
	v_mul_f32_e32 v223, v157, v157
	v_mul_f32_e32 v224, v158, v158
	v_mul_f32_e32 v225, v159, v159
	v_pk_fma_f32 v[218:219], v[74:75], v[74:75], v[184:185] op_sel_hi:[1,1,0]
	v_mov_b32_e32 v217, v222
	v_mov_b32_e32 v219, v223
	v_mov_b32_e32 v209, v224
	v_mov_b32_e32 v207, v225
	v_pk_add_f32 v[216:217], v[216:217], v[218:219]
	v_pk_add_f32 v[206:207], v[208:209], v[206:207]
	s_nop 0
	v_pk_add_f32 v[206:207], v[216:217], v[206:207]
	v_mov_b32_e32 v216, v160
	v_pk_add_f32 v[206:207], v[214:215], v[206:207]
	v_mov_b32_e32 v214, v210
	v_mov_b32_e32 v210, v211
	v_mov_b32_e32 v211, v183
	v_mov_b32_e32 v160, v161
	v_mov_b32_e32 v161, v183
	v_mov_b32_e32 v215, v182
	v_mov_b32_e32 v217, v182
	v_pk_mul_f32 v[160:161], v[210:211], v[160:161]
	v_mov_b32_e32 v210, v204
	v_pk_fma_f32 v[160:161], v[214:215], v[216:217], v[160:161]
	v_mov_b32_e32 v214, v162
	v_mov_b32_e32 v204, v205
	v_mov_b32_e32 v205, v181
	v_mov_b32_e32 v162, v163
	v_mov_b32_e32 v163, v181
	v_mov_b32_e32 v211, v180
	v_mov_b32_e32 v215, v180
	v_pk_mul_f32 v[162:163], v[204:205], v[162:163]
	ds_bpermute_b32 v208, v240, v206
	v_pk_fma_f32 v[162:163], v[210:211], v[214:215], v[162:163]
	ds_bpermute_b32 v209, v240, v207
	v_pk_add_f32 v[160:161], v[160:161], v[162:163]
	v_mul_f32_e32 v162, v183, v149
	v_pk_fma_f32 v[148:149], v[182:183], v[148:149], v[162:163] op_sel_hi:[1,1,0]
	v_mul_f32_e32 v162, v181, v151
	v_pk_fma_f32 v[150:151], v[180:181], v[150:151], v[162:163] op_sel_hi:[1,1,0]
	v_mov_b32_e32 v149, v213
	v_mov_b32_e32 v151, v33
	v_pk_add_f32 v[148:149], v[148:149], v[150:151]
	v_pk_mov_b32 v[150:151], v[152:153], v[188:189] op_sel:[1,0]
	v_mov_b32_e32 v153, v189
	v_pk_mul_f32 v[152:153], v[188:189], v[152:153]
	v_mov_b32_e32 v33, v185
	v_pk_fma_f32 v[150:151], v[188:189], v[150:151], v[152:153] op_sel:[1,0,0] op_sel_hi:[0,1,1]
	v_pk_mov_b32 v[152:153], v[154:155], v[186:187] op_sel:[1,0]
	v_mov_b32_e32 v155, v187
	v_pk_mul_f32 v[154:155], v[186:187], v[154:155]
	v_pk_add_f32 v[148:149], v[148:149], v[32:33]
	v_pk_fma_f32 v[152:153], v[186:187], v[152:153], v[154:155] op_sel:[1,0,0] op_sel_hi:[0,1,1]
	v_pk_add_f32 v[148:149], v[160:161], v[148:149]
	v_pk_add_f32 v[150:151], v[150:151], v[152:153]
	s_waitcnt lgkmcnt(0)
	v_pk_add_f32 v[206:207], v[206:207], v[208:209]
	v_pk_add_f32 v[148:149], v[148:149], v[150:151]
	v_pk_mov_b32 v[150:151], v[156:157], v[192:193] op_sel:[1,0]
	v_mov_b32_e32 v157, v193
	v_pk_mul_f32 v[152:153], v[192:193], v[156:157]
	ds_bpermute_b32 v208, v239, v206
	v_pk_fma_f32 v[150:151], v[192:193], v[150:151], v[152:153] op_sel:[1,0,0] op_sel_hi:[0,1,1]
	v_pk_mov_b32 v[152:153], v[158:159], v[190:191] op_sel:[1,0]
	v_mov_b32_e32 v159, v191
	v_pk_mul_f32 v[154:155], v[190:191], v[158:159]
	ds_bpermute_b32 v209, v239, v207
	v_pk_fma_f32 v[152:153], v[190:191], v[152:153], v[154:155] op_sel:[1,0,0] op_sel_hi:[0,1,1]
	v_pk_add_f32 v[150:151], v[150:151], v[152:153]
	s_nop 0
	v_pk_add_f32 v[148:149], v[148:149], v[150:151]
	ds_bpermute_b32 v150, v240, v148
	ds_bpermute_b32 v151, v240, v149
	s_waitcnt lgkmcnt(0)
	v_pk_add_f32 v[148:149], v[148:149], v[150:151]
	ds_bpermute_b32 v150, v239, v148
	ds_bpermute_b32 v151, v239, v149
	s_and_saveexec_b64 s[6:7], vcc
	s_cbranch_execz .LBB0_839
	v_lshl_add_u32 v33, v212, 6, s19
	s_waitcnt lgkmcnt(0)
	v_pk_add_f32 v[150:151], v[148:149], v[150:151]
	v_pk_add_f32 v[148:149], v[206:207], v[208:209]
	ds_write_b128 v33, v[148:151]
;     __device__ __forceinline__ void fused(f32x4 (&acc)[2][2][4][2], const Unit& u, int wr, int wc, int fr, int fq, PG8_LAS unsigned char* lds, int wid, int lane) const {
;     ...
;             for (int m = 0; m < 4; ++m) { const int r = ai * HALF + wr * 64 + m * 16 + fr; const size_t off = (size_t)(u.pm * BM + r) * 1024 + col0;
;                 float s0 = 0.f, s1 = 0.f, s2 = 0.f, s3 = 0.f;
; #pragma unroll
;                 for (int bj = 0; bj < 2; ++bj)
; #pragma unroll
;                     for (int n = 0; n < 2; ++n) { const f32x4 bs = *(const f32x4*)(base + off + bj * HALF + n * 16), a = acc[ai][bj][m][n], ag = a * gv[bj][n];
;                         s0 += (a[0] * a[0] + a[1] * a[1]) + (a[2] * a[2] + a[3] * a[3]); s1 += (bs[0] * bs[0] + bs[1] * bs[1]) + (bs[2] * bs[2] + bs[3] * bs[3]);
;                         s2 += (bs[0] * ag[0] + bs[1] * ag[1]) + (bs[2] * ag[2] + bs[3] * ag[3]); s3 += (ag[0] * ag[0] + ag[1] * ag[1]) + (ag[2] * ag[2] + ag[3] * ag[3]); }
;                 s0 += __shfl_xor(s0, 16); s0 += __shfl_xor(s0, 32); s1 += __shfl_xor(s1, 16); s1 += __shfl_xor(s1, 32);
;                 s2 += __shfl_xor(s2, 16); s2 += __shfl_xor(s2, 32); s3 += __shfl_xor(s3, 16); s3 += __shfl_xor(s3, 32);
;                 if (fq == 0) P[r * 4 + wc] = (f32x4){s0, s1, s2, s3};
.LBB0_839:
	s_or_b64 exec, exec, s[6:7]
	s_mov_b64 s[98:99], 0xa0000
	v_lshl_add_u64 v[160:161], v[164:165], 0, s[98:99]
	s_add_i32 m0, s72, 0x0
	s_nop 0
	global_load_lds_dwordx4 v[160:161], off
	s_mov_b64 s[98:99], 0xa0040
	v_lshl_add_u64 v[160:161], v[164:165], 0, s[98:99]
	s_add_i32 m0, s72, 0x400
	s_nop 0
	global_load_lds_dwordx4 v[160:161], off
	s_mov_b64 s[98:99], 0xa0200
	v_lshl_add_u64 v[160:161], v[164:165], 0, s[98:99]
	s_add_i32 m0, s72, 0x800
	s_nop 0
	global_load_lds_dwordx4 v[160:161], off
	s_mov_b64 s[98:99], 0xa0240
	v_lshl_add_u64 v[160:161], v[164:165], 0, s[98:99]
	s_add_i32 m0, s72, 0xc00
	s_nop 0
	global_load_lds_dwordx4 v[160:161], off
	v_add_u32_e32 v216, 0x80, v237
	v_add_u32_e32 v182, s17, v216
	v_ashrrev_i32_e32 v183, 31, v182
	v_lshlrev_b64 v[148:149], 12, v[182:183]
	v_lshl_add_u64 v[148:149], s[26:27], 0, v[148:149]
	v_lshl_add_u64 v[180:181], v[34:35], 2, v[148:149]
	s_waitcnt lgkmcnt(0)
	s_add_i32 s98, s72, 0x1000
	s_waitcnt vmcnt(11)
	v_and_b32_e32 v148, 63, v228
	v_lshl_add_u32 v148, v148, 4, s98
	ds_read_b128 v[148:151], v148
	s_waitcnt vmcnt(10)
	v_and_b32_e32 v160, 63, v228
	v_lshl_add_u32 v160, v160, 4, s98
	ds_read_b128 v[160:163], v160 offset:1024
	v_pk_mul_f32 v[152:153], v[66:67], v[66:67]
	v_pk_mul_f32 v[154:155], v[64:65], v[64:65]
	v_pk_mul_f32 v[208:209], v[62:63], v[106:107]
	v_pk_mov_b32 v[156:157], v[154:155], v[152:153] op_sel:[1,0]
	v_mov_b32_e32 v155, v153
	v_pk_add_f32 v[210:211], v[156:157], v[154:155]
	v_pk_mul_f32 v[186:187], v[64:65], v[116:117]
	v_pk_add_f32 v[210:211], v[210:211], v[210:211] op_sel:[0,1] op_sel_hi:[1,0]
	v_pk_mul_f32 v[214:215], v[60:61], v[104:105]
	v_pk_mul_f32 v[184:185], v[66:67], v[118:119]
	v_mul_f32_e32 v217, v214, v214
	v_mul_f32_e32 v33, v215, v215
	v_pk_mul_f32 v[192:193], v[56:57], v[100:101]
	v_pk_mul_f32 v[190:191], v[58:59], v[102:103]
	v_pk_mul_f32 v[206:207], v[52:53], v[92:93]
	v_pk_mul_f32 v[204:205], v[54:55], v[94:95]
	s_waitcnt lgkmcnt(1)
	v_pk_mul_f32 v[152:153], v[150:151], v[150:151]
	v_pk_mul_f32 v[154:155], v[148:149], v[148:149]
	s_nop 0
	v_pk_mov_b32 v[156:157], v[154:155], v[152:153] op_sel:[1,0]
	v_mov_b32_e32 v155, v153
	v_pk_add_f32 v[152:153], v[156:157], v[154:155]
	v_pk_mul_f32 v[154:155], v[60:61], v[60:61]
	v_pk_add_f32 v[218:219], v[152:153], v[152:153] op_sel_hi:[0,1]
	v_pk_mul_f32 v[152:153], v[62:63], v[62:63]
	v_mul_f32_e32 v218, v52, v52
	v_pk_mov_b32 v[156:157], v[154:155], v[152:153] op_sel:[1,0]
	v_mov_b32_e32 v155, v153
	v_pk_add_f32 v[212:213], v[156:157], v[154:155]
	s_waitcnt lgkmcnt(0)
	v_pk_mul_f32 v[152:153], v[162:163], v[162:163]
	v_pk_mul_f32 v[154:155], v[160:161], v[160:161]
	v_pk_add_f32 v[212:213], v[212:213], v[212:213] op_sel:[0,1] op_sel_hi:[1,0]
	v_pk_mov_b32 v[156:157], v[154:155], v[152:153] op_sel:[1,0]
	v_mov_b32_e32 v155, v153
	v_pk_add_f32 v[152:153], v[156:157], v[154:155]
	s_nop 0
	v_pk_add_f32 v[220:221], v[152:153], v[152:153] op_sel_hi:[0,1]
	v_mul_f32_e32 v152, v208, v208
	v_pk_fma_f32 v[188:189], v[208:209], v[208:209], v[152:153] op_sel_hi:[1,1,0]
	s_waitcnt vmcnt(9)
	v_and_b32_e32 v152, 63, v228
	v_lshl_add_u32 v152, v152, 4, s98
	ds_read_b128 v[152:155], v152 offset:2048
	v_mul_f32_e32 v220, v53, v53
	v_pk_add_f32 v[218:219], v[218:219], v[220:221]
	v_mul_f32_e32 v188, v57, v57
	s_waitcnt lgkmcnt(0)
	v_mul_f32_e32 v156, v152, v152
	v_pk_fma_f32 v[222:223], v[152:153], v[152:153], v[156:157] op_sel_hi:[1,1,0]
	v_mul_f32_e32 v156, v154, v154
	v_pk_fma_f32 v[224:225], v[154:155], v[154:155], v[156:157] op_sel_hi:[1,1,0]
	s_waitcnt vmcnt(8)
	v_and_b32_e32 v156, 63, v228
	v_lshl_add_u32 v156, v156, 4, s98
	ds_read_b128 v[156:159], v156 offset:3072
	v_mul_f32_e32 v222, v54, v54
	v_mul_f32_e32 v224, v55, v55
	v_pk_add_f32 v[220:221], v[222:223], v[224:225]
	s_waitcnt lgkmcnt(0)
	v_mul_f32_e32 v226, v156, v156
	v_pk_add_f32 v[218:219], v[218:219], v[220:221]
	v_pk_fma_f32 v[220:221], v[56:57], v[56:57], v[188:189] op_sel_hi:[1,1,0]
	v_mul_f32_e32 v188, v59, v59
	v_mul_f32_e32 v227, v157, v157
	v_mul_f32_e32 v241, v158, v158
	v_mul_f32_e32 v242, v159, v159
	v_pk_fma_f32 v[222:223], v[58:59], v[58:59], v[188:189] op_sel_hi:[1,1,0]
	v_mov_b32_e32 v221, v226
	v_mov_b32_e32 v223, v227
	v_mov_b32_e32 v213, v241
	v_mov_b32_e32 v211, v242
	v_pk_add_f32 v[220:221], v[220:221], v[222:223]
	v_pk_add_f32 v[210:211], v[212:213], v[210:211]
	s_nop 0
	v_pk_add_f32 v[210:211], v[220:221], v[210:211]
	v_mov_b32_e32 v220, v160
	v_pk_add_f32 v[210:211], v[218:219], v[210:211]
	v_mov_b32_e32 v218, v214
	v_mov_b32_e32 v214, v215
	v_mov_b32_e32 v215, v187
	v_mov_b32_e32 v160, v161
	v_mov_b32_e32 v161, v187
	v_mov_b32_e32 v219, v186
	v_mov_b32_e32 v221, v186
	v_pk_mul_f32 v[160:161], v[214:215], v[160:161]
	v_mov_b32_e32 v214, v208
	v_pk_fma_f32 v[160:161], v[218:219], v[220:221], v[160:161]
	v_mov_b32_e32 v218, v162
	v_mov_b32_e32 v208, v209
	v_mov_b32_e32 v209, v185
	v_mov_b32_e32 v162, v163
	v_mov_b32_e32 v163, v185
	v_mov_b32_e32 v215, v184
	v_mov_b32_e32 v219, v184
	v_pk_mul_f32 v[162:163], v[208:209], v[162:163]
	ds_bpermute_b32 v212, v240, v210
	v_pk_fma_f32 v[162:163], v[214:215], v[218:219], v[162:163]
	ds_bpermute_b32 v213, v240, v211
	v_pk_add_f32 v[160:161], v[160:161], v[162:163]
	v_mul_f32_e32 v162, v187, v149
	v_pk_fma_f32 v[148:149], v[186:187], v[148:149], v[162:163] op_sel_hi:[1,1,0]
	v_mul_f32_e32 v162, v185, v151
	v_pk_fma_f32 v[150:151], v[184:185], v[150:151], v[162:163] op_sel_hi:[1,1,0]
	v_mov_b32_e32 v149, v217
	v_mov_b32_e32 v151, v33
	v_pk_add_f32 v[148:149], v[148:149], v[150:151]
	v_pk_mov_b32 v[150:151], v[152:153], v[192:193] op_sel:[1,0]
	v_mov_b32_e32 v153, v193
	v_pk_mul_f32 v[152:153], v[192:193], v[152:153]
	v_mov_b32_e32 v33, v189
	v_pk_fma_f32 v[150:151], v[192:193], v[150:151], v[152:153] op_sel:[1,0,0] op_sel_hi:[0,1,1]
	v_pk_mov_b32 v[152:153], v[154:155], v[190:191] op_sel:[1,0]
	v_mov_b32_e32 v155, v191
	v_pk_mul_f32 v[154:155], v[190:191], v[154:155]
	v_pk_add_f32 v[148:149], v[148:149], v[32:33]
	v_pk_fma_f32 v[152:153], v[190:191], v[152:153], v[154:155] op_sel:[1,0,0] op_sel_hi:[0,1,1]
	v_pk_add_f32 v[148:149], v[160:161], v[148:149]
	v_pk_add_f32 v[150:151], v[150:151], v[152:153]
	s_waitcnt lgkmcnt(0)
;     __device__ __forceinline__ void fused(f32x4 (&acc)[2][2][4][2], const Unit& u, int wr, int wc, int fr, int fq, PG8_LAS unsigned char* lds, int wid, int lane) const {
;     ...
;             for (int m = 0; m < 4; ++m) { const int r = ai * HALF + wr * 64 + m * 16 + fr; const size_t off = (size_t)(u.pm * BM + r) * 1024 + col0;
;                 float s0 = 0.f, s1 = 0.f, s2 = 0.f, s3 = 0.f;
; #pragma unroll
;                 for (int bj = 0; bj < 2; ++bj)
; #pragma unroll
;                     for (int n = 0; n < 2; ++n) { const f32x4 bs = *(const f32x4*)(base + off + bj * HALF + n * 16), a = acc[ai][bj][m][n], ag = a * gv[bj][n];
;                         s0 += (a[0] * a[0] + a[1] * a[1]) + (a[2] * a[2] + a[3] * a[3]); s1 += (bs[0] * bs[0] + bs[1] * bs[1]) + (bs[2] * bs[2] + bs[3] * bs[3]);
;                         s2 += (bs[0] * ag[0] + bs[1] * ag[1]) + (bs[2] * ag[2] + bs[3] * ag[3]); s3 += (ag[0] * ag[0] + ag[1] * ag[1]) + (ag[2] * ag[2] + ag[3] * ag[3]); }
;                 s0 += __shfl_xor(s0, 16); s0 += __shfl_xor(s0, 32); s1 += __shfl_xor(s1, 16); s1 += __shfl_xor(s1, 32);
;                 s2 += __shfl_xor(s2, 16); s2 += __shfl_xor(s2, 32); s3 += __shfl_xor(s3, 16); s3 += __shfl_xor(s3, 32);
;                 if (fq == 0) P[r * 4 + wc] = (f32x4){s0, s1, s2, s3};
	v_pk_add_f32 v[210:211], v[210:211], v[212:213]
	v_pk_add_f32 v[148:149], v[148:149], v[150:151]
	v_pk_mov_b32 v[150:151], v[156:157], v[206:207] op_sel:[1,0]
	v_mov_b32_e32 v157, v207
	v_pk_mul_f32 v[152:153], v[206:207], v[156:157]
	ds_bpermute_b32 v212, v239, v210
	v_pk_fma_f32 v[150:151], v[206:207], v[150:151], v[152:153] op_sel:[1,0,0] op_sel_hi:[0,1,1]
	v_pk_mov_b32 v[152:153], v[158:159], v[204:205] op_sel:[1,0]
	v_mov_b32_e32 v159, v205
	v_pk_mul_f32 v[154:155], v[204:205], v[158:159]
	ds_bpermute_b32 v213, v239, v211
	v_pk_fma_f32 v[152:153], v[204:205], v[152:153], v[154:155] op_sel:[1,0,0] op_sel_hi:[0,1,1]
	v_pk_add_f32 v[150:151], v[150:151], v[152:153]
	s_nop 0
	v_pk_add_f32 v[148:149], v[148:149], v[150:151]
	ds_bpermute_b32 v150, v240, v148
	ds_bpermute_b32 v151, v240, v149
	s_waitcnt lgkmcnt(0)
	v_pk_add_f32 v[148:149], v[148:149], v[150:151]
	ds_bpermute_b32 v150, v239, v148
	ds_bpermute_b32 v151, v239, v149
	s_and_saveexec_b64 s[6:7], vcc
	s_cbranch_execz .LBB0_841
	v_lshl_add_u32 v33, v216, 6, s19
	s_waitcnt lgkmcnt(0)
	v_pk_add_f32 v[150:151], v[148:149], v[150:151]
	v_pk_add_f32 v[148:149], v[210:211], v[212:213]
	ds_write_b128 v33, v[148:151]
.LBB0_841:
	s_or_b64 exec, exec, s[6:7]
	s_mov_b64 s[98:99], 0xb0000
	v_lshl_add_u64 v[160:161], v[164:165], 0, s[98:99]
	s_add_i32 m0, s72, 0x1000
	s_nop 0
	global_load_lds_dwordx4 v[160:161], off
	s_mov_b64 s[98:99], 0xb0040
	v_lshl_add_u64 v[160:161], v[164:165], 0, s[98:99]
	s_add_i32 m0, s72, 0x1400
	s_nop 0
	global_load_lds_dwordx4 v[160:161], off
	s_mov_b64 s[98:99], 0xb0200
	v_lshl_add_u64 v[160:161], v[164:165], 0, s[98:99]
	s_add_i32 m0, s72, 0x1800
	s_nop 0
	global_load_lds_dwordx4 v[160:161], off
	s_mov_b64 s[98:99], 0xb0240
	v_lshl_add_u64 v[160:161], v[164:165], 0, s[98:99]
	s_add_i32 m0, s72, 0x1c00
	s_nop 0
	global_load_lds_dwordx4 v[160:161], off
	v_add_u32_e32 v220, 0x90, v237
	v_add_u32_e32 v186, s17, v220
	v_ashrrev_i32_e32 v187, 31, v186
	v_lshlrev_b64 v[148:149], 12, v[186:187]
	v_lshl_add_u64 v[148:149], s[26:27], 0, v[148:149]
	v_lshl_add_u64 v[184:185], v[34:35], 2, v[148:149]
	s_waitcnt lgkmcnt(0)
	s_add_i32 s98, s72, 0x2000
	s_waitcnt vmcnt(11)
	v_and_b32_e32 v148, 63, v228
	v_lshl_add_u32 v148, v148, 4, s98
	ds_read_b128 v[148:151], v148
	s_waitcnt vmcnt(10)
	v_and_b32_e32 v160, 63, v228
	v_lshl_add_u32 v160, v160, 4, s98
	ds_read_b128 v[160:163], v160 offset:1024
	v_pk_mul_f32 v[152:153], v[50:51], v[50:51]
	v_pk_mul_f32 v[154:155], v[48:49], v[48:49]
	v_pk_mul_f32 v[212:213], v[46:47], v[106:107]
	v_pk_mov_b32 v[156:157], v[154:155], v[152:153] op_sel:[1,0]
	v_mov_b32_e32 v155, v153
	v_pk_add_f32 v[214:215], v[156:157], v[154:155]
	v_pk_mul_f32 v[190:191], v[48:49], v[116:117]
	v_pk_add_f32 v[214:215], v[214:215], v[214:215] op_sel:[0,1] op_sel_hi:[1,0]
	v_pk_mul_f32 v[218:219], v[44:45], v[104:105]
	v_pk_mul_f32 v[188:189], v[50:51], v[118:119]
	v_mul_f32_e32 v221, v218, v218
	v_mul_f32_e32 v33, v219, v219
	v_pk_mul_f32 v[206:207], v[40:41], v[100:101]
	v_pk_mul_f32 v[204:205], v[42:43], v[102:103]
	v_pk_mul_f32 v[210:211], v[36:37], v[92:93]
	v_pk_mul_f32 v[208:209], v[38:39], v[94:95]
	s_waitcnt lgkmcnt(1)
	v_pk_mul_f32 v[152:153], v[150:151], v[150:151]
	v_pk_mul_f32 v[154:155], v[148:149], v[148:149]
	s_nop 0
	v_pk_mov_b32 v[156:157], v[154:155], v[152:153] op_sel:[1,0]
	v_mov_b32_e32 v155, v153
	v_pk_add_f32 v[152:153], v[156:157], v[154:155]
	v_pk_mul_f32 v[154:155], v[44:45], v[44:45]
	v_pk_add_f32 v[222:223], v[152:153], v[152:153] op_sel_hi:[0,1]
	v_pk_mul_f32 v[152:153], v[46:47], v[46:47]
	v_mul_f32_e32 v222, v36, v36
	v_pk_mov_b32 v[156:157], v[154:155], v[152:153] op_sel:[1,0]
	v_mov_b32_e32 v155, v153
	v_pk_add_f32 v[216:217], v[156:157], v[154:155]
	s_waitcnt lgkmcnt(0)
	v_pk_mul_f32 v[152:153], v[162:163], v[162:163]
	v_pk_mul_f32 v[154:155], v[160:161], v[160:161]
	v_pk_add_f32 v[216:217], v[216:217], v[216:217] op_sel:[0,1] op_sel_hi:[1,0]
	v_pk_mov_b32 v[156:157], v[154:155], v[152:153] op_sel:[1,0]
	v_mov_b32_e32 v155, v153
	v_pk_add_f32 v[152:153], v[156:157], v[154:155]
	s_nop 0
	v_pk_add_f32 v[224:225], v[152:153], v[152:153] op_sel_hi:[0,1]
	v_mul_f32_e32 v152, v212, v212
	v_pk_fma_f32 v[192:193], v[212:213], v[212:213], v[152:153] op_sel_hi:[1,1,0]
	s_waitcnt vmcnt(9)
	v_and_b32_e32 v152, 63, v228
	v_lshl_add_u32 v152, v152, 4, s98
	ds_read_b128 v[152:155], v152 offset:2048
	v_mul_f32_e32 v224, v37, v37
	v_pk_add_f32 v[222:223], v[222:223], v[224:225]
	v_mul_f32_e32 v192, v41, v41
	s_waitcnt lgkmcnt(0)
	v_mul_f32_e32 v156, v152, v152
	v_pk_fma_f32 v[226:227], v[152:153], v[152:153], v[156:157] op_sel_hi:[1,1,0]
	v_mul_f32_e32 v156, v154, v154
	v_pk_fma_f32 v[242:243], v[154:155], v[154:155], v[156:157] op_sel_hi:[1,1,0]
	s_waitcnt vmcnt(8)
	v_and_b32_e32 v156, 63, v228
	v_lshl_add_u32 v156, v156, 4, s98
	ds_read_b128 v[156:159], v156 offset:3072
	v_mul_f32_e32 v226, v38, v38
	v_mul_f32_e32 v242, v39, v39
	v_pk_add_f32 v[224:225], v[226:227], v[242:243]
	s_waitcnt lgkmcnt(0)
;     __device__ __forceinline__ void fused(f32x4 (&acc)[2][2][4][2], const Unit& u, int wr, int wc, int fr, int fq, PG8_LAS unsigned char* lds, int wid, int lane) const {
;     ...
;             for (int m = 0; m < 4; ++m) { const int r = ai * HALF + wr * 64 + m * 16 + fr; const size_t off = (size_t)(u.pm * BM + r) * 1024 + col0;
;                 float s0 = 0.f, s1 = 0.f, s2 = 0.f, s3 = 0.f;
; #pragma unroll
;                 for (int bj = 0; bj < 2; ++bj)
; #pragma unroll
;                     for (int n = 0; n < 2; ++n) { const f32x4 bs = *(const f32x4*)(base + off + bj * HALF + n * 16), a = acc[ai][bj][m][n], ag = a * gv[bj][n];
;                         s0 += (a[0] * a[0] + a[1] * a[1]) + (a[2] * a[2] + a[3] * a[3]); s1 += (bs[0] * bs[0] + bs[1] * bs[1]) + (bs[2] * bs[2] + bs[3] * bs[3]);
;                         s2 += (bs[0] * ag[0] + bs[1] * ag[1]) + (bs[2] * ag[2] + bs[3] * ag[3]); s3 += (ag[0] * ag[0] + ag[1] * ag[1]) + (ag[2] * ag[2] + ag[3] * ag[3]); }
;                 s0 += __shfl_xor(s0, 16); s0 += __shfl_xor(s0, 32); s1 += __shfl_xor(s1, 16); s1 += __shfl_xor(s1, 32);
;                 s2 += __shfl_xor(s2, 16); s2 += __shfl_xor(s2, 32); s3 += __shfl_xor(s3, 16); s3 += __shfl_xor(s3, 32);
;                 if (fq == 0) P[r * 4 + wc] = (f32x4){s0, s1, s2, s3};
	v_mul_f32_e32 v241, v156, v156
	v_pk_add_f32 v[222:223], v[222:223], v[224:225]
	v_pk_fma_f32 v[224:225], v[40:41], v[40:41], v[192:193] op_sel_hi:[1,1,0]
	v_mul_f32_e32 v192, v43, v43
	v_mul_f32_e32 v244, v157, v157
	v_mul_f32_e32 v245, v158, v158
	v_mul_f32_e32 v246, v159, v159
	v_pk_fma_f32 v[226:227], v[42:43], v[42:43], v[192:193] op_sel_hi:[1,1,0]
	v_mov_b32_e32 v225, v241
	v_mov_b32_e32 v227, v244
	v_mov_b32_e32 v217, v245
	v_mov_b32_e32 v215, v246
	v_pk_add_f32 v[224:225], v[224:225], v[226:227]
	v_pk_add_f32 v[214:215], v[216:217], v[214:215]
	s_nop 0
	v_pk_add_f32 v[214:215], v[224:225], v[214:215]
	v_mov_b32_e32 v224, v160
	v_pk_add_f32 v[214:215], v[222:223], v[214:215]
	v_mov_b32_e32 v222, v218
	v_mov_b32_e32 v218, v219
	v_mov_b32_e32 v219, v191
	v_mov_b32_e32 v160, v161
	v_mov_b32_e32 v161, v191
	v_mov_b32_e32 v223, v190
	v_mov_b32_e32 v225, v190
	v_pk_mul_f32 v[160:161], v[218:219], v[160:161]
	v_mov_b32_e32 v218, v212
	v_pk_fma_f32 v[160:161], v[222:223], v[224:225], v[160:161]
	v_mov_b32_e32 v222, v162
	v_mov_b32_e32 v212, v213
	v_mov_b32_e32 v213, v189
	v_mov_b32_e32 v162, v163
	v_mov_b32_e32 v163, v189
	v_mov_b32_e32 v219, v188
	v_mov_b32_e32 v223, v188
	v_pk_mul_f32 v[162:163], v[212:213], v[162:163]
	ds_bpermute_b32 v216, v240, v214
	v_pk_fma_f32 v[162:163], v[218:219], v[222:223], v[162:163]
	ds_bpermute_b32 v217, v240, v215
	v_pk_add_f32 v[160:161], v[160:161], v[162:163]
	v_mul_f32_e32 v162, v191, v149
	v_pk_fma_f32 v[148:149], v[190:191], v[148:149], v[162:163] op_sel_hi:[1,1,0]
	v_mul_f32_e32 v162, v189, v151
	v_pk_fma_f32 v[150:151], v[188:189], v[150:151], v[162:163] op_sel_hi:[1,1,0]
	v_mov_b32_e32 v149, v221
	v_mov_b32_e32 v151, v33
	v_pk_add_f32 v[148:149], v[148:149], v[150:151]
	v_pk_mov_b32 v[150:151], v[152:153], v[206:207] op_sel:[1,0]
	v_mov_b32_e32 v153, v207
	v_pk_mul_f32 v[152:153], v[206:207], v[152:153]
	v_mov_b32_e32 v33, v193
	v_pk_fma_f32 v[150:151], v[206:207], v[150:151], v[152:153] op_sel:[1,0,0] op_sel_hi:[0,1,1]
	v_pk_mov_b32 v[152:153], v[154:155], v[204:205] op_sel:[1,0]
	v_mov_b32_e32 v155, v205
	v_pk_mul_f32 v[154:155], v[204:205], v[154:155]
	v_pk_add_f32 v[148:149], v[148:149], v[32:33]
	v_pk_fma_f32 v[152:153], v[204:205], v[152:153], v[154:155] op_sel:[1,0,0] op_sel_hi:[0,1,1]
	v_pk_add_f32 v[148:149], v[160:161], v[148:149]
	v_pk_add_f32 v[150:151], v[150:151], v[152:153]
	s_waitcnt lgkmcnt(0)
	v_pk_add_f32 v[214:215], v[214:215], v[216:217]
	v_pk_add_f32 v[148:149], v[148:149], v[150:151]
	v_pk_mov_b32 v[150:151], v[156:157], v[210:211] op_sel:[1,0]
	v_mov_b32_e32 v157, v211
	v_pk_mul_f32 v[152:153], v[210:211], v[156:157]
	ds_bpermute_b32 v216, v239, v214
	v_pk_fma_f32 v[150:151], v[210:211], v[150:151], v[152:153] op_sel:[1,0,0] op_sel_hi:[0,1,1]
	v_pk_mov_b32 v[152:153], v[158:159], v[208:209] op_sel:[1,0]
	v_mov_b32_e32 v159, v209
	v_pk_mul_f32 v[154:155], v[208:209], v[158:159]
	ds_bpermute_b32 v217, v239, v215
	v_pk_fma_f32 v[152:153], v[208:209], v[152:153], v[154:155] op_sel:[1,0,0] op_sel_hi:[0,1,1]
	v_pk_add_f32 v[150:151], v[150:151], v[152:153]
	s_nop 0
	v_pk_add_f32 v[148:149], v[148:149], v[150:151]
	ds_bpermute_b32 v150, v240, v148
	ds_bpermute_b32 v151, v240, v149
	s_waitcnt lgkmcnt(0)
	v_pk_add_f32 v[148:149], v[148:149], v[150:151]
	ds_bpermute_b32 v150, v239, v148
	ds_bpermute_b32 v151, v239, v149
	s_and_saveexec_b64 s[6:7], vcc
	s_cbranch_execz .LBB0_843
	v_lshl_add_u32 v33, v220, 6, s19
	s_waitcnt lgkmcnt(0)
	v_pk_add_f32 v[150:151], v[148:149], v[150:151]
	v_pk_add_f32 v[148:149], v[214:215], v[216:217]
	ds_write_b128 v33, v[148:151]
.LBB0_843:
	s_or_b64 exec, exec, s[6:7]
	v_add_u32_e32 v224, 0xa0, v237
	v_add_u32_e32 v190, s17, v224
	v_ashrrev_i32_e32 v191, 31, v190
	v_lshlrev_b64 v[148:149], 12, v[190:191]
	v_lshl_add_u64 v[148:149], s[26:27], 0, v[148:149]
	v_lshl_add_u64 v[188:189], v[34:35], 2, v[148:149]
	s_waitcnt lgkmcnt(0)
	s_add_i32 s98, s72, 0x0
	s_waitcnt vmcnt(7)
	v_and_b32_e32 v148, 63, v228
	v_lshl_add_u32 v148, v148, 4, s98
	ds_read_b128 v[148:151], v148
	s_waitcnt vmcnt(6)
	v_and_b32_e32 v160, 63, v228
	v_lshl_add_u32 v160, v160, 4, s98
	ds_read_b128 v[160:163], v160 offset:1024
	v_pk_mul_f32 v[152:153], v[30:31], v[30:31]
	v_pk_mul_f32 v[154:155], v[28:29], v[28:29]
	v_pk_mul_f32 v[216:217], v[26:27], v[106:107]
	v_pk_mov_b32 v[156:157], v[154:155], v[152:153] op_sel:[1,0]
	v_mov_b32_e32 v155, v153
	v_pk_add_f32 v[218:219], v[156:157], v[154:155]
	v_pk_mul_f32 v[204:205], v[28:29], v[116:117]
	v_pk_add_f32 v[218:219], v[218:219], v[218:219] op_sel:[0,1] op_sel_hi:[1,0]
	v_pk_mul_f32 v[222:223], v[24:25], v[104:105]
	v_pk_mul_f32 v[192:193], v[30:31], v[118:119]
	v_mul_f32_e32 v225, v222, v222
	v_mul_f32_e32 v33, v223, v223
	v_pk_mul_f32 v[210:211], v[20:21], v[100:101]
	v_pk_mul_f32 v[208:209], v[22:23], v[102:103]
	v_pk_mul_f32 v[214:215], v[16:17], v[92:93]
	v_pk_mul_f32 v[212:213], v[18:19], v[94:95]
	s_waitcnt lgkmcnt(1)
	v_pk_mul_f32 v[152:153], v[150:151], v[150:151]
	v_pk_mul_f32 v[154:155], v[148:149], v[148:149]
	s_nop 0
	v_pk_mov_b32 v[156:157], v[154:155], v[152:153] op_sel:[1,0]
	v_mov_b32_e32 v155, v153
	v_pk_add_f32 v[152:153], v[156:157], v[154:155]
	v_pk_mul_f32 v[154:155], v[24:25], v[24:25]
	v_pk_add_f32 v[226:227], v[152:153], v[152:153] op_sel_hi:[0,1]
	v_pk_mul_f32 v[152:153], v[26:27], v[26:27]
	v_mul_f32_e32 v226, v16, v16
	v_pk_mov_b32 v[156:157], v[154:155], v[152:153] op_sel:[1,0]
	v_mov_b32_e32 v155, v153
	v_pk_add_f32 v[220:221], v[156:157], v[154:155]
	s_waitcnt lgkmcnt(0)
;     __device__ __forceinline__ void fused(f32x4 (&acc)[2][2][4][2], const Unit& u, int wr, int wc, int fr, int fq, PG8_LAS unsigned char* lds, int wid, int lane) const {
;     ...
;                     for (int n = 0; n < 2; ++n) { const f32x4 bs = *(const f32x4*)(base + off + bj * HALF + n * 16), a = acc[ai][bj][m][n], ag = a * gv[bj][n];
;                         s0 += (a[0] * a[0] + a[1] * a[1]) + (a[2] * a[2] + a[3] * a[3]); s1 += (bs[0] * bs[0] + bs[1] * bs[1]) + (bs[2] * bs[2] + bs[3] * bs[3]);
;                         s2 += (bs[0] * ag[0] + bs[1] * ag[1]) + (bs[2] * ag[2] + bs[3] * ag[3]); s3 += (ag[0] * ag[0] + ag[1] * ag[1]) + (ag[2] * ag[2] + ag[3] * ag[3]); }
;                 s0 += __shfl_xor(s0, 16); s0 += __shfl_xor(s0, 32); s1 += __shfl_xor(s1, 16); s1 += __shfl_xor(s1, 32);
;                 s2 += __shfl_xor(s2, 16); s2 += __shfl_xor(s2, 32); s3 += __shfl_xor(s3, 16); s3 += __shfl_xor(s3, 32);
;                 if (fq == 0) P[r * 4 + wc] = (f32x4){s0, s1, s2, s3};
	v_pk_mul_f32 v[152:153], v[162:163], v[162:163]
	v_pk_mul_f32 v[154:155], v[160:161], v[160:161]
	v_pk_add_f32 v[220:221], v[220:221], v[220:221] op_sel:[0,1] op_sel_hi:[1,0]
	v_pk_mov_b32 v[156:157], v[154:155], v[152:153] op_sel:[1,0]
	v_mov_b32_e32 v155, v153
	v_pk_add_f32 v[152:153], v[156:157], v[154:155]
	s_nop 0
	v_pk_add_f32 v[242:243], v[152:153], v[152:153] op_sel_hi:[0,1]
	v_mul_f32_e32 v152, v216, v216
	v_pk_fma_f32 v[206:207], v[216:217], v[216:217], v[152:153] op_sel_hi:[1,1,0]
	s_waitcnt vmcnt(5)
	v_and_b32_e32 v152, 63, v228
	v_lshl_add_u32 v152, v152, 4, s98
	ds_read_b128 v[152:155], v152 offset:2048
	v_mul_f32_e32 v242, v17, v17
	v_pk_add_f32 v[226:227], v[226:227], v[242:243]
	v_mul_f32_e32 v206, v21, v21
	s_waitcnt lgkmcnt(0)
	v_mul_f32_e32 v156, v152, v152
	v_pk_fma_f32 v[244:245], v[152:153], v[152:153], v[156:157] op_sel_hi:[1,1,0]
	v_mul_f32_e32 v156, v154, v154
	v_pk_fma_f32 v[246:247], v[154:155], v[154:155], v[156:157] op_sel_hi:[1,1,0]
	s_waitcnt vmcnt(4)
	v_and_b32_e32 v156, 63, v228
	v_lshl_add_u32 v156, v156, 4, s98
	ds_read_b128 v[156:159], v156 offset:3072
	v_mul_f32_e32 v244, v18, v18
	v_mul_f32_e32 v246, v19, v19
	v_pk_add_f32 v[242:243], v[244:245], v[246:247]
	s_waitcnt lgkmcnt(0)
	v_mul_f32_e32 v241, v156, v156
	v_pk_add_f32 v[226:227], v[226:227], v[242:243]
	v_pk_fma_f32 v[242:243], v[20:21], v[20:21], v[206:207] op_sel_hi:[1,1,0]
	v_mul_f32_e32 v206, v23, v23
	v_mul_f32_e32 v248, v157, v157
	v_mul_f32_e32 v249, v158, v158
	v_mul_f32_e32 v250, v159, v159
	v_pk_fma_f32 v[244:245], v[22:23], v[22:23], v[206:207] op_sel_hi:[1,1,0]
	v_mov_b32_e32 v243, v241
	v_mov_b32_e32 v245, v248
	v_mov_b32_e32 v221, v249
	v_mov_b32_e32 v219, v250
	v_pk_add_f32 v[242:243], v[242:243], v[244:245]
	v_pk_add_f32 v[218:219], v[220:221], v[218:219]
	s_nop 0
	v_pk_add_f32 v[218:219], v[242:243], v[218:219]
	v_mov_b32_e32 v242, v160
	v_pk_add_f32 v[218:219], v[226:227], v[218:219]
	v_mov_b32_e32 v226, v222
	v_mov_b32_e32 v222, v223
	v_mov_b32_e32 v223, v205
	v_mov_b32_e32 v160, v161
	v_mov_b32_e32 v161, v205
	v_mov_b32_e32 v227, v204
	v_mov_b32_e32 v243, v204
	v_pk_mul_f32 v[160:161], v[222:223], v[160:161]
	v_mov_b32_e32 v222, v216
	v_pk_fma_f32 v[160:161], v[226:227], v[242:243], v[160:161]
	v_mov_b32_e32 v226, v162
	v_mov_b32_e32 v216, v217
	v_mov_b32_e32 v217, v193
	v_mov_b32_e32 v162, v163
	v_mov_b32_e32 v163, v193
	v_mov_b32_e32 v223, v192
	v_mov_b32_e32 v227, v192
	v_pk_mul_f32 v[162:163], v[216:217], v[162:163]
	ds_bpermute_b32 v220, v240, v218
	v_pk_fma_f32 v[162:163], v[222:223], v[226:227], v[162:163]
	ds_bpermute_b32 v221, v240, v219
	v_pk_add_f32 v[160:161], v[160:161], v[162:163]
	v_mul_f32_e32 v162, v205, v149
	v_pk_fma_f32 v[148:149], v[204:205], v[148:149], v[162:163] op_sel_hi:[1,1,0]
	v_mul_f32_e32 v162, v193, v151
	v_pk_fma_f32 v[150:151], v[192:193], v[150:151], v[162:163] op_sel_hi:[1,1,0]
	v_mov_b32_e32 v149, v225
	v_mov_b32_e32 v151, v33
	v_pk_add_f32 v[148:149], v[148:149], v[150:151]
	v_pk_mov_b32 v[150:151], v[152:153], v[210:211] op_sel:[1,0]
	v_mov_b32_e32 v153, v211
	v_pk_mul_f32 v[152:153], v[210:211], v[152:153]
	v_mov_b32_e32 v33, v207
	v_pk_fma_f32 v[150:151], v[210:211], v[150:151], v[152:153] op_sel:[1,0,0] op_sel_hi:[0,1,1]
	v_pk_mov_b32 v[152:153], v[154:155], v[208:209] op_sel:[1,0]
	v_mov_b32_e32 v155, v209
	v_pk_mul_f32 v[154:155], v[208:209], v[154:155]
	v_pk_add_f32 v[148:149], v[148:149], v[32:33]
	v_pk_fma_f32 v[152:153], v[208:209], v[152:153], v[154:155] op_sel:[1,0,0] op_sel_hi:[0,1,1]
	v_pk_add_f32 v[148:149], v[160:161], v[148:149]
	v_pk_add_f32 v[150:151], v[150:151], v[152:153]
	s_waitcnt lgkmcnt(0)
	v_pk_add_f32 v[218:219], v[218:219], v[220:221]
	v_pk_add_f32 v[148:149], v[148:149], v[150:151]
	v_pk_mov_b32 v[150:151], v[156:157], v[214:215] op_sel:[1,0]
	v_mov_b32_e32 v157, v215
	v_pk_mul_f32 v[152:153], v[214:215], v[156:157]
	ds_bpermute_b32 v220, v239, v218
	v_pk_fma_f32 v[150:151], v[214:215], v[150:151], v[152:153] op_sel:[1,0,0] op_sel_hi:[0,1,1]
	v_pk_mov_b32 v[152:153], v[158:159], v[212:213] op_sel:[1,0]
	v_mov_b32_e32 v159, v213
	v_pk_mul_f32 v[154:155], v[212:213], v[158:159]
	ds_bpermute_b32 v221, v239, v219
	v_pk_fma_f32 v[152:153], v[212:213], v[152:153], v[154:155] op_sel:[1,0,0] op_sel_hi:[0,1,1]
	v_pk_add_f32 v[150:151], v[150:151], v[152:153]
	s_nop 0
	v_pk_add_f32 v[148:149], v[148:149], v[150:151]
	ds_bpermute_b32 v150, v240, v148
	ds_bpermute_b32 v151, v240, v149
	s_waitcnt lgkmcnt(0)
	v_pk_add_f32 v[148:149], v[148:149], v[150:151]
	ds_bpermute_b32 v150, v239, v148
	ds_bpermute_b32 v151, v239, v149
	s_and_saveexec_b64 s[6:7], vcc
	s_cbranch_execz .LBB0_845
	v_lshl_add_u32 v33, v224, 6, s19
	s_waitcnt lgkmcnt(0)
	v_pk_add_f32 v[150:151], v[148:149], v[150:151]
	v_pk_add_f32 v[148:149], v[218:219], v[220:221]
	ds_write_b128 v33, v[148:151]
;     __device__ __forceinline__ void fused(f32x4 (&acc)[2][2][4][2], const Unit& u, int wr, int wc, int fr, int fq, PG8_LAS unsigned char* lds, int wid, int lane) const {
;     ...
;             for (int m = 0; m < 4; ++m) { const int r = ai * HALF + wr * 64 + m * 16 + fr; const size_t off = (size_t)(u.pm * BM + r) * 1024 + col0;
;                 float s0 = 0.f, s1 = 0.f, s2 = 0.f, s3 = 0.f;
; #pragma unroll
;                 for (int bj = 0; bj < 2; ++bj)
; #pragma unroll
;                     for (int n = 0; n < 2; ++n) { const f32x4 bs = *(const f32x4*)(base + off + bj * HALF + n * 16), a = acc[ai][bj][m][n], ag = a * gv[bj][n];
;                         s0 += (a[0] * a[0] + a[1] * a[1]) + (a[2] * a[2] + a[3] * a[3]); s1 += (bs[0] * bs[0] + bs[1] * bs[1]) + (bs[2] * bs[2] + bs[3] * bs[3]);
;                         s2 += (bs[0] * ag[0] + bs[1] * ag[1]) + (bs[2] * ag[2] + bs[3] * ag[3]); s3 += (ag[0] * ag[0] + ag[1] * ag[1]) + (ag[2] * ag[2] + ag[3] * ag[3]); }
;                 s0 += __shfl_xor(s0, 16); s0 += __shfl_xor(s0, 32); s1 += __shfl_xor(s1, 16); s1 += __shfl_xor(s1, 32);
;                 s2 += __shfl_xor(s2, 16); s2 += __shfl_xor(s2, 32); s3 += __shfl_xor(s3, 16); s3 += __shfl_xor(s3, 32);
;                 if (fq == 0) P[r * 4 + wc] = (f32x4){s0, s1, s2, s3};
.LBB0_845:
	s_or_b64 exec, exec, s[6:7]
	v_add_u32_e32 v241, 0xb0, v237
	v_add_u32_e32 v204, s17, v241
	v_ashrrev_i32_e32 v205, 31, v204
	v_lshlrev_b64 v[148:149], 12, v[204:205]
	v_lshl_add_u64 v[148:149], s[26:27], 0, v[148:149]
	v_lshl_add_u64 v[192:193], v[34:35], 2, v[148:149]
	s_waitcnt lgkmcnt(0)
	s_add_i32 s98, s72, 0x1000
	s_waitcnt vmcnt(3)
	v_and_b32_e32 v148, 63, v228
	v_lshl_add_u32 v148, v148, 4, s98
	ds_read_b128 v[148:151], v148
	s_waitcnt vmcnt(2)
	v_and_b32_e32 v160, 63, v228
	v_lshl_add_u32 v160, v160, 4, s98
	ds_read_b128 v[160:163], v160 offset:1024
	v_pk_mul_f32 v[152:153], v[14:15], v[14:15]
	v_pk_mul_f32 v[154:155], v[12:13], v[12:13]
	v_pk_mul_f32 v[220:221], v[10:11], v[106:107]
	v_pk_mov_b32 v[156:157], v[154:155], v[152:153] op_sel:[1,0]
	v_mov_b32_e32 v155, v153
	v_pk_add_f32 v[222:223], v[156:157], v[154:155]
	v_pk_mul_f32 v[208:209], v[12:13], v[116:117]
	v_pk_add_f32 v[222:223], v[222:223], v[222:223] op_sel:[0,1] op_sel_hi:[1,0]
	v_pk_mul_f32 v[226:227], v[8:9], v[104:105]
	v_pk_mul_f32 v[206:207], v[14:15], v[118:119]
	v_mul_f32_e32 v242, v226, v226
	v_mul_f32_e32 v33, v227, v227
	v_pk_mul_f32 v[214:215], v[4:5], v[100:101]
	v_pk_mul_f32 v[212:213], v[6:7], v[102:103]
	v_pk_mul_f32 v[218:219], v[0:1], v[92:93]
	v_pk_mul_f32 v[216:217], v[2:3], v[94:95]
	s_waitcnt lgkmcnt(1)
	v_pk_mul_f32 v[152:153], v[150:151], v[150:151]
	v_pk_mul_f32 v[154:155], v[148:149], v[148:149]
	s_nop 0
	v_pk_mov_b32 v[156:157], v[154:155], v[152:153] op_sel:[1,0]
	v_mov_b32_e32 v155, v153
	v_pk_add_f32 v[152:153], v[156:157], v[154:155]
	v_pk_mul_f32 v[154:155], v[8:9], v[8:9]
	v_pk_add_f32 v[244:245], v[152:153], v[152:153] op_sel_hi:[0,1]
	v_pk_mul_f32 v[152:153], v[10:11], v[10:11]
	v_mul_f32_e32 v244, v0, v0
	v_pk_mov_b32 v[156:157], v[154:155], v[152:153] op_sel:[1,0]
	v_mov_b32_e32 v155, v153
	v_pk_add_f32 v[224:225], v[156:157], v[154:155]
	s_waitcnt lgkmcnt(0)
	v_pk_mul_f32 v[152:153], v[162:163], v[162:163]
	v_pk_mul_f32 v[154:155], v[160:161], v[160:161]
	v_pk_add_f32 v[224:225], v[224:225], v[224:225] op_sel:[0,1] op_sel_hi:[1,0]
	v_pk_mov_b32 v[156:157], v[154:155], v[152:153] op_sel:[1,0]
	v_mov_b32_e32 v155, v153
	v_pk_add_f32 v[152:153], v[156:157], v[154:155]
	s_nop 0
	v_pk_add_f32 v[246:247], v[152:153], v[152:153] op_sel_hi:[0,1]
	v_mul_f32_e32 v152, v220, v220
	v_pk_fma_f32 v[210:211], v[220:221], v[220:221], v[152:153] op_sel_hi:[1,1,0]
	s_waitcnt vmcnt(1)
	v_and_b32_e32 v152, 63, v228
	v_lshl_add_u32 v152, v152, 4, s98
	ds_read_b128 v[152:155], v152 offset:2048
	v_mul_f32_e32 v246, v1, v1
	v_pk_add_f32 v[244:245], v[244:245], v[246:247]
	v_mul_f32_e32 v210, v5, v5
	s_waitcnt lgkmcnt(0)
	v_mul_f32_e32 v156, v152, v152
	v_pk_fma_f32 v[248:249], v[152:153], v[152:153], v[156:157] op_sel_hi:[1,1,0]
	v_mul_f32_e32 v156, v154, v154
	v_pk_fma_f32 v[250:251], v[154:155], v[154:155], v[156:157] op_sel_hi:[1,1,0]
	s_waitcnt vmcnt(0)
	v_and_b32_e32 v156, 63, v228
	v_lshl_add_u32 v156, v156, 4, s98
	ds_read_b128 v[156:159], v156 offset:3072
	v_mul_f32_e32 v248, v2, v2
	v_mul_f32_e32 v250, v3, v3
	v_pk_add_f32 v[246:247], v[248:249], v[250:251]
	s_waitcnt lgkmcnt(0)
	v_mul_f32_e32 v243, v156, v156
	v_pk_add_f32 v[244:245], v[244:245], v[246:247]
	v_pk_fma_f32 v[246:247], v[4:5], v[4:5], v[210:211] op_sel_hi:[1,1,0]
	v_mul_f32_e32 v210, v7, v7
	v_mul_f32_e32 v252, v157, v157
	v_mul_f32_e32 v253, v158, v158
	v_mul_f32_e32 v230, v159, v159
	v_pk_fma_f32 v[248:249], v[6:7], v[6:7], v[210:211] op_sel_hi:[1,1,0]
	v_mov_b32_e32 v247, v243
	v_mov_b32_e32 v249, v252
	v_mov_b32_e32 v225, v253
	v_mov_b32_e32 v223, v230
	v_pk_add_f32 v[246:247], v[246:247], v[248:249]
	v_pk_add_f32 v[222:223], v[224:225], v[222:223]
	s_nop 0
	v_pk_add_f32 v[222:223], v[246:247], v[222:223]
	v_mov_b32_e32 v246, v160
	v_pk_add_f32 v[222:223], v[244:245], v[222:223]
	v_mov_b32_e32 v244, v226
	v_mov_b32_e32 v226, v227
	v_mov_b32_e32 v227, v209
	v_mov_b32_e32 v160, v161
	v_mov_b32_e32 v161, v209
	v_mov_b32_e32 v245, v208
	v_mov_b32_e32 v247, v208
	v_pk_mul_f32 v[160:161], v[226:227], v[160:161]
	v_mov_b32_e32 v226, v220
	v_pk_fma_f32 v[160:161], v[244:245], v[246:247], v[160:161]
	v_mov_b32_e32 v244, v162
	v_mov_b32_e32 v220, v221
	v_mov_b32_e32 v221, v207
	v_mov_b32_e32 v162, v163
	v_mov_b32_e32 v163, v207
	v_mov_b32_e32 v227, v206
	v_mov_b32_e32 v245, v206
	v_pk_mul_f32 v[162:163], v[220:221], v[162:163]
	ds_bpermute_b32 v224, v240, v222
	v_pk_fma_f32 v[162:163], v[226:227], v[244:245], v[162:163]
	ds_bpermute_b32 v225, v240, v223
	v_pk_add_f32 v[160:161], v[160:161], v[162:163]
	v_mul_f32_e32 v162, v209, v149
	v_pk_fma_f32 v[148:149], v[208:209], v[148:149], v[162:163] op_sel_hi:[1,1,0]
	v_mul_f32_e32 v162, v207, v151
	v_pk_fma_f32 v[150:151], v[206:207], v[150:151], v[162:163] op_sel_hi:[1,1,0]
	v_mov_b32_e32 v149, v242
	v_mov_b32_e32 v151, v33
	v_pk_add_f32 v[148:149], v[148:149], v[150:151]
	v_pk_mov_b32 v[150:151], v[152:153], v[214:215] op_sel:[1,0]
	v_mov_b32_e32 v153, v215
	v_pk_mul_f32 v[152:153], v[214:215], v[152:153]
	v_mov_b32_e32 v33, v211
	v_pk_fma_f32 v[150:151], v[214:215], v[150:151], v[152:153] op_sel:[1,0,0] op_sel_hi:[0,1,1]
	v_pk_mov_b32 v[152:153], v[154:155], v[212:213] op_sel:[1,0]
	v_mov_b32_e32 v155, v213
	v_pk_mul_f32 v[154:155], v[212:213], v[154:155]
	v_pk_add_f32 v[148:149], v[148:149], v[32:33]
	v_pk_fma_f32 v[152:153], v[212:213], v[152:153], v[154:155] op_sel:[1,0,0] op_sel_hi:[0,1,1]
	v_pk_add_f32 v[148:149], v[160:161], v[148:149]
	v_pk_add_f32 v[150:151], v[150:151], v[152:153]
	s_waitcnt lgkmcnt(0)
	v_pk_add_f32 v[222:223], v[222:223], v[224:225]
	v_pk_add_f32 v[148:149], v[148:149], v[150:151]
	v_pk_mov_b32 v[150:151], v[156:157], v[218:219] op_sel:[1,0]
	v_mov_b32_e32 v157, v219
	v_pk_mul_f32 v[152:153], v[218:219], v[156:157]
	ds_bpermute_b32 v224, v239, v222
	v_pk_fma_f32 v[150:151], v[218:219], v[150:151], v[152:153] op_sel:[1,0,0] op_sel_hi:[0,1,1]
	v_pk_mov_b32 v[152:153], v[158:159], v[216:217] op_sel:[1,0]
	v_mov_b32_e32 v159, v217
	v_pk_mul_f32 v[154:155], v[216:217], v[158:159]
	ds_bpermute_b32 v225, v239, v223
	v_pk_fma_f32 v[152:153], v[216:217], v[152:153], v[154:155] op_sel:[1,0,0] op_sel_hi:[0,1,1]
	v_pk_add_f32 v[150:151], v[150:151], v[152:153]
	s_nop 0
	v_pk_add_f32 v[148:149], v[148:149], v[150:151]
	ds_bpermute_b32 v150, v240, v148
	ds_bpermute_b32 v151, v240, v149
	s_waitcnt lgkmcnt(0)
	v_pk_add_f32 v[148:149], v[148:149], v[150:151]
	ds_bpermute_b32 v150, v239, v148
	ds_bpermute_b32 v151, v239, v149
	s_and_saveexec_b64 s[6:7], vcc
	s_cbranch_execz .LBB0_847
	v_lshl_add_u32 v33, v241, 6, s19
	s_waitcnt lgkmcnt(0)
	v_pk_add_f32 v[150:151], v[148:149], v[150:151]
	v_pk_add_f32 v[148:149], v[222:223], v[224:225]
	ds_write_b128 v33, v[148:151]

;     __device__ __forceinline__ void fused(f32x4 (&acc)[2][2][4][2], const Unit& u, int wr, int wc, int fr, int fq, PG8_LAS unsigned char* lds, int wid, int lane) const {
;     ...
;         const int col0 = u.pn * BM + wc * 32 + 4 * fq;
;         f32x4 gv[2][2];
; #pragma unroll
;         for (int bj = 0; bj < 2; ++bj)
; #pragma unroll
;             for (int n = 0; n < 2; ++n) gv[bj][n] = *(const f32x4*)(g1 + col0 + bj * HALF + n * 16);
; #pragma unroll
;         for (int ai = 0; ai < 2; ++ai)
; #pragma unroll
;             for (int m = 0; m < 4; ++m) { const int r = ai * HALF + wr * 64 + m * 16 + fr; const size_t off = (size_t)(u.pm * BM + r) * 1024 + col0;
;                 float s0 = 0.f, s1 = 0.f, s2 = 0.f, s3 = 0.f;
; #pragma unroll
;                 for (int bj = 0; bj < 2; ++bj)
; #pragma unroll
;                     for (int n = 0; n < 2; ++n) { const f32x4 bs = *(const f32x4*)(base + off + bj * HALF + n * 16), a = acc[ai][bj][m][n], ag = a * gv[bj][n];
;                         s0 += (a[0] * a[0] + a[1] * a[1]) + (a[2] * a[2] + a[3] * a[3]); s1 += (bs[0] * bs[0] + bs[1] * bs[1]) + (bs[2] * bs[2] + bs[3] * bs[3]);
;                         s2 += (bs[0] * ag[0] + bs[1] * ag[1]) + (bs[2] * ag[2] + bs[3] * ag[3]); s3 += (ag[0] * ag[0] + ag[1] * ag[1]) + (ag[2] * ag[2] + ag[3] * ag[3]); }
;                 s0 += __shfl_xor(s0, 16); s0 += __shfl_xor(s0, 32); s1 += __shfl_xor(s1, 16); s1 += __shfl_xor(s1, 32);
;                 s2 += __shfl_xor(s2, 16); s2 += __shfl_xor(s2, 32); s3 += __shfl_xor(s3, 16); s3 += __shfl_xor(s3, 32);
;                 if (fq == 0) P[r * 4 + wc] = (f32x4){s0, s1, s2, s3};
.LBB0_1088:
	s_ashr_i32 s17, s16, 31
	s_lshl_b64 s[4:5], s[16:17], 14
	s_add_u32 s42, s26, s4
	s_addc_u32 s43, s27, s5
	s_lshl_b32 s4, s29, 5
	s_lshl_b32 s5, s28, 8
	s_or_b32 s4, s5, s4
	v_lshrrev_b32_e32 v33, 2, v195
	v_and_or_b32 v34, v33, 12, s4
	v_ashrrev_i32_e32 v35, 31, v34
	v_lshlrev_b64 v[148:149], 2, v[34:35]
	v_lshl_add_u64 v[132:133], s[42:43], 0, v[148:149]
	s_mov_b64 s[4:5], 0x3000
	v_lshl_add_u64 v[134:135], v[132:133], 0, s[4:5]
	v_add_co_u32_e32 v132, vcc, s2, v132
	v_and_b32_e32 v150, 64, v233
	s_nop 0
	v_addc_co_u32_e32 v133, vcc, 0, v133, vcc
	v_xor_b32_e32 v33, 16, v233
	v_add_u32_e32 v150, 64, v150
	s_lshl_b32 s17, s90, 8
	v_cmp_lt_i32_e32 vcc, v33, v150
	v_add_u32_e32 v166, s17, v237
	v_ashrrev_i32_e32 v167, 31, v166
	v_cndmask_b32_e32 v33, v233, v33, vcc
	v_lshlrev_b32_e32 v240, 2, v33
	v_xor_b32_e32 v33, 32, v233
	v_cmp_lt_i32_e32 vcc, v33, v150
	v_lshlrev_b64 v[150:151], 12, v[166:167]
	v_lshl_add_u64 v[150:151], s[30:31], 0, v[150:151]
	v_lshl_add_u64 v[164:165], v[150:151], 0, v[148:149]
	s_barrier
	global_load_dwordx4 v[144:147], v[132:133], off
	global_load_dwordx4 v[140:143], v[134:135], off offset:64
	global_load_dwordx4 v[136:139], v[134:135], off offset:512
	s_nop 0
	global_load_dwordx4 v[132:135], v[134:135], off offset:576
	v_pk_mul_f32 v[152:153], v[130:131], v[130:131]
	v_readfirstlane_b32 s72, v228
	s_nop 3
	s_lshr_b32 s72, s72, 6
	s_mul_i32 s72, s72, 0x3000
	s_add_i32 s72, s72, 0x5000
	s_mov_b64 s[98:99], 0x0
	v_lshl_add_u64 v[160:161], v[164:165], 0, s[98:99]
	s_add_i32 m0, s72, 0x0
	s_nop 0
	global_load_lds_dwordx4 v[160:161], off
	s_mov_b64 s[98:99], 0x40
	v_lshl_add_u64 v[160:161], v[164:165], 0, s[98:99]
	s_add_i32 m0, s72, 0x400
	s_nop 0
	global_load_lds_dwordx4 v[160:161], off
	s_mov_b64 s[98:99], 0x200
	v_lshl_add_u64 v[160:161], v[164:165], 0, s[98:99]
	s_add_i32 m0, s72, 0x800
	s_nop 0
	global_load_lds_dwordx4 v[160:161], off
	s_mov_b64 s[98:99], 0x240
	v_lshl_add_u64 v[160:161], v[164:165], 0, s[98:99]
	s_add_i32 m0, s72, 0xc00
	s_nop 0
	global_load_lds_dwordx4 v[160:161], off
	s_mov_b64 s[98:99], 0x10000
	v_lshl_add_u64 v[160:161], v[164:165], 0, s[98:99]
	s_add_i32 m0, s72, 0x1000
	s_nop 0
	global_load_lds_dwordx4 v[160:161], off
	s_mov_b64 s[98:99], 0x10040
	v_lshl_add_u64 v[160:161], v[164:165], 0, s[98:99]
	s_add_i32 m0, s72, 0x1400
	s_nop 0
	global_load_lds_dwordx4 v[160:161], off
	s_mov_b64 s[98:99], 0x10200
	v_lshl_add_u64 v[160:161], v[164:165], 0, s[98:99]
	s_add_i32 m0, s72, 0x1800
	s_nop 0
	global_load_lds_dwordx4 v[160:161], off
	s_mov_b64 s[98:99], 0x10240
	v_lshl_add_u64 v[160:161], v[164:165], 0, s[98:99]
	s_add_i32 m0, s72, 0x1c00
	s_nop 0
	global_load_lds_dwordx4 v[160:161], off
	s_mov_b64 s[98:99], 0x20000
	v_lshl_add_u64 v[160:161], v[164:165], 0, s[98:99]
	s_add_i32 m0, s72, 0x2000
	s_nop 0
	global_load_lds_dwordx4 v[160:161], off
	s_mov_b64 s[98:99], 0x20040
	v_lshl_add_u64 v[160:161], v[164:165], 0, s[98:99]
	s_add_i32 m0, s72, 0x2400
	s_nop 0
	global_load_lds_dwordx4 v[160:161], off
	s_mov_b64 s[98:99], 0x20200
	v_lshl_add_u64 v[160:161], v[164:165], 0, s[98:99]
	s_add_i32 m0, s72, 0x2800
	s_nop 0
	global_load_lds_dwordx4 v[160:161], off
	s_mov_b64 s[98:99], 0x20240
	v_lshl_add_u64 v[160:161], v[164:165], 0, s[98:99]
	s_add_i32 m0, s72, 0x2c00
	s_nop 0
	global_load_lds_dwordx4 v[160:161], off
	s_add_i32 s98, s72, 0x0
	s_waitcnt vmcnt(11)
	v_and_b32_e32 v148, 63, v228
	v_lshl_add_u32 v148, v148, 4, s98
	ds_read_b128 v[148:151], v148
	v_pk_mul_f32 v[154:155], v[128:129], v[128:129]
	v_pk_mul_f32 v[158:159], v[124:125], v[124:125]
	v_pk_mov_b32 v[156:157], v[154:155], v[152:153] op_sel:[1,0]
	v_mov_b32_e32 v155, v153
	v_pk_add_f32 v[172:173], v[156:157], v[154:155]
	v_cndmask_b32_e32 v33, v233, v33, vcc
	v_pk_add_f32 v[172:173], v[172:173], v[172:173] op_sel:[0,1] op_sel_hi:[1,0]
	v_lshlrev_b32_e32 v239, 2, v33
	v_and_b32_e32 v238, 63, v195
	s_lshl_b32 s4, s29, 4
	v_cmp_gt_u32_e32 vcc, 16, v238
	s_add_i32 s29, s4, 0
	s_waitcnt lgkmcnt(0)
	v_pk_mul_f32 v[170:171], v[128:129], v[144:145]
	v_pk_mul_f32 v[176:177], v[126:127], v[142:143]
	v_pk_mul_f32 v[178:179], v[124:125], v[140:141]
	v_pk_mul_f32 v[168:169], v[130:131], v[146:147]
	v_mul_f32_e32 v193, v178, v178
	v_pk_mul_f32 v[152:153], v[150:151], v[150:151]
	v_pk_mul_f32 v[154:155], v[148:149], v[148:149]
	v_mul_f32_e32 v33, v179, v179
	v_pk_mov_b32 v[156:157], v[154:155], v[152:153] op_sel:[1,0]
	v_mov_b32_e32 v155, v153
	v_pk_add_f32 v[152:153], v[156:157], v[154:155]
	v_pk_mul_f32 v[156:157], v[126:127], v[126:127]
	v_pk_add_f32 v[190:191], v[152:153], v[152:153] op_sel_hi:[0,1]
	s_waitcnt vmcnt(10)
	v_and_b32_e32 v152, 63, v228
	v_lshl_add_u32 v152, v152, 4, s98
	ds_read_b128 v[152:155], v152 offset:1024
	v_pk_mov_b32 v[160:161], v[158:159], v[156:157] op_sel:[1,0]
	v_mov_b32_e32 v159, v157
	v_pk_add_f32 v[180:181], v[160:161], v[158:159]
	v_mul_f32_e32 v190, v116, v116
	v_pk_add_f32 v[180:181], v[180:181], v[180:181] op_sel:[0,1] op_sel_hi:[1,0]
	v_pk_mul_f32 v[184:185], v[120:121], v[136:137]
	v_pk_mul_f32 v[182:183], v[122:123], v[138:139]
	v_pk_mul_f32 v[188:189], v[116:117], v[132:133]
	v_pk_mul_f32 v[186:187], v[118:119], v[134:135]
	s_waitcnt lgkmcnt(0)
	v_pk_mul_f32 v[156:157], v[154:155], v[154:155]
	v_pk_mul_f32 v[158:159], v[152:153], v[152:153]
	s_nop 0
	v_pk_mov_b32 v[160:161], v[158:159], v[156:157] op_sel:[1,0]
	v_mov_b32_e32 v159, v157
	v_pk_add_f32 v[156:157], v[160:161], v[158:159]
	s_nop 0
	v_pk_add_f32 v[204:205], v[156:157], v[156:157] op_sel_hi:[0,1]
	v_mul_f32_e32 v156, v176, v176
	v_pk_fma_f32 v[174:175], v[176:177], v[176:177], v[156:157] op_sel_hi:[1,1,0]
	s_waitcnt vmcnt(9)
;     __device__ __forceinline__ void fused(f32x4 (&acc)[2][2][4][2], const Unit& u, int wr, int wc, int fr, int fq, PG8_LAS unsigned char* lds, int wid, int lane) const {
;     ...
;                     for (int n = 0; n < 2; ++n) { const f32x4 bs = *(const f32x4*)(base + off + bj * HALF + n * 16), a = acc[ai][bj][m][n], ag = a * gv[bj][n];
;                         s0 += (a[0] * a[0] + a[1] * a[1]) + (a[2] * a[2] + a[3] * a[3]); s1 += (bs[0] * bs[0] + bs[1] * bs[1]) + (bs[2] * bs[2] + bs[3] * bs[3]);
;                         s2 += (bs[0] * ag[0] + bs[1] * ag[1]) + (bs[2] * ag[2] + bs[3] * ag[3]); s3 += (ag[0] * ag[0] + ag[1] * ag[1]) + (ag[2] * ag[2] + ag[3] * ag[3]); }
;                 s0 += __shfl_xor(s0, 16); s0 += __shfl_xor(s0, 32); s1 += __shfl_xor(s1, 16); s1 += __shfl_xor(s1, 32);
;                 s2 += __shfl_xor(s2, 16); s2 += __shfl_xor(s2, 32); s3 += __shfl_xor(s3, 16); s3 += __shfl_xor(s3, 32);
;                 if (fq == 0) P[r * 4 + wc] = (f32x4){s0, s1, s2, s3};
	v_and_b32_e32 v156, 63, v228
	v_lshl_add_u32 v156, v156, 4, s98
	ds_read_b128 v[156:159], v156 offset:2048
	v_mul_f32_e32 v204, v117, v117
	v_pk_add_f32 v[190:191], v[190:191], v[204:205]
	v_mul_f32_e32 v174, v121, v121
	s_waitcnt lgkmcnt(0)
	v_mul_f32_e32 v160, v156, v156
	v_pk_fma_f32 v[206:207], v[156:157], v[156:157], v[160:161] op_sel_hi:[1,1,0]
	v_mul_f32_e32 v160, v158, v158
	v_pk_fma_f32 v[208:209], v[158:159], v[158:159], v[160:161] op_sel_hi:[1,1,0]
	s_waitcnt vmcnt(8)
	v_and_b32_e32 v160, 63, v228
	v_lshl_add_u32 v160, v160, 4, s98
	ds_read_b128 v[160:163], v160 offset:3072
	v_mul_f32_e32 v206, v118, v118
	v_mul_f32_e32 v208, v119, v119
	v_pk_add_f32 v[204:205], v[206:207], v[208:209]
	s_waitcnt lgkmcnt(0)
	v_mul_f32_e32 v210, v160, v160
	v_pk_add_f32 v[190:191], v[190:191], v[204:205]
	v_pk_fma_f32 v[204:205], v[120:121], v[120:121], v[174:175] op_sel_hi:[1,1,0]
	v_mul_f32_e32 v174, v123, v123
	v_mul_f32_e32 v211, v161, v161
	v_mul_f32_e32 v212, v162, v162
	v_mul_f32_e32 v213, v163, v163
	v_pk_fma_f32 v[206:207], v[122:123], v[122:123], v[174:175] op_sel_hi:[1,1,0]
	v_mov_b32_e32 v205, v210
	v_mov_b32_e32 v207, v211
	v_mov_b32_e32 v181, v212
	v_mov_b32_e32 v173, v213
	v_pk_add_f32 v[204:205], v[204:205], v[206:207]
	v_pk_add_f32 v[172:173], v[180:181], v[172:173]
	s_nop 0
	v_pk_add_f32 v[172:173], v[204:205], v[172:173]
	v_mov_b32_e32 v204, v152
	v_pk_add_f32 v[172:173], v[190:191], v[172:173]
	v_mov_b32_e32 v190, v178
	v_mov_b32_e32 v178, v179
	v_mov_b32_e32 v179, v171
	v_mov_b32_e32 v152, v153
	v_mov_b32_e32 v153, v171
	v_mov_b32_e32 v191, v170
	v_mov_b32_e32 v205, v170
	v_pk_mul_f32 v[152:153], v[178:179], v[152:153]
	v_mov_b32_e32 v178, v176
	v_pk_fma_f32 v[152:153], v[190:191], v[204:205], v[152:153]
	v_mov_b32_e32 v190, v154
	v_mov_b32_e32 v176, v177
	v_mov_b32_e32 v177, v169
	v_mov_b32_e32 v154, v155
	v_mov_b32_e32 v155, v169
	v_mov_b32_e32 v179, v168
	v_mov_b32_e32 v191, v168
	v_pk_mul_f32 v[154:155], v[176:177], v[154:155]
	ds_bpermute_b32 v180, v240, v172
	v_pk_fma_f32 v[154:155], v[178:179], v[190:191], v[154:155]
	ds_bpermute_b32 v181, v240, v173
	v_pk_add_f32 v[152:153], v[152:153], v[154:155]
	v_mul_f32_e32 v154, v171, v149
	v_pk_fma_f32 v[148:149], v[170:171], v[148:149], v[154:155] op_sel_hi:[1,1,0]
	v_mul_f32_e32 v154, v169, v151
	v_pk_fma_f32 v[150:151], v[168:169], v[150:151], v[154:155] op_sel_hi:[1,1,0]
	v_mov_b32_e32 v149, v193
	v_mov_b32_e32 v151, v33
	v_pk_add_f32 v[148:149], v[148:149], v[150:151]
	v_mov_b32_e32 v33, v175
	v_pk_add_f32 v[148:149], v[148:149], v[32:33]
	v_pk_mov_b32 v[150:151], v[156:157], v[184:185] op_sel:[1,0]
	v_mov_b32_e32 v157, v185
	v_pk_add_f32 v[148:149], v[152:153], v[148:149]
	v_pk_mul_f32 v[152:153], v[184:185], v[156:157]
	s_waitcnt lgkmcnt(0)
	v_pk_add_f32 v[172:173], v[172:173], v[180:181]
	v_pk_fma_f32 v[150:151], v[184:185], v[150:151], v[152:153] op_sel:[1,0,0] op_sel_hi:[0,1,1]
	v_pk_mov_b32 v[152:153], v[158:159], v[182:183] op_sel:[1,0]
	v_mov_b32_e32 v159, v183
	v_pk_mul_f32 v[154:155], v[182:183], v[158:159]
	ds_bpermute_b32 v180, v239, v172
	v_pk_fma_f32 v[152:153], v[182:183], v[152:153], v[154:155] op_sel:[1,0,0] op_sel_hi:[0,1,1]
	v_pk_add_f32 v[150:151], v[150:151], v[152:153]
	ds_bpermute_b32 v181, v239, v173
	v_pk_add_f32 v[148:149], v[148:149], v[150:151]
	v_pk_mov_b32 v[150:151], v[160:161], v[188:189] op_sel:[1,0]
	v_mov_b32_e32 v161, v189
	v_pk_mul_f32 v[152:153], v[188:189], v[160:161]
	s_nop 0
	v_pk_fma_f32 v[150:151], v[188:189], v[150:151], v[152:153] op_sel:[1,0,0] op_sel_hi:[0,1,1]
	v_pk_mov_b32 v[152:153], v[162:163], v[186:187] op_sel:[1,0]
	v_mov_b32_e32 v163, v187
	v_pk_mul_f32 v[154:155], v[186:187], v[162:163]
	s_nop 0
	v_pk_fma_f32 v[152:153], v[186:187], v[152:153], v[154:155] op_sel:[1,0,0] op_sel_hi:[0,1,1]
	v_pk_add_f32 v[150:151], v[150:151], v[152:153]
	s_nop 0
	v_pk_add_f32 v[148:149], v[148:149], v[150:151]
	ds_bpermute_b32 v150, v240, v148
	ds_bpermute_b32 v151, v240, v149
	s_waitcnt lgkmcnt(0)
	v_pk_add_f32 v[148:149], v[148:149], v[150:151]
	ds_bpermute_b32 v150, v239, v148
	ds_bpermute_b32 v151, v239, v149
	s_and_saveexec_b64 s[6:7], vcc
	v_readlane_b32 s56, v255, 4
	v_readlane_b32 s58, v255, 6
	v_readlane_b32 s52, v255, 8
	v_readlane_b32 s57, v255, 5
	v_readlane_b32 s59, v255, 7
	v_readlane_b32 s53, v255, 9
	v_readlane_b32 s55, v255, 10
	s_cbranch_execz .LBB0_1090
	v_add_u32_e32 v33, s29, v192
	s_waitcnt lgkmcnt(0)
	v_pk_add_f32 v[150:151], v[148:149], v[150:151]
	v_pk_add_f32 v[148:149], v[172:173], v[180:181]
	ds_write_b128 v33, v[148:151]
;     __device__ __forceinline__ void fused(f32x4 (&acc)[2][2][4][2], const Unit& u, int wr, int wc, int fr, int fq, PG8_LAS unsigned char* lds, int wid, int lane) const {
;     ...
;             for (int m = 0; m < 4; ++m) { const int r = ai * HALF + wr * 64 + m * 16 + fr; const size_t off = (size_t)(u.pm * BM + r) * 1024 + col0;
;                 float s0 = 0.f, s1 = 0.f, s2 = 0.f, s3 = 0.f;
; #pragma unroll
;                 for (int bj = 0; bj < 2; ++bj)
; #pragma unroll
;                     for (int n = 0; n < 2; ++n) { const f32x4 bs = *(const f32x4*)(base + off + bj * HALF + n * 16), a = acc[ai][bj][m][n], ag = a * gv[bj][n];
;                         s0 += (a[0] * a[0] + a[1] * a[1]) + (a[2] * a[2] + a[3] * a[3]); s1 += (bs[0] * bs[0] + bs[1] * bs[1]) + (bs[2] * bs[2] + bs[3] * bs[3]);
;                         s2 += (bs[0] * ag[0] + bs[1] * ag[1]) + (bs[2] * ag[2] + bs[3] * ag[3]); s3 += (ag[0] * ag[0] + ag[1] * ag[1]) + (ag[2] * ag[2] + ag[3] * ag[3]); }
;                 s0 += __shfl_xor(s0, 16); s0 += __shfl_xor(s0, 32); s1 += __shfl_xor(s1, 16); s1 += __shfl_xor(s1, 32);
;                 s2 += __shfl_xor(s2, 16); s2 += __shfl_xor(s2, 32); s3 += __shfl_xor(s3, 16); s3 += __shfl_xor(s3, 32);
;                 if (fq == 0) P[r * 4 + wc] = (f32x4){s0, s1, s2, s3};
.LBB0_1090:
	s_or_b64 exec, exec, s[6:7]
	s_mov_b64 s[98:99], 0x30000
	v_lshl_add_u64 v[160:161], v[164:165], 0, s[98:99]
	s_add_i32 m0, s72, 0x0
	s_nop 0
	global_load_lds_dwordx4 v[160:161], off
	s_mov_b64 s[98:99], 0x30040
	v_lshl_add_u64 v[160:161], v[164:165], 0, s[98:99]
	s_add_i32 m0, s72, 0x400
	s_nop 0
	global_load_lds_dwordx4 v[160:161], off
	s_mov_b64 s[98:99], 0x30200
	v_lshl_add_u64 v[160:161], v[164:165], 0, s[98:99]
	s_add_i32 m0, s72, 0x800
	s_nop 0
	global_load_lds_dwordx4 v[160:161], off
	s_mov_b64 s[98:99], 0x30240
	v_lshl_add_u64 v[160:161], v[164:165], 0, s[98:99]
	s_add_i32 m0, s72, 0xc00
	s_nop 0
	global_load_lds_dwordx4 v[160:161], off
	v_or_b32_e32 v204, 16, v237
	v_add_u32_e32 v170, s17, v204
	v_ashrrev_i32_e32 v171, 31, v170
	v_lshlrev_b64 v[148:149], 12, v[170:171]
	v_lshl_add_u64 v[148:149], s[30:31], 0, v[148:149]
	v_lshl_add_u64 v[168:169], v[34:35], 2, v[148:149]
	s_waitcnt lgkmcnt(0)
	s_add_i32 s98, s72, 0x1000
	s_waitcnt vmcnt(11)
	v_and_b32_e32 v148, 63, v228
	v_lshl_add_u32 v148, v148, 4, s98
	ds_read_b128 v[148:151], v148
	s_waitcnt vmcnt(10)
	v_and_b32_e32 v160, 63, v228
	v_lshl_add_u32 v160, v160, 4, s98
	ds_read_b128 v[160:163], v160 offset:1024
	v_pk_mul_f32 v[152:153], v[114:115], v[114:115]
	v_pk_mul_f32 v[154:155], v[112:113], v[112:113]
	v_pk_mul_f32 v[186:187], v[110:111], v[142:143]
	v_pk_mov_b32 v[156:157], v[154:155], v[152:153] op_sel:[1,0]
	v_mov_b32_e32 v155, v153
	v_pk_add_f32 v[188:189], v[156:157], v[154:155]
	v_pk_mul_f32 v[174:175], v[112:113], v[144:145]
	v_pk_add_f32 v[188:189], v[188:189], v[188:189] op_sel:[0,1] op_sel_hi:[1,0]
	v_pk_mul_f32 v[192:193], v[108:109], v[140:141]
	v_pk_mul_f32 v[172:173], v[114:115], v[146:147]
	v_mul_f32_e32 v205, v192, v192
	v_mul_f32_e32 v33, v193, v193
	v_pk_mul_f32 v[180:181], v[104:105], v[136:137]
	v_pk_mul_f32 v[178:179], v[106:107], v[138:139]
	v_pk_mul_f32 v[184:185], v[100:101], v[132:133]
	v_pk_mul_f32 v[182:183], v[102:103], v[134:135]
	s_waitcnt lgkmcnt(1)
	v_pk_mul_f32 v[152:153], v[150:151], v[150:151]
	v_pk_mul_f32 v[154:155], v[148:149], v[148:149]
	s_nop 0
	v_pk_mov_b32 v[156:157], v[154:155], v[152:153] op_sel:[1,0]
	v_mov_b32_e32 v155, v153
	v_pk_add_f32 v[152:153], v[156:157], v[154:155]
	v_pk_mul_f32 v[154:155], v[108:109], v[108:109]
	v_pk_add_f32 v[206:207], v[152:153], v[152:153] op_sel_hi:[0,1]
	v_pk_mul_f32 v[152:153], v[110:111], v[110:111]
	v_mul_f32_e32 v206, v100, v100
	v_pk_mov_b32 v[156:157], v[154:155], v[152:153] op_sel:[1,0]
	v_mov_b32_e32 v155, v153
	v_pk_add_f32 v[190:191], v[156:157], v[154:155]
	s_waitcnt lgkmcnt(0)
	v_pk_mul_f32 v[152:153], v[162:163], v[162:163]
	v_pk_mul_f32 v[154:155], v[160:161], v[160:161]
	v_pk_add_f32 v[190:191], v[190:191], v[190:191] op_sel:[0,1] op_sel_hi:[1,0]
	v_pk_mov_b32 v[156:157], v[154:155], v[152:153] op_sel:[1,0]
	v_mov_b32_e32 v155, v153
	v_pk_add_f32 v[152:153], v[156:157], v[154:155]
	s_nop 0
	v_pk_add_f32 v[208:209], v[152:153], v[152:153] op_sel_hi:[0,1]
	v_mul_f32_e32 v152, v186, v186
	v_pk_fma_f32 v[176:177], v[186:187], v[186:187], v[152:153] op_sel_hi:[1,1,0]
	s_waitcnt vmcnt(9)
	v_and_b32_e32 v152, 63, v228
	v_lshl_add_u32 v152, v152, 4, s98
	ds_read_b128 v[152:155], v152 offset:2048
	v_mul_f32_e32 v208, v101, v101
	v_pk_add_f32 v[206:207], v[206:207], v[208:209]
	v_mul_f32_e32 v176, v105, v105
	s_waitcnt lgkmcnt(0)
	v_mul_f32_e32 v156, v152, v152
	v_pk_fma_f32 v[210:211], v[152:153], v[152:153], v[156:157] op_sel_hi:[1,1,0]
	v_mul_f32_e32 v156, v154, v154
	v_pk_fma_f32 v[212:213], v[154:155], v[154:155], v[156:157] op_sel_hi:[1,1,0]
	s_waitcnt vmcnt(8)
	v_and_b32_e32 v156, 63, v228
	v_lshl_add_u32 v156, v156, 4, s98
	ds_read_b128 v[156:159], v156 offset:3072
	v_mul_f32_e32 v210, v102, v102
	v_mul_f32_e32 v212, v103, v103
	v_pk_add_f32 v[208:209], v[210:211], v[212:213]
	s_waitcnt lgkmcnt(0)
	v_mul_f32_e32 v214, v156, v156
	v_pk_add_f32 v[206:207], v[206:207], v[208:209]
	v_pk_fma_f32 v[208:209], v[104:105], v[104:105], v[176:177] op_sel_hi:[1,1,0]
	v_mul_f32_e32 v176, v107, v107
	v_mul_f32_e32 v215, v157, v157
	v_mul_f32_e32 v216, v158, v158
	v_mul_f32_e32 v217, v159, v159
	v_pk_fma_f32 v[210:211], v[106:107], v[106:107], v[176:177] op_sel_hi:[1,1,0]
	v_mov_b32_e32 v209, v214
	v_mov_b32_e32 v211, v215
	v_mov_b32_e32 v191, v216
	v_mov_b32_e32 v189, v217
	v_pk_add_f32 v[208:209], v[208:209], v[210:211]
	v_pk_add_f32 v[188:189], v[190:191], v[188:189]
	s_nop 0
	v_pk_add_f32 v[188:189], v[208:209], v[188:189]
	v_mov_b32_e32 v208, v160
	v_pk_add_f32 v[188:189], v[206:207], v[188:189]
	v_mov_b32_e32 v206, v192
	v_mov_b32_e32 v192, v193
	v_mov_b32_e32 v193, v175
	v_mov_b32_e32 v160, v161
	v_mov_b32_e32 v161, v175
	v_mov_b32_e32 v207, v174
	v_mov_b32_e32 v209, v174
	v_pk_mul_f32 v[160:161], v[192:193], v[160:161]
	v_mov_b32_e32 v192, v186
	v_pk_fma_f32 v[160:161], v[206:207], v[208:209], v[160:161]
	v_mov_b32_e32 v206, v162
	v_mov_b32_e32 v186, v187
	v_mov_b32_e32 v187, v173
	v_mov_b32_e32 v162, v163
	v_mov_b32_e32 v163, v173
	v_mov_b32_e32 v193, v172
	v_mov_b32_e32 v207, v172
	v_pk_mul_f32 v[162:163], v[186:187], v[162:163]
	ds_bpermute_b32 v190, v240, v188
	v_pk_fma_f32 v[162:163], v[192:193], v[206:207], v[162:163]
	ds_bpermute_b32 v191, v240, v189
	v_pk_add_f32 v[160:161], v[160:161], v[162:163]
	v_mul_f32_e32 v162, v175, v149
	v_pk_fma_f32 v[148:149], v[174:175], v[148:149], v[162:163] op_sel_hi:[1,1,0]
	v_mul_f32_e32 v162, v173, v151
	v_pk_fma_f32 v[150:151], v[172:173], v[150:151], v[162:163] op_sel_hi:[1,1,0]
	v_mov_b32_e32 v149, v205
	v_mov_b32_e32 v151, v33
	v_pk_add_f32 v[148:149], v[148:149], v[150:151]
	v_pk_mov_b32 v[150:151], v[152:153], v[180:181] op_sel:[1,0]
	v_mov_b32_e32 v153, v181
	v_pk_mul_f32 v[152:153], v[180:181], v[152:153]
	v_mov_b32_e32 v33, v177
	v_pk_fma_f32 v[150:151], v[180:181], v[150:151], v[152:153] op_sel:[1,0,0] op_sel_hi:[0,1,1]
	v_pk_mov_b32 v[152:153], v[154:155], v[178:179] op_sel:[1,0]
	v_mov_b32_e32 v155, v179
	v_pk_mul_f32 v[154:155], v[178:179], v[154:155]
	v_pk_add_f32 v[148:149], v[148:149], v[32:33]
	v_pk_fma_f32 v[152:153], v[178:179], v[152:153], v[154:155] op_sel:[1,0,0] op_sel_hi:[0,1,1]
	v_pk_add_f32 v[148:149], v[160:161], v[148:149]
	v_pk_add_f32 v[150:151], v[150:151], v[152:153]
	s_waitcnt lgkmcnt(0)
;     __device__ __forceinline__ void fused(f32x4 (&acc)[2][2][4][2], const Unit& u, int wr, int wc, int fr, int fq, PG8_LAS unsigned char* lds, int wid, int lane) const {
;     ...
;             for (int m = 0; m < 4; ++m) { const int r = ai * HALF + wr * 64 + m * 16 + fr; const size_t off = (size_t)(u.pm * BM + r) * 1024 + col0;
;                 float s0 = 0.f, s1 = 0.f, s2 = 0.f, s3 = 0.f;
; #pragma unroll
;                 for (int bj = 0; bj < 2; ++bj)
; #pragma unroll
;                     for (int n = 0; n < 2; ++n) { const f32x4 bs = *(const f32x4*)(base + off + bj * HALF + n * 16), a = acc[ai][bj][m][n], ag = a * gv[bj][n];
;                         s0 += (a[0] * a[0] + a[1] * a[1]) + (a[2] * a[2] + a[3] * a[3]); s1 += (bs[0] * bs[0] + bs[1] * bs[1]) + (bs[2] * bs[2] + bs[3] * bs[3]);
;                         s2 += (bs[0] * ag[0] + bs[1] * ag[1]) + (bs[2] * ag[2] + bs[3] * ag[3]); s3 += (ag[0] * ag[0] + ag[1] * ag[1]) + (ag[2] * ag[2] + ag[3] * ag[3]); }
;                 s0 += __shfl_xor(s0, 16); s0 += __shfl_xor(s0, 32); s1 += __shfl_xor(s1, 16); s1 += __shfl_xor(s1, 32);
;                 s2 += __shfl_xor(s2, 16); s2 += __shfl_xor(s2, 32); s3 += __shfl_xor(s3, 16); s3 += __shfl_xor(s3, 32);
;                 if (fq == 0) P[r * 4 + wc] = (f32x4){s0, s1, s2, s3};
	v_pk_add_f32 v[188:189], v[188:189], v[190:191]
	v_pk_add_f32 v[148:149], v[148:149], v[150:151]
	v_pk_mov_b32 v[150:151], v[156:157], v[184:185] op_sel:[1,0]
	v_mov_b32_e32 v157, v185
	v_pk_mul_f32 v[152:153], v[184:185], v[156:157]
	ds_bpermute_b32 v190, v239, v188
	v_pk_fma_f32 v[150:151], v[184:185], v[150:151], v[152:153] op_sel:[1,0,0] op_sel_hi:[0,1,1]
	v_pk_mov_b32 v[152:153], v[158:159], v[182:183] op_sel:[1,0]
	v_mov_b32_e32 v159, v183
	v_pk_mul_f32 v[154:155], v[182:183], v[158:159]
	ds_bpermute_b32 v191, v239, v189
	v_pk_fma_f32 v[152:153], v[182:183], v[152:153], v[154:155] op_sel:[1,0,0] op_sel_hi:[0,1,1]
	v_pk_add_f32 v[150:151], v[150:151], v[152:153]
	s_nop 0
	v_pk_add_f32 v[148:149], v[148:149], v[150:151]
	ds_bpermute_b32 v150, v240, v148
	ds_bpermute_b32 v151, v240, v149
	s_waitcnt lgkmcnt(0)
	v_pk_add_f32 v[148:149], v[148:149], v[150:151]
	ds_bpermute_b32 v150, v239, v148
	ds_bpermute_b32 v151, v239, v149
	s_and_saveexec_b64 s[6:7], vcc
	s_cbranch_execz .LBB0_1092
	v_lshl_add_u32 v33, v204, 6, s29
	s_waitcnt lgkmcnt(0)
	v_pk_add_f32 v[150:151], v[148:149], v[150:151]
	v_pk_add_f32 v[148:149], v[188:189], v[190:191]
	ds_write_b128 v33, v[148:151]
.LBB0_1092:
	s_or_b64 exec, exec, s[6:7]
	s_mov_b64 s[98:99], 0x80000
	v_lshl_add_u64 v[160:161], v[164:165], 0, s[98:99]
	s_add_i32 m0, s72, 0x1000
	s_nop 0
	global_load_lds_dwordx4 v[160:161], off
	s_mov_b64 s[98:99], 0x80040
	v_lshl_add_u64 v[160:161], v[164:165], 0, s[98:99]
	s_add_i32 m0, s72, 0x1400
	s_nop 0
	global_load_lds_dwordx4 v[160:161], off
	s_mov_b64 s[98:99], 0x80200
	v_lshl_add_u64 v[160:161], v[164:165], 0, s[98:99]
	s_add_i32 m0, s72, 0x1800
	s_nop 0
	global_load_lds_dwordx4 v[160:161], off
	s_mov_b64 s[98:99], 0x80240
	v_lshl_add_u64 v[160:161], v[164:165], 0, s[98:99]
	s_add_i32 m0, s72, 0x1c00
	s_nop 0
	global_load_lds_dwordx4 v[160:161], off
	v_or_b32_e32 v208, 32, v237
	v_add_u32_e32 v174, s17, v208
	v_ashrrev_i32_e32 v175, 31, v174
	v_lshlrev_b64 v[148:149], 12, v[174:175]
	v_lshl_add_u64 v[148:149], s[30:31], 0, v[148:149]
	v_lshl_add_u64 v[172:173], v[34:35], 2, v[148:149]
	s_waitcnt lgkmcnt(0)
	s_add_i32 s98, s72, 0x2000
	s_waitcnt vmcnt(11)
	v_and_b32_e32 v148, 63, v228
	v_lshl_add_u32 v148, v148, 4, s98
	ds_read_b128 v[148:151], v148
	s_waitcnt vmcnt(10)
	v_and_b32_e32 v160, 63, v228
	v_lshl_add_u32 v160, v160, 4, s98
	ds_read_b128 v[160:163], v160 offset:1024
	v_pk_mul_f32 v[152:153], v[98:99], v[98:99]
	v_pk_mul_f32 v[154:155], v[96:97], v[96:97]
	v_pk_mul_f32 v[190:191], v[94:95], v[142:143]
	v_pk_mov_b32 v[156:157], v[154:155], v[152:153] op_sel:[1,0]
	v_mov_b32_e32 v155, v153
	v_pk_add_f32 v[192:193], v[156:157], v[154:155]
	v_pk_mul_f32 v[178:179], v[96:97], v[144:145]
	v_pk_add_f32 v[192:193], v[192:193], v[192:193] op_sel:[0,1] op_sel_hi:[1,0]
	v_pk_mul_f32 v[206:207], v[92:93], v[140:141]
	v_pk_mul_f32 v[176:177], v[98:99], v[146:147]
	v_mul_f32_e32 v209, v206, v206
	v_mul_f32_e32 v33, v207, v207
	v_pk_mul_f32 v[184:185], v[88:89], v[136:137]
	v_pk_mul_f32 v[182:183], v[90:91], v[138:139]
	v_pk_mul_f32 v[188:189], v[84:85], v[132:133]
	v_pk_mul_f32 v[186:187], v[86:87], v[134:135]
	s_waitcnt lgkmcnt(1)
	v_pk_mul_f32 v[152:153], v[150:151], v[150:151]
	v_pk_mul_f32 v[154:155], v[148:149], v[148:149]
	s_nop 0
	v_pk_mov_b32 v[156:157], v[154:155], v[152:153] op_sel:[1,0]
	v_mov_b32_e32 v155, v153
	v_pk_add_f32 v[152:153], v[156:157], v[154:155]
	v_pk_mul_f32 v[154:155], v[92:93], v[92:93]
	v_pk_add_f32 v[210:211], v[152:153], v[152:153] op_sel_hi:[0,1]
	v_pk_mul_f32 v[152:153], v[94:95], v[94:95]
	v_mul_f32_e32 v210, v84, v84
	v_pk_mov_b32 v[156:157], v[154:155], v[152:153] op_sel:[1,0]
	v_mov_b32_e32 v155, v153
	v_pk_add_f32 v[204:205], v[156:157], v[154:155]
	s_waitcnt lgkmcnt(0)
	v_pk_mul_f32 v[152:153], v[162:163], v[162:163]
	v_pk_mul_f32 v[154:155], v[160:161], v[160:161]
	v_pk_add_f32 v[204:205], v[204:205], v[204:205] op_sel:[0,1] op_sel_hi:[1,0]
	v_pk_mov_b32 v[156:157], v[154:155], v[152:153] op_sel:[1,0]
	v_mov_b32_e32 v155, v153
	v_pk_add_f32 v[152:153], v[156:157], v[154:155]
	s_nop 0
	v_pk_add_f32 v[212:213], v[152:153], v[152:153] op_sel_hi:[0,1]
	v_mul_f32_e32 v152, v190, v190
	v_pk_fma_f32 v[180:181], v[190:191], v[190:191], v[152:153] op_sel_hi:[1,1,0]
	s_waitcnt vmcnt(9)
	v_and_b32_e32 v152, 63, v228
	v_lshl_add_u32 v152, v152, 4, s98
	ds_read_b128 v[152:155], v152 offset:2048
	v_mul_f32_e32 v212, v85, v85
	v_pk_add_f32 v[210:211], v[210:211], v[212:213]
	v_mul_f32_e32 v180, v89, v89
	s_waitcnt lgkmcnt(0)
	v_mul_f32_e32 v156, v152, v152
	v_pk_fma_f32 v[214:215], v[152:153], v[152:153], v[156:157] op_sel_hi:[1,1,0]
	v_mul_f32_e32 v156, v154, v154
	v_pk_fma_f32 v[216:217], v[154:155], v[154:155], v[156:157] op_sel_hi:[1,1,0]
	s_waitcnt vmcnt(8)
	v_and_b32_e32 v156, 63, v228
	v_lshl_add_u32 v156, v156, 4, s98
	ds_read_b128 v[156:159], v156 offset:3072
	v_mul_f32_e32 v214, v86, v86
	v_mul_f32_e32 v216, v87, v87
	v_pk_add_f32 v[212:213], v[214:215], v[216:217]
	s_waitcnt lgkmcnt(0)
;     __device__ __forceinline__ void fused(f32x4 (&acc)[2][2][4][2], const Unit& u, int wr, int wc, int fr, int fq, PG8_LAS unsigned char* lds, int wid, int lane) const {
;     ...
;             for (int m = 0; m < 4; ++m) { const int r = ai * HALF + wr * 64 + m * 16 + fr; const size_t off = (size_t)(u.pm * BM + r) * 1024 + col0;
;                 float s0 = 0.f, s1 = 0.f, s2 = 0.f, s3 = 0.f;
; #pragma unroll
;                 for (int bj = 0; bj < 2; ++bj)
; #pragma unroll
;                     for (int n = 0; n < 2; ++n) { const f32x4 bs = *(const f32x4*)(base + off + bj * HALF + n * 16), a = acc[ai][bj][m][n], ag = a * gv[bj][n];
;                         s0 += (a[0] * a[0] + a[1] * a[1]) + (a[2] * a[2] + a[3] * a[3]); s1 += (bs[0] * bs[0] + bs[1] * bs[1]) + (bs[2] * bs[2] + bs[3] * bs[3]);
;                         s2 += (bs[0] * ag[0] + bs[1] * ag[1]) + (bs[2] * ag[2] + bs[3] * ag[3]); s3 += (ag[0] * ag[0] + ag[1] * ag[1]) + (ag[2] * ag[2] + ag[3] * ag[3]); }
;                 s0 += __shfl_xor(s0, 16); s0 += __shfl_xor(s0, 32); s1 += __shfl_xor(s1, 16); s1 += __shfl_xor(s1, 32);
;                 s2 += __shfl_xor(s2, 16); s2 += __shfl_xor(s2, 32); s3 += __shfl_xor(s3, 16); s3 += __shfl_xor(s3, 32);
;                 if (fq == 0) P[r * 4 + wc] = (f32x4){s0, s1, s2, s3};
	v_mul_f32_e32 v218, v156, v156
	v_pk_add_f32 v[210:211], v[210:211], v[212:213]
	v_pk_fma_f32 v[212:213], v[88:89], v[88:89], v[180:181] op_sel_hi:[1,1,0]
	v_mul_f32_e32 v180, v91, v91
	v_mul_f32_e32 v219, v157, v157
	v_mul_f32_e32 v220, v158, v158
	v_mul_f32_e32 v221, v159, v159
	v_pk_fma_f32 v[214:215], v[90:91], v[90:91], v[180:181] op_sel_hi:[1,1,0]
	v_mov_b32_e32 v213, v218
	v_mov_b32_e32 v215, v219
	v_mov_b32_e32 v205, v220
	v_mov_b32_e32 v193, v221
	v_pk_add_f32 v[212:213], v[212:213], v[214:215]
	v_pk_add_f32 v[192:193], v[204:205], v[192:193]
	s_nop 0
	v_pk_add_f32 v[192:193], v[212:213], v[192:193]
	v_mov_b32_e32 v212, v160
	v_pk_add_f32 v[192:193], v[210:211], v[192:193]
	v_mov_b32_e32 v210, v206
	v_mov_b32_e32 v206, v207
	v_mov_b32_e32 v207, v179
	v_mov_b32_e32 v160, v161
	v_mov_b32_e32 v161, v179
	v_mov_b32_e32 v211, v178
	v_mov_b32_e32 v213, v178
	v_pk_mul_f32 v[160:161], v[206:207], v[160:161]
	v_mov_b32_e32 v206, v190
	v_pk_fma_f32 v[160:161], v[210:211], v[212:213], v[160:161]
	v_mov_b32_e32 v210, v162
	v_mov_b32_e32 v190, v191
	v_mov_b32_e32 v191, v177
	v_mov_b32_e32 v162, v163
	v_mov_b32_e32 v163, v177
	v_mov_b32_e32 v207, v176
	v_mov_b32_e32 v211, v176
	v_pk_mul_f32 v[162:163], v[190:191], v[162:163]
	ds_bpermute_b32 v204, v240, v192
	v_pk_fma_f32 v[162:163], v[206:207], v[210:211], v[162:163]
	ds_bpermute_b32 v205, v240, v193
	v_pk_add_f32 v[160:161], v[160:161], v[162:163]
	v_mul_f32_e32 v162, v179, v149
	v_pk_fma_f32 v[148:149], v[178:179], v[148:149], v[162:163] op_sel_hi:[1,1,0]
	v_mul_f32_e32 v162, v177, v151
	v_pk_fma_f32 v[150:151], v[176:177], v[150:151], v[162:163] op_sel_hi:[1,1,0]
	v_mov_b32_e32 v149, v209
	v_mov_b32_e32 v151, v33
	v_pk_add_f32 v[148:149], v[148:149], v[150:151]
	v_pk_mov_b32 v[150:151], v[152:153], v[184:185] op_sel:[1,0]
	v_mov_b32_e32 v153, v185
	v_pk_mul_f32 v[152:153], v[184:185], v[152:153]
	v_mov_b32_e32 v33, v181
	v_pk_fma_f32 v[150:151], v[184:185], v[150:151], v[152:153] op_sel:[1,0,0] op_sel_hi:[0,1,1]
	v_pk_mov_b32 v[152:153], v[154:155], v[182:183] op_sel:[1,0]
	v_mov_b32_e32 v155, v183
	v_pk_mul_f32 v[154:155], v[182:183], v[154:155]
	v_pk_add_f32 v[148:149], v[148:149], v[32:33]
	v_pk_fma_f32 v[152:153], v[182:183], v[152:153], v[154:155] op_sel:[1,0,0] op_sel_hi:[0,1,1]
	v_pk_add_f32 v[148:149], v[160:161], v[148:149]
	v_pk_add_f32 v[150:151], v[150:151], v[152:153]
	s_waitcnt lgkmcnt(0)
	v_pk_add_f32 v[192:193], v[192:193], v[204:205]
	v_pk_add_f32 v[148:149], v[148:149], v[150:151]
	v_pk_mov_b32 v[150:151], v[156:157], v[188:189] op_sel:[1,0]
	v_mov_b32_e32 v157, v189
	v_pk_mul_f32 v[152:153], v[188:189], v[156:157]
	ds_bpermute_b32 v204, v239, v192
	v_pk_fma_f32 v[150:151], v[188:189], v[150:151], v[152:153] op_sel:[1,0,0] op_sel_hi:[0,1,1]
	v_pk_mov_b32 v[152:153], v[158:159], v[186:187] op_sel:[1,0]
	v_mov_b32_e32 v159, v187
	v_pk_mul_f32 v[154:155], v[186:187], v[158:159]
	ds_bpermute_b32 v205, v239, v193
	v_pk_fma_f32 v[152:153], v[186:187], v[152:153], v[154:155] op_sel:[1,0,0] op_sel_hi:[0,1,1]
	v_pk_add_f32 v[150:151], v[150:151], v[152:153]
	s_nop 0
	v_pk_add_f32 v[148:149], v[148:149], v[150:151]
	ds_bpermute_b32 v150, v240, v148
	ds_bpermute_b32 v151, v240, v149
	s_waitcnt lgkmcnt(0)
	v_pk_add_f32 v[148:149], v[148:149], v[150:151]
	ds_bpermute_b32 v150, v239, v148
	ds_bpermute_b32 v151, v239, v149
	s_and_saveexec_b64 s[6:7], vcc
	s_cbranch_execz .LBB0_1094
	v_lshl_add_u32 v33, v208, 6, s29
	s_waitcnt lgkmcnt(0)
	v_pk_add_f32 v[150:151], v[148:149], v[150:151]
	v_pk_add_f32 v[148:149], v[192:193], v[204:205]
	ds_write_b128 v33, v[148:151]
.LBB0_1094:
	s_or_b64 exec, exec, s[6:7]
	s_mov_b64 s[98:99], 0x90000
	v_lshl_add_u64 v[160:161], v[164:165], 0, s[98:99]
	s_add_i32 m0, s72, 0x2000
	s_nop 0
	global_load_lds_dwordx4 v[160:161], off
	s_mov_b64 s[98:99], 0x90040
	v_lshl_add_u64 v[160:161], v[164:165], 0, s[98:99]
	s_add_i32 m0, s72, 0x2400
	s_nop 0
	global_load_lds_dwordx4 v[160:161], off
	s_mov_b64 s[98:99], 0x90200
	v_lshl_add_u64 v[160:161], v[164:165], 0, s[98:99]
	s_add_i32 m0, s72, 0x2800
	s_nop 0
	global_load_lds_dwordx4 v[160:161], off
	s_mov_b64 s[98:99], 0x90240
	v_lshl_add_u64 v[160:161], v[164:165], 0, s[98:99]
	s_add_i32 m0, s72, 0x2c00
	s_nop 0
	global_load_lds_dwordx4 v[160:161], off
	v_or_b32_e32 v212, 48, v237
	v_add_u32_e32 v178, s17, v212
	v_ashrrev_i32_e32 v179, 31, v178
	v_lshlrev_b64 v[148:149], 12, v[178:179]
	v_lshl_add_u64 v[148:149], s[30:31], 0, v[148:149]
	v_lshl_add_u64 v[176:177], v[34:35], 2, v[148:149]
	s_waitcnt lgkmcnt(0)
	s_add_i32 s98, s72, 0x0
	s_waitcnt vmcnt(11)
	v_and_b32_e32 v148, 63, v228
	v_lshl_add_u32 v148, v148, 4, s98
	ds_read_b128 v[148:151], v148
	s_waitcnt vmcnt(10)
	v_and_b32_e32 v160, 63, v228
	v_lshl_add_u32 v160, v160, 4, s98
	ds_read_b128 v[160:163], v160 offset:1024
	v_pk_mul_f32 v[152:153], v[82:83], v[82:83]
	v_pk_mul_f32 v[154:155], v[80:81], v[80:81]
	v_pk_mul_f32 v[204:205], v[78:79], v[142:143]
	v_pk_mov_b32 v[156:157], v[154:155], v[152:153] op_sel:[1,0]
	v_mov_b32_e32 v155, v153
	v_pk_add_f32 v[206:207], v[156:157], v[154:155]
	v_pk_mul_f32 v[182:183], v[80:81], v[144:145]
	v_pk_add_f32 v[206:207], v[206:207], v[206:207] op_sel:[0,1] op_sel_hi:[1,0]
	v_pk_mul_f32 v[210:211], v[76:77], v[140:141]
	v_pk_mul_f32 v[180:181], v[82:83], v[146:147]
	v_mul_f32_e32 v213, v210, v210
	v_mul_f32_e32 v33, v211, v211
	v_pk_mul_f32 v[188:189], v[72:73], v[136:137]
	v_pk_mul_f32 v[186:187], v[74:75], v[138:139]
	v_pk_mul_f32 v[192:193], v[68:69], v[132:133]
	v_pk_mul_f32 v[190:191], v[70:71], v[134:135]
	s_waitcnt lgkmcnt(1)
;     __device__ __forceinline__ void fused(f32x4 (&acc)[2][2][4][2], const Unit& u, int wr, int wc, int fr, int fq, PG8_LAS unsigned char* lds, int wid, int lane) const {
;     ...
;                     for (int n = 0; n < 2; ++n) { const f32x4 bs = *(const f32x4*)(base + off + bj * HALF + n * 16), a = acc[ai][bj][m][n], ag = a * gv[bj][n];
;                         s0 += (a[0] * a[0] + a[1] * a[1]) + (a[2] * a[2] + a[3] * a[3]); s1 += (bs[0] * bs[0] + bs[1] * bs[1]) + (bs[2] * bs[2] + bs[3] * bs[3]);
;                         s2 += (bs[0] * ag[0] + bs[1] * ag[1]) + (bs[2] * ag[2] + bs[3] * ag[3]); s3 += (ag[0] * ag[0] + ag[1] * ag[1]) + (ag[2] * ag[2] + ag[3] * ag[3]); }
;                 s0 += __shfl_xor(s0, 16); s0 += __shfl_xor(s0, 32); s1 += __shfl_xor(s1, 16); s1 += __shfl_xor(s1, 32);
;                 s2 += __shfl_xor(s2, 16); s2 += __shfl_xor(s2, 32); s3 += __shfl_xor(s3, 16); s3 += __shfl_xor(s3, 32);
;                 if (fq == 0) P[r * 4 + wc] = (f32x4){s0, s1, s2, s3};
	v_pk_mul_f32 v[152:153], v[150:151], v[150:151]
	v_pk_mul_f32 v[154:155], v[148:149], v[148:149]
	s_nop 0
	v_pk_mov_b32 v[156:157], v[154:155], v[152:153] op_sel:[1,0]
	v_mov_b32_e32 v155, v153
	v_pk_add_f32 v[152:153], v[156:157], v[154:155]
	v_pk_mul_f32 v[154:155], v[76:77], v[76:77]
	v_pk_add_f32 v[214:215], v[152:153], v[152:153] op_sel_hi:[0,1]
	v_pk_mul_f32 v[152:153], v[78:79], v[78:79]
	v_mul_f32_e32 v214, v68, v68
	v_pk_mov_b32 v[156:157], v[154:155], v[152:153] op_sel:[1,0]
	v_mov_b32_e32 v155, v153
	v_pk_add_f32 v[208:209], v[156:157], v[154:155]
	s_waitcnt lgkmcnt(0)
	v_pk_mul_f32 v[152:153], v[162:163], v[162:163]
	v_pk_mul_f32 v[154:155], v[160:161], v[160:161]
	v_pk_add_f32 v[208:209], v[208:209], v[208:209] op_sel:[0,1] op_sel_hi:[1,0]
	v_pk_mov_b32 v[156:157], v[154:155], v[152:153] op_sel:[1,0]
	v_mov_b32_e32 v155, v153
	v_pk_add_f32 v[152:153], v[156:157], v[154:155]
	s_nop 0
	v_pk_add_f32 v[216:217], v[152:153], v[152:153] op_sel_hi:[0,1]
	v_mul_f32_e32 v152, v204, v204
	v_pk_fma_f32 v[184:185], v[204:205], v[204:205], v[152:153] op_sel_hi:[1,1,0]
	s_waitcnt vmcnt(9)
	v_and_b32_e32 v152, 63, v228
	v_lshl_add_u32 v152, v152, 4, s98
	ds_read_b128 v[152:155], v152 offset:2048
	v_mul_f32_e32 v216, v69, v69
	v_pk_add_f32 v[214:215], v[214:215], v[216:217]
	v_mul_f32_e32 v184, v73, v73
	s_waitcnt lgkmcnt(0)
	v_mul_f32_e32 v156, v152, v152
	v_pk_fma_f32 v[218:219], v[152:153], v[152:153], v[156:157] op_sel_hi:[1,1,0]
	v_mul_f32_e32 v156, v154, v154
	v_pk_fma_f32 v[220:221], v[154:155], v[154:155], v[156:157] op_sel_hi:[1,1,0]
	s_waitcnt vmcnt(8)
	v_and_b32_e32 v156, 63, v228
	v_lshl_add_u32 v156, v156, 4, s98
	ds_read_b128 v[156:159], v156 offset:3072
	v_mul_f32_e32 v218, v70, v70
	v_mul_f32_e32 v220, v71, v71
	v_pk_add_f32 v[216:217], v[218:219], v[220:221]
	s_waitcnt lgkmcnt(0)
	v_mul_f32_e32 v222, v156, v156
	v_pk_add_f32 v[214:215], v[214:215], v[216:217]
	v_pk_fma_f32 v[216:217], v[72:73], v[72:73], v[184:185] op_sel_hi:[1,1,0]
	v_mul_f32_e32 v184, v75, v75
	v_mul_f32_e32 v223, v157, v157
	v_mul_f32_e32 v224, v158, v158
	v_mul_f32_e32 v225, v159, v159
	v_pk_fma_f32 v[218:219], v[74:75], v[74:75], v[184:185] op_sel_hi:[1,1,0]
	v_mov_b32_e32 v217, v222
	v_mov_b32_e32 v219, v223
	v_mov_b32_e32 v209, v224
	v_mov_b32_e32 v207, v225
	v_pk_add_f32 v[216:217], v[216:217], v[218:219]
	v_pk_add_f32 v[206:207], v[208:209], v[206:207]
	s_nop 0
	v_pk_add_f32 v[206:207], v[216:217], v[206:207]
	v_mov_b32_e32 v216, v160
	v_pk_add_f32 v[206:207], v[214:215], v[206:207]
	v_mov_b32_e32 v214, v210
	v_mov_b32_e32 v210, v211
	v_mov_b32_e32 v211, v183
	v_mov_b32_e32 v160, v161
	v_mov_b32_e32 v161, v183
	v_mov_b32_e32 v215, v182
	v_mov_b32_e32 v217, v182
	v_pk_mul_f32 v[160:161], v[210:211], v[160:161]
	v_mov_b32_e32 v210, v204
	v_pk_fma_f32 v[160:161], v[214:215], v[216:217], v[160:161]
	v_mov_b32_e32 v214, v162
	v_mov_b32_e32 v204, v205
	v_mov_b32_e32 v205, v181
	v_mov_b32_e32 v162, v163
	v_mov_b32_e32 v163, v181
	v_mov_b32_e32 v211, v180
	v_mov_b32_e32 v215, v180
	v_pk_mul_f32 v[162:163], v[204:205], v[162:163]
	ds_bpermute_b32 v208, v240, v206
	v_pk_fma_f32 v[162:163], v[210:211], v[214:215], v[162:163]
	ds_bpermute_b32 v209, v240, v207
	v_pk_add_f32 v[160:161], v[160:161], v[162:163]
	v_mul_f32_e32 v162, v183, v149
	v_pk_fma_f32 v[148:149], v[182:183], v[148:149], v[162:163] op_sel_hi:[1,1,0]
	v_mul_f32_e32 v162, v181, v151
	v_pk_fma_f32 v[150:151], v[180:181], v[150:151], v[162:163] op_sel_hi:[1,1,0]
	v_mov_b32_e32 v149, v213
	v_mov_b32_e32 v151, v33
	v_pk_add_f32 v[148:149], v[148:149], v[150:151]
	v_pk_mov_b32 v[150:151], v[152:153], v[188:189] op_sel:[1,0]
	v_mov_b32_e32 v153, v189
	v_pk_mul_f32 v[152:153], v[188:189], v[152:153]
	v_mov_b32_e32 v33, v185
	v_pk_fma_f32 v[150:151], v[188:189], v[150:151], v[152:153] op_sel:[1,0,0] op_sel_hi:[0,1,1]
	v_pk_mov_b32 v[152:153], v[154:155], v[186:187] op_sel:[1,0]
	v_mov_b32_e32 v155, v187
	v_pk_mul_f32 v[154:155], v[186:187], v[154:155]
	v_pk_add_f32 v[148:149], v[148:149], v[32:33]
	v_pk_fma_f32 v[152:153], v[186:187], v[152:153], v[154:155] op_sel:[1,0,0] op_sel_hi:[0,1,1]
	v_pk_add_f32 v[148:149], v[160:161], v[148:149]
	v_pk_add_f32 v[150:151], v[150:151], v[152:153]
	s_waitcnt lgkmcnt(0)
	v_pk_add_f32 v[206:207], v[206:207], v[208:209]
	v_pk_add_f32 v[148:149], v[148:149], v[150:151]
	v_pk_mov_b32 v[150:151], v[156:157], v[192:193] op_sel:[1,0]
	v_mov_b32_e32 v157, v193
	v_pk_mul_f32 v[152:153], v[192:193], v[156:157]
	ds_bpermute_b32 v208, v239, v206
	v_pk_fma_f32 v[150:151], v[192:193], v[150:151], v[152:153] op_sel:[1,0,0] op_sel_hi:[0,1,1]
	v_pk_mov_b32 v[152:153], v[158:159], v[190:191] op_sel:[1,0]
	v_mov_b32_e32 v159, v191
	v_pk_mul_f32 v[154:155], v[190:191], v[158:159]
	ds_bpermute_b32 v209, v239, v207
	v_pk_fma_f32 v[152:153], v[190:191], v[152:153], v[154:155] op_sel:[1,0,0] op_sel_hi:[0,1,1]
	v_pk_add_f32 v[150:151], v[150:151], v[152:153]
	s_nop 0
	v_pk_add_f32 v[148:149], v[148:149], v[150:151]
	ds_bpermute_b32 v150, v240, v148
	ds_bpermute_b32 v151, v240, v149
	s_waitcnt lgkmcnt(0)
	v_pk_add_f32 v[148:149], v[148:149], v[150:151]
	ds_bpermute_b32 v150, v239, v148
	ds_bpermute_b32 v151, v239, v149
	s_and_saveexec_b64 s[6:7], vcc
	s_cbranch_execz .LBB0_1096
	v_lshl_add_u32 v33, v212, 6, s29
	s_waitcnt lgkmcnt(0)
	v_pk_add_f32 v[150:151], v[148:149], v[150:151]
	v_pk_add_f32 v[148:149], v[206:207], v[208:209]
	ds_write_b128 v33, v[148:151]
;     __device__ __forceinline__ void fused(f32x4 (&acc)[2][2][4][2], const Unit& u, int wr, int wc, int fr, int fq, PG8_LAS unsigned char* lds, int wid, int lane) const {
;     ...
;             for (int m = 0; m < 4; ++m) { const int r = ai * HALF + wr * 64 + m * 16 + fr; const size_t off = (size_t)(u.pm * BM + r) * 1024 + col0;
;                 float s0 = 0.f, s1 = 0.f, s2 = 0.f, s3 = 0.f;
; #pragma unroll
;                 for (int bj = 0; bj < 2; ++bj)
; #pragma unroll
;                     for (int n = 0; n < 2; ++n) { const f32x4 bs = *(const f32x4*)(base + off + bj * HALF + n * 16), a = acc[ai][bj][m][n], ag = a * gv[bj][n];
;                         s0 += (a[0] * a[0] + a[1] * a[1]) + (a[2] * a[2] + a[3] * a[3]); s1 += (bs[0] * bs[0] + bs[1] * bs[1]) + (bs[2] * bs[2] + bs[3] * bs[3]);
;                         s2 += (bs[0] * ag[0] + bs[1] * ag[1]) + (bs[2] * ag[2] + bs[3] * ag[3]); s3 += (ag[0] * ag[0] + ag[1] * ag[1]) + (ag[2] * ag[2] + ag[3] * ag[3]); }
;                 s0 += __shfl_xor(s0, 16); s0 += __shfl_xor(s0, 32); s1 += __shfl_xor(s1, 16); s1 += __shfl_xor(s1, 32);
;                 s2 += __shfl_xor(s2, 16); s2 += __shfl_xor(s2, 32); s3 += __shfl_xor(s3, 16); s3 += __shfl_xor(s3, 32);
;                 if (fq == 0) P[r * 4 + wc] = (f32x4){s0, s1, s2, s3};
.LBB0_1096:
	s_or_b64 exec, exec, s[6:7]
	s_mov_b64 s[98:99], 0xa0000
	v_lshl_add_u64 v[160:161], v[164:165], 0, s[98:99]
	s_add_i32 m0, s72, 0x0
	s_nop 0
	global_load_lds_dwordx4 v[160:161], off
	s_mov_b64 s[98:99], 0xa0040
	v_lshl_add_u64 v[160:161], v[164:165], 0, s[98:99]
	s_add_i32 m0, s72, 0x400
	s_nop 0
	global_load_lds_dwordx4 v[160:161], off
	s_mov_b64 s[98:99], 0xa0200
	v_lshl_add_u64 v[160:161], v[164:165], 0, s[98:99]
	s_add_i32 m0, s72, 0x800
	s_nop 0
	global_load_lds_dwordx4 v[160:161], off
	s_mov_b64 s[98:99], 0xa0240
	v_lshl_add_u64 v[160:161], v[164:165], 0, s[98:99]
	s_add_i32 m0, s72, 0xc00
	s_nop 0
	global_load_lds_dwordx4 v[160:161], off
	v_add_u32_e32 v216, 0x80, v237
	v_add_u32_e32 v182, s17, v216
	v_ashrrev_i32_e32 v183, 31, v182
	v_lshlrev_b64 v[148:149], 12, v[182:183]
	v_lshl_add_u64 v[148:149], s[30:31], 0, v[148:149]
	v_lshl_add_u64 v[180:181], v[34:35], 2, v[148:149]
	s_waitcnt lgkmcnt(0)
	s_add_i32 s98, s72, 0x1000
	s_waitcnt vmcnt(11)
	v_and_b32_e32 v148, 63, v228
	v_lshl_add_u32 v148, v148, 4, s98
	ds_read_b128 v[148:151], v148
	s_waitcnt vmcnt(10)
	v_and_b32_e32 v160, 63, v228
	v_lshl_add_u32 v160, v160, 4, s98
	ds_read_b128 v[160:163], v160 offset:1024
	v_pk_mul_f32 v[152:153], v[66:67], v[66:67]
	v_pk_mul_f32 v[154:155], v[64:65], v[64:65]
	v_pk_mul_f32 v[208:209], v[62:63], v[142:143]
	v_pk_mov_b32 v[156:157], v[154:155], v[152:153] op_sel:[1,0]
	v_mov_b32_e32 v155, v153
	v_pk_add_f32 v[210:211], v[156:157], v[154:155]
	v_pk_mul_f32 v[186:187], v[64:65], v[144:145]
	v_pk_add_f32 v[210:211], v[210:211], v[210:211] op_sel:[0,1] op_sel_hi:[1,0]
	v_pk_mul_f32 v[214:215], v[60:61], v[140:141]
	v_pk_mul_f32 v[184:185], v[66:67], v[146:147]
	v_mul_f32_e32 v217, v214, v214
	v_mul_f32_e32 v33, v215, v215
	v_pk_mul_f32 v[192:193], v[56:57], v[136:137]
	v_pk_mul_f32 v[190:191], v[58:59], v[138:139]
	v_pk_mul_f32 v[206:207], v[52:53], v[132:133]
	v_pk_mul_f32 v[204:205], v[54:55], v[134:135]
	s_waitcnt lgkmcnt(1)
	v_pk_mul_f32 v[152:153], v[150:151], v[150:151]
	v_pk_mul_f32 v[154:155], v[148:149], v[148:149]
	s_nop 0
	v_pk_mov_b32 v[156:157], v[154:155], v[152:153] op_sel:[1,0]
	v_mov_b32_e32 v155, v153
	v_pk_add_f32 v[152:153], v[156:157], v[154:155]
	v_pk_mul_f32 v[154:155], v[60:61], v[60:61]
	v_pk_add_f32 v[218:219], v[152:153], v[152:153] op_sel_hi:[0,1]
	v_pk_mul_f32 v[152:153], v[62:63], v[62:63]
	v_mul_f32_e32 v218, v52, v52
	v_pk_mov_b32 v[156:157], v[154:155], v[152:153] op_sel:[1,0]
	v_mov_b32_e32 v155, v153
	v_pk_add_f32 v[212:213], v[156:157], v[154:155]
	s_waitcnt lgkmcnt(0)
	v_pk_mul_f32 v[152:153], v[162:163], v[162:163]
	v_pk_mul_f32 v[154:155], v[160:161], v[160:161]
	v_pk_add_f32 v[212:213], v[212:213], v[212:213] op_sel:[0,1] op_sel_hi:[1,0]
	v_pk_mov_b32 v[156:157], v[154:155], v[152:153] op_sel:[1,0]
	v_mov_b32_e32 v155, v153
	v_pk_add_f32 v[152:153], v[156:157], v[154:155]
	s_nop 0
	v_pk_add_f32 v[220:221], v[152:153], v[152:153] op_sel_hi:[0,1]
	v_mul_f32_e32 v152, v208, v208
	v_pk_fma_f32 v[188:189], v[208:209], v[208:209], v[152:153] op_sel_hi:[1,1,0]
	s_waitcnt vmcnt(9)
	v_and_b32_e32 v152, 63, v228
	v_lshl_add_u32 v152, v152, 4, s98
	ds_read_b128 v[152:155], v152 offset:2048
	v_mul_f32_e32 v220, v53, v53
	v_pk_add_f32 v[218:219], v[218:219], v[220:221]
	v_mul_f32_e32 v188, v57, v57
	s_waitcnt lgkmcnt(0)
	v_mul_f32_e32 v156, v152, v152
	v_pk_fma_f32 v[222:223], v[152:153], v[152:153], v[156:157] op_sel_hi:[1,1,0]
	v_mul_f32_e32 v156, v154, v154
	v_pk_fma_f32 v[224:225], v[154:155], v[154:155], v[156:157] op_sel_hi:[1,1,0]
	s_waitcnt vmcnt(8)
	v_and_b32_e32 v156, 63, v228
	v_lshl_add_u32 v156, v156, 4, s98
	ds_read_b128 v[156:159], v156 offset:3072
	v_mul_f32_e32 v222, v54, v54
	v_mul_f32_e32 v224, v55, v55
	v_pk_add_f32 v[220:221], v[222:223], v[224:225]
	s_waitcnt lgkmcnt(0)
	v_mul_f32_e32 v226, v156, v156
	v_pk_add_f32 v[218:219], v[218:219], v[220:221]
	v_pk_fma_f32 v[220:221], v[56:57], v[56:57], v[188:189] op_sel_hi:[1,1,0]
	v_mul_f32_e32 v188, v59, v59
	v_mul_f32_e32 v227, v157, v157
	v_mul_f32_e32 v230, v158, v158
	v_mul_f32_e32 v241, v159, v159
	v_pk_fma_f32 v[222:223], v[58:59], v[58:59], v[188:189] op_sel_hi:[1,1,0]
	v_mov_b32_e32 v221, v226
	v_mov_b32_e32 v223, v227
	v_mov_b32_e32 v213, v230
	v_mov_b32_e32 v211, v241
	v_pk_add_f32 v[220:221], v[220:221], v[222:223]
	v_pk_add_f32 v[210:211], v[212:213], v[210:211]
	s_nop 0
	v_pk_add_f32 v[210:211], v[220:221], v[210:211]
	v_mov_b32_e32 v220, v160
	v_pk_add_f32 v[210:211], v[218:219], v[210:211]
	v_mov_b32_e32 v218, v214
	v_mov_b32_e32 v214, v215
	v_mov_b32_e32 v215, v187
	v_mov_b32_e32 v160, v161
	v_mov_b32_e32 v161, v187
	v_mov_b32_e32 v219, v186
	v_mov_b32_e32 v221, v186
	v_pk_mul_f32 v[160:161], v[214:215], v[160:161]
	v_mov_b32_e32 v214, v208
	v_pk_fma_f32 v[160:161], v[218:219], v[220:221], v[160:161]
	v_mov_b32_e32 v218, v162
	v_mov_b32_e32 v208, v209
	v_mov_b32_e32 v209, v185
	v_mov_b32_e32 v162, v163
	v_mov_b32_e32 v163, v185
	v_mov_b32_e32 v215, v184
	v_mov_b32_e32 v219, v184
	v_pk_mul_f32 v[162:163], v[208:209], v[162:163]
	ds_bpermute_b32 v212, v240, v210
	v_pk_fma_f32 v[162:163], v[214:215], v[218:219], v[162:163]
	ds_bpermute_b32 v213, v240, v211
	v_pk_add_f32 v[160:161], v[160:161], v[162:163]
	v_mul_f32_e32 v162, v187, v149
	v_pk_fma_f32 v[148:149], v[186:187], v[148:149], v[162:163] op_sel_hi:[1,1,0]
	v_mul_f32_e32 v162, v185, v151
	v_pk_fma_f32 v[150:151], v[184:185], v[150:151], v[162:163] op_sel_hi:[1,1,0]
	v_mov_b32_e32 v149, v217
	v_mov_b32_e32 v151, v33
	v_pk_add_f32 v[148:149], v[148:149], v[150:151]
	v_pk_mov_b32 v[150:151], v[152:153], v[192:193] op_sel:[1,0]
	v_mov_b32_e32 v153, v193
	v_pk_mul_f32 v[152:153], v[192:193], v[152:153]
	v_mov_b32_e32 v33, v189
	v_pk_fma_f32 v[150:151], v[192:193], v[150:151], v[152:153] op_sel:[1,0,0] op_sel_hi:[0,1,1]
	v_pk_mov_b32 v[152:153], v[154:155], v[190:191] op_sel:[1,0]
	v_mov_b32_e32 v155, v191
	v_pk_mul_f32 v[154:155], v[190:191], v[154:155]
	v_pk_add_f32 v[148:149], v[148:149], v[32:33]
	v_pk_fma_f32 v[152:153], v[190:191], v[152:153], v[154:155] op_sel:[1,0,0] op_sel_hi:[0,1,1]
	v_pk_add_f32 v[148:149], v[160:161], v[148:149]
	v_pk_add_f32 v[150:151], v[150:151], v[152:153]
	s_waitcnt lgkmcnt(0)
;     __device__ __forceinline__ void fused(f32x4 (&acc)[2][2][4][2], const Unit& u, int wr, int wc, int fr, int fq, PG8_LAS unsigned char* lds, int wid, int lane) const {
;     ...
;             for (int m = 0; m < 4; ++m) { const int r = ai * HALF + wr * 64 + m * 16 + fr; const size_t off = (size_t)(u.pm * BM + r) * 1024 + col0;
;                 float s0 = 0.f, s1 = 0.f, s2 = 0.f, s3 = 0.f;
; #pragma unroll
;                 for (int bj = 0; bj < 2; ++bj)
; #pragma unroll
;                     for (int n = 0; n < 2; ++n) { const f32x4 bs = *(const f32x4*)(base + off + bj * HALF + n * 16), a = acc[ai][bj][m][n], ag = a * gv[bj][n];
;                         s0 += (a[0] * a[0] + a[1] * a[1]) + (a[2] * a[2] + a[3] * a[3]); s1 += (bs[0] * bs[0] + bs[1] * bs[1]) + (bs[2] * bs[2] + bs[3] * bs[3]);
;                         s2 += (bs[0] * ag[0] + bs[1] * ag[1]) + (bs[2] * ag[2] + bs[3] * ag[3]); s3 += (ag[0] * ag[0] + ag[1] * ag[1]) + (ag[2] * ag[2] + ag[3] * ag[3]); }
;                 s0 += __shfl_xor(s0, 16); s0 += __shfl_xor(s0, 32); s1 += __shfl_xor(s1, 16); s1 += __shfl_xor(s1, 32);
;                 s2 += __shfl_xor(s2, 16); s2 += __shfl_xor(s2, 32); s3 += __shfl_xor(s3, 16); s3 += __shfl_xor(s3, 32);
;                 if (fq == 0) P[r * 4 + wc] = (f32x4){s0, s1, s2, s3};
	v_pk_add_f32 v[210:211], v[210:211], v[212:213]
	v_pk_add_f32 v[148:149], v[148:149], v[150:151]
	v_pk_mov_b32 v[150:151], v[156:157], v[206:207] op_sel:[1,0]
	v_mov_b32_e32 v157, v207
	v_pk_mul_f32 v[152:153], v[206:207], v[156:157]
	ds_bpermute_b32 v212, v239, v210
	v_pk_fma_f32 v[150:151], v[206:207], v[150:151], v[152:153] op_sel:[1,0,0] op_sel_hi:[0,1,1]
	v_pk_mov_b32 v[152:153], v[158:159], v[204:205] op_sel:[1,0]
	v_mov_b32_e32 v159, v205
	v_pk_mul_f32 v[154:155], v[204:205], v[158:159]
	ds_bpermute_b32 v213, v239, v211
	v_pk_fma_f32 v[152:153], v[204:205], v[152:153], v[154:155] op_sel:[1,0,0] op_sel_hi:[0,1,1]
	v_pk_add_f32 v[150:151], v[150:151], v[152:153]
	s_nop 0
	v_pk_add_f32 v[148:149], v[148:149], v[150:151]
	ds_bpermute_b32 v150, v240, v148
	ds_bpermute_b32 v151, v240, v149
	s_waitcnt lgkmcnt(0)
	v_pk_add_f32 v[148:149], v[148:149], v[150:151]
	ds_bpermute_b32 v150, v239, v148
	ds_bpermute_b32 v151, v239, v149
	s_and_saveexec_b64 s[6:7], vcc
	s_cbranch_execz .LBB0_1098
	v_lshl_add_u32 v33, v216, 6, s29
	s_waitcnt lgkmcnt(0)
	v_pk_add_f32 v[150:151], v[148:149], v[150:151]
	v_pk_add_f32 v[148:149], v[210:211], v[212:213]
	ds_write_b128 v33, v[148:151]
.LBB0_1098:
	s_or_b64 exec, exec, s[6:7]
	s_mov_b64 s[98:99], 0xb0000
	v_lshl_add_u64 v[160:161], v[164:165], 0, s[98:99]
	s_add_i32 m0, s72, 0x1000
	s_nop 0
	global_load_lds_dwordx4 v[160:161], off
	s_mov_b64 s[98:99], 0xb0040
	v_lshl_add_u64 v[160:161], v[164:165], 0, s[98:99]
	s_add_i32 m0, s72, 0x1400
	s_nop 0
	global_load_lds_dwordx4 v[160:161], off
	s_mov_b64 s[98:99], 0xb0200
	v_lshl_add_u64 v[160:161], v[164:165], 0, s[98:99]
	s_add_i32 m0, s72, 0x1800
	s_nop 0
	global_load_lds_dwordx4 v[160:161], off
	s_mov_b64 s[98:99], 0xb0240
	v_lshl_add_u64 v[160:161], v[164:165], 0, s[98:99]
	s_add_i32 m0, s72, 0x1c00
	s_nop 0
	global_load_lds_dwordx4 v[160:161], off
	v_add_u32_e32 v220, 0x90, v237
	v_add_u32_e32 v186, s17, v220
	v_ashrrev_i32_e32 v187, 31, v186
	v_lshlrev_b64 v[148:149], 12, v[186:187]
	v_lshl_add_u64 v[148:149], s[30:31], 0, v[148:149]
	v_lshl_add_u64 v[184:185], v[34:35], 2, v[148:149]
	s_waitcnt lgkmcnt(0)
	s_add_i32 s98, s72, 0x2000
	s_waitcnt vmcnt(11)
	v_and_b32_e32 v148, 63, v228
	v_lshl_add_u32 v148, v148, 4, s98
	ds_read_b128 v[148:151], v148
	s_waitcnt vmcnt(10)
	v_and_b32_e32 v160, 63, v228
	v_lshl_add_u32 v160, v160, 4, s98
	ds_read_b128 v[160:163], v160 offset:1024
	v_pk_mul_f32 v[152:153], v[50:51], v[50:51]
	v_pk_mul_f32 v[154:155], v[48:49], v[48:49]
	v_pk_mul_f32 v[212:213], v[46:47], v[142:143]
	v_pk_mov_b32 v[156:157], v[154:155], v[152:153] op_sel:[1,0]
	v_mov_b32_e32 v155, v153
	v_pk_add_f32 v[214:215], v[156:157], v[154:155]
	v_pk_mul_f32 v[190:191], v[48:49], v[144:145]
	v_pk_add_f32 v[214:215], v[214:215], v[214:215] op_sel:[0,1] op_sel_hi:[1,0]
	v_pk_mul_f32 v[218:219], v[44:45], v[140:141]
	v_pk_mul_f32 v[188:189], v[50:51], v[146:147]
	v_mul_f32_e32 v221, v218, v218
	v_mul_f32_e32 v33, v219, v219
	v_pk_mul_f32 v[206:207], v[40:41], v[136:137]
	v_pk_mul_f32 v[204:205], v[42:43], v[138:139]
	v_pk_mul_f32 v[210:211], v[36:37], v[132:133]
	v_pk_mul_f32 v[208:209], v[38:39], v[134:135]
	s_waitcnt lgkmcnt(1)
	v_pk_mul_f32 v[152:153], v[150:151], v[150:151]
	v_pk_mul_f32 v[154:155], v[148:149], v[148:149]
	s_nop 0
	v_pk_mov_b32 v[156:157], v[154:155], v[152:153] op_sel:[1,0]
	v_mov_b32_e32 v155, v153
	v_pk_add_f32 v[152:153], v[156:157], v[154:155]
	v_pk_mul_f32 v[154:155], v[44:45], v[44:45]
	v_pk_add_f32 v[222:223], v[152:153], v[152:153] op_sel_hi:[0,1]
	v_pk_mul_f32 v[152:153], v[46:47], v[46:47]
	v_mul_f32_e32 v222, v36, v36
	v_pk_mov_b32 v[156:157], v[154:155], v[152:153] op_sel:[1,0]
	v_mov_b32_e32 v155, v153
	v_pk_add_f32 v[216:217], v[156:157], v[154:155]
	s_waitcnt lgkmcnt(0)
	v_pk_mul_f32 v[152:153], v[162:163], v[162:163]
	v_pk_mul_f32 v[154:155], v[160:161], v[160:161]
	v_pk_add_f32 v[216:217], v[216:217], v[216:217] op_sel:[0,1] op_sel_hi:[1,0]
	v_pk_mov_b32 v[156:157], v[154:155], v[152:153] op_sel:[1,0]
	v_mov_b32_e32 v155, v153
	v_pk_add_f32 v[152:153], v[156:157], v[154:155]
	s_nop 0
	v_pk_add_f32 v[224:225], v[152:153], v[152:153] op_sel_hi:[0,1]
	v_mul_f32_e32 v152, v212, v212
	v_pk_fma_f32 v[192:193], v[212:213], v[212:213], v[152:153] op_sel_hi:[1,1,0]
	s_waitcnt vmcnt(9)
	v_and_b32_e32 v152, 63, v228
	v_lshl_add_u32 v152, v152, 4, s98
	ds_read_b128 v[152:155], v152 offset:2048
	v_mul_f32_e32 v224, v37, v37
	v_pk_add_f32 v[222:223], v[222:223], v[224:225]
	v_mul_f32_e32 v192, v41, v41
	s_waitcnt lgkmcnt(0)
	v_mul_f32_e32 v156, v152, v152
	v_pk_fma_f32 v[226:227], v[152:153], v[152:153], v[156:157] op_sel_hi:[1,1,0]
	v_mul_f32_e32 v156, v154, v154
	v_pk_fma_f32 v[242:243], v[154:155], v[154:155], v[156:157] op_sel_hi:[1,1,0]
	s_waitcnt vmcnt(8)
	v_and_b32_e32 v156, 63, v228
	v_lshl_add_u32 v156, v156, 4, s98
	ds_read_b128 v[156:159], v156 offset:3072
	v_mul_f32_e32 v226, v38, v38
	v_mul_f32_e32 v242, v39, v39
	v_pk_add_f32 v[224:225], v[226:227], v[242:243]
	s_waitcnt lgkmcnt(0)
;     __device__ __forceinline__ void fused(f32x4 (&acc)[2][2][4][2], const Unit& u, int wr, int wc, int fr, int fq, PG8_LAS unsigned char* lds, int wid, int lane) const {
;     ...
;             for (int m = 0; m < 4; ++m) { const int r = ai * HALF + wr * 64 + m * 16 + fr; const size_t off = (size_t)(u.pm * BM + r) * 1024 + col0;
;                 float s0 = 0.f, s1 = 0.f, s2 = 0.f, s3 = 0.f;
; #pragma unroll
;                 for (int bj = 0; bj < 2; ++bj)
; #pragma unroll
;                     for (int n = 0; n < 2; ++n) { const f32x4 bs = *(const f32x4*)(base + off + bj * HALF + n * 16), a = acc[ai][bj][m][n], ag = a * gv[bj][n];
;                         s0 += (a[0] * a[0] + a[1] * a[1]) + (a[2] * a[2] + a[3] * a[3]); s1 += (bs[0] * bs[0] + bs[1] * bs[1]) + (bs[2] * bs[2] + bs[3] * bs[3]);
;                         s2 += (bs[0] * ag[0] + bs[1] * ag[1]) + (bs[2] * ag[2] + bs[3] * ag[3]); s3 += (ag[0] * ag[0] + ag[1] * ag[1]) + (ag[2] * ag[2] + ag[3] * ag[3]); }
;                 s0 += __shfl_xor(s0, 16); s0 += __shfl_xor(s0, 32); s1 += __shfl_xor(s1, 16); s1 += __shfl_xor(s1, 32);
;                 s2 += __shfl_xor(s2, 16); s2 += __shfl_xor(s2, 32); s3 += __shfl_xor(s3, 16); s3 += __shfl_xor(s3, 32);
;                 if (fq == 0) P[r * 4 + wc] = (f32x4){s0, s1, s2, s3};
	v_mul_f32_e32 v230, v156, v156
	v_pk_add_f32 v[222:223], v[222:223], v[224:225]
	v_pk_fma_f32 v[224:225], v[40:41], v[40:41], v[192:193] op_sel_hi:[1,1,0]
	v_mul_f32_e32 v192, v43, v43
	v_mul_f32_e32 v241, v157, v157
	v_mul_f32_e32 v244, v158, v158
	v_mul_f32_e32 v245, v159, v159
	v_pk_fma_f32 v[226:227], v[42:43], v[42:43], v[192:193] op_sel_hi:[1,1,0]
	v_mov_b32_e32 v225, v230
	v_mov_b32_e32 v227, v241
	v_mov_b32_e32 v217, v244
	v_mov_b32_e32 v215, v245
	v_pk_add_f32 v[224:225], v[224:225], v[226:227]
	v_pk_add_f32 v[214:215], v[216:217], v[214:215]
	s_nop 0
	v_pk_add_f32 v[214:215], v[224:225], v[214:215]
	v_mov_b32_e32 v224, v160
	v_pk_add_f32 v[214:215], v[222:223], v[214:215]
	v_mov_b32_e32 v222, v218
	v_mov_b32_e32 v218, v219
	v_mov_b32_e32 v219, v191
	v_mov_b32_e32 v160, v161
	v_mov_b32_e32 v161, v191
	v_mov_b32_e32 v223, v190
	v_mov_b32_e32 v225, v190
	v_pk_mul_f32 v[160:161], v[218:219], v[160:161]
	v_mov_b32_e32 v218, v212
	v_pk_fma_f32 v[160:161], v[222:223], v[224:225], v[160:161]
	v_mov_b32_e32 v222, v162
	v_mov_b32_e32 v212, v213
	v_mov_b32_e32 v213, v189
	v_mov_b32_e32 v162, v163
	v_mov_b32_e32 v163, v189
	v_mov_b32_e32 v219, v188
	v_mov_b32_e32 v223, v188
	v_pk_mul_f32 v[162:163], v[212:213], v[162:163]
	ds_bpermute_b32 v216, v240, v214
	v_pk_fma_f32 v[162:163], v[218:219], v[222:223], v[162:163]
	ds_bpermute_b32 v217, v240, v215
	v_pk_add_f32 v[160:161], v[160:161], v[162:163]
	v_mul_f32_e32 v162, v191, v149
	v_pk_fma_f32 v[148:149], v[190:191], v[148:149], v[162:163] op_sel_hi:[1,1,0]
	v_mul_f32_e32 v162, v189, v151
	v_pk_fma_f32 v[150:151], v[188:189], v[150:151], v[162:163] op_sel_hi:[1,1,0]
	v_mov_b32_e32 v149, v221
	v_mov_b32_e32 v151, v33
	v_pk_add_f32 v[148:149], v[148:149], v[150:151]
	v_pk_mov_b32 v[150:151], v[152:153], v[206:207] op_sel:[1,0]
	v_mov_b32_e32 v153, v207
	v_pk_mul_f32 v[152:153], v[206:207], v[152:153]
	v_mov_b32_e32 v33, v193
	v_pk_fma_f32 v[150:151], v[206:207], v[150:151], v[152:153] op_sel:[1,0,0] op_sel_hi:[0,1,1]
	v_pk_mov_b32 v[152:153], v[154:155], v[204:205] op_sel:[1,0]
	v_mov_b32_e32 v155, v205
	v_pk_mul_f32 v[154:155], v[204:205], v[154:155]
	v_pk_add_f32 v[148:149], v[148:149], v[32:33]
	v_pk_fma_f32 v[152:153], v[204:205], v[152:153], v[154:155] op_sel:[1,0,0] op_sel_hi:[0,1,1]
	v_pk_add_f32 v[148:149], v[160:161], v[148:149]
	v_pk_add_f32 v[150:151], v[150:151], v[152:153]
	s_waitcnt lgkmcnt(0)
	v_pk_add_f32 v[214:215], v[214:215], v[216:217]
	v_pk_add_f32 v[148:149], v[148:149], v[150:151]
	v_pk_mov_b32 v[150:151], v[156:157], v[210:211] op_sel:[1,0]
	v_mov_b32_e32 v157, v211
	v_pk_mul_f32 v[152:153], v[210:211], v[156:157]
	ds_bpermute_b32 v216, v239, v214
	v_pk_fma_f32 v[150:151], v[210:211], v[150:151], v[152:153] op_sel:[1,0,0] op_sel_hi:[0,1,1]
	v_pk_mov_b32 v[152:153], v[158:159], v[208:209] op_sel:[1,0]
	v_mov_b32_e32 v159, v209
	v_pk_mul_f32 v[154:155], v[208:209], v[158:159]
	ds_bpermute_b32 v217, v239, v215
	v_pk_fma_f32 v[152:153], v[208:209], v[152:153], v[154:155] op_sel:[1,0,0] op_sel_hi:[0,1,1]
	v_pk_add_f32 v[150:151], v[150:151], v[152:153]
	s_nop 0
	v_pk_add_f32 v[148:149], v[148:149], v[150:151]
	ds_bpermute_b32 v150, v240, v148
	ds_bpermute_b32 v151, v240, v149
	s_waitcnt lgkmcnt(0)
	v_pk_add_f32 v[148:149], v[148:149], v[150:151]
	ds_bpermute_b32 v150, v239, v148
	ds_bpermute_b32 v151, v239, v149
	s_and_saveexec_b64 s[6:7], vcc
	s_cbranch_execz .LBB0_1100
	v_lshl_add_u32 v33, v220, 6, s29
	s_waitcnt lgkmcnt(0)
	v_pk_add_f32 v[150:151], v[148:149], v[150:151]
	v_pk_add_f32 v[148:149], v[214:215], v[216:217]
	ds_write_b128 v33, v[148:151]
.LBB0_1100:
	s_or_b64 exec, exec, s[6:7]
	v_add_u32_e32 v224, 0xa0, v237
	v_add_u32_e32 v190, s17, v224
	v_ashrrev_i32_e32 v191, 31, v190
	v_lshlrev_b64 v[148:149], 12, v[190:191]
	v_lshl_add_u64 v[148:149], s[30:31], 0, v[148:149]
	v_lshl_add_u64 v[188:189], v[34:35], 2, v[148:149]
	s_waitcnt lgkmcnt(0)
	s_add_i32 s98, s72, 0x0
	s_waitcnt vmcnt(7)
	v_and_b32_e32 v148, 63, v228
	v_lshl_add_u32 v148, v148, 4, s98
	ds_read_b128 v[148:151], v148
	s_waitcnt vmcnt(6)
	v_and_b32_e32 v160, 63, v228
	v_lshl_add_u32 v160, v160, 4, s98
	ds_read_b128 v[160:163], v160 offset:1024
	v_pk_mul_f32 v[152:153], v[30:31], v[30:31]
	v_pk_mul_f32 v[154:155], v[28:29], v[28:29]
	v_pk_mul_f32 v[216:217], v[26:27], v[142:143]
	v_pk_mov_b32 v[156:157], v[154:155], v[152:153] op_sel:[1,0]
	v_mov_b32_e32 v155, v153
	v_pk_add_f32 v[218:219], v[156:157], v[154:155]
	v_pk_mul_f32 v[204:205], v[28:29], v[144:145]
	v_pk_add_f32 v[218:219], v[218:219], v[218:219] op_sel:[0,1] op_sel_hi:[1,0]
	v_pk_mul_f32 v[222:223], v[24:25], v[140:141]
	v_pk_mul_f32 v[192:193], v[30:31], v[146:147]
	v_mul_f32_e32 v225, v222, v222
	v_mul_f32_e32 v33, v223, v223
	v_pk_mul_f32 v[210:211], v[20:21], v[136:137]
	v_pk_mul_f32 v[208:209], v[22:23], v[138:139]
	v_pk_mul_f32 v[214:215], v[16:17], v[132:133]
	v_pk_mul_f32 v[212:213], v[18:19], v[134:135]
	s_waitcnt lgkmcnt(1)
	v_pk_mul_f32 v[152:153], v[150:151], v[150:151]
	v_pk_mul_f32 v[154:155], v[148:149], v[148:149]
	s_nop 0
	v_pk_mov_b32 v[156:157], v[154:155], v[152:153] op_sel:[1,0]
	v_mov_b32_e32 v155, v153
	v_pk_add_f32 v[152:153], v[156:157], v[154:155]
	v_pk_mul_f32 v[154:155], v[24:25], v[24:25]
	v_pk_add_f32 v[226:227], v[152:153], v[152:153] op_sel_hi:[0,1]
	v_pk_mul_f32 v[152:153], v[26:27], v[26:27]
	v_mul_f32_e32 v226, v16, v16
	v_pk_mov_b32 v[156:157], v[154:155], v[152:153] op_sel:[1,0]
	v_mov_b32_e32 v155, v153
	v_pk_add_f32 v[220:221], v[156:157], v[154:155]
	s_waitcnt lgkmcnt(0)
;     __device__ __forceinline__ void fused(f32x4 (&acc)[2][2][4][2], const Unit& u, int wr, int wc, int fr, int fq, PG8_LAS unsigned char* lds, int wid, int lane) const {
;     ...
;                     for (int n = 0; n < 2; ++n) { const f32x4 bs = *(const f32x4*)(base + off + bj * HALF + n * 16), a = acc[ai][bj][m][n], ag = a * gv[bj][n];
;                         s0 += (a[0] * a[0] + a[1] * a[1]) + (a[2] * a[2] + a[3] * a[3]); s1 += (bs[0] * bs[0] + bs[1] * bs[1]) + (bs[2] * bs[2] + bs[3] * bs[3]);
;                         s2 += (bs[0] * ag[0] + bs[1] * ag[1]) + (bs[2] * ag[2] + bs[3] * ag[3]); s3 += (ag[0] * ag[0] + ag[1] * ag[1]) + (ag[2] * ag[2] + ag[3] * ag[3]); }
;                 s0 += __shfl_xor(s0, 16); s0 += __shfl_xor(s0, 32); s1 += __shfl_xor(s1, 16); s1 += __shfl_xor(s1, 32);
;                 s2 += __shfl_xor(s2, 16); s2 += __shfl_xor(s2, 32); s3 += __shfl_xor(s3, 16); s3 += __shfl_xor(s3, 32);
;                 if (fq == 0) P[r * 4 + wc] = (f32x4){s0, s1, s2, s3};
	v_pk_mul_f32 v[152:153], v[162:163], v[162:163]
	v_pk_mul_f32 v[154:155], v[160:161], v[160:161]
	v_pk_add_f32 v[220:221], v[220:221], v[220:221] op_sel:[0,1] op_sel_hi:[1,0]
	v_pk_mov_b32 v[156:157], v[154:155], v[152:153] op_sel:[1,0]
	v_mov_b32_e32 v155, v153
	v_pk_add_f32 v[152:153], v[156:157], v[154:155]
	s_nop 0
	v_pk_add_f32 v[242:243], v[152:153], v[152:153] op_sel_hi:[0,1]
	v_mul_f32_e32 v152, v216, v216
	v_pk_fma_f32 v[206:207], v[216:217], v[216:217], v[152:153] op_sel_hi:[1,1,0]
	s_waitcnt vmcnt(5)
	v_and_b32_e32 v152, 63, v228
	v_lshl_add_u32 v152, v152, 4, s98
	ds_read_b128 v[152:155], v152 offset:2048
	v_mul_f32_e32 v242, v17, v17
	v_pk_add_f32 v[226:227], v[226:227], v[242:243]
	v_mul_f32_e32 v206, v21, v21
	s_waitcnt lgkmcnt(0)
	v_mul_f32_e32 v156, v152, v152
	v_pk_fma_f32 v[244:245], v[152:153], v[152:153], v[156:157] op_sel_hi:[1,1,0]
	v_mul_f32_e32 v156, v154, v154
	v_pk_fma_f32 v[246:247], v[154:155], v[154:155], v[156:157] op_sel_hi:[1,1,0]
	s_waitcnt vmcnt(4)
	v_and_b32_e32 v156, 63, v228
	v_lshl_add_u32 v156, v156, 4, s98
	ds_read_b128 v[156:159], v156 offset:3072
	v_mul_f32_e32 v244, v18, v18
	v_mul_f32_e32 v246, v19, v19
	v_pk_add_f32 v[242:243], v[244:245], v[246:247]
	s_waitcnt lgkmcnt(0)
	v_mul_f32_e32 v230, v156, v156
	v_pk_add_f32 v[226:227], v[226:227], v[242:243]
	v_pk_fma_f32 v[242:243], v[20:21], v[20:21], v[206:207] op_sel_hi:[1,1,0]
	v_mul_f32_e32 v206, v23, v23
	v_mul_f32_e32 v241, v157, v157
	v_mul_f32_e32 v248, v158, v158
	v_mul_f32_e32 v249, v159, v159
	v_pk_fma_f32 v[244:245], v[22:23], v[22:23], v[206:207] op_sel_hi:[1,1,0]
	v_mov_b32_e32 v243, v230
	v_mov_b32_e32 v245, v241
	v_mov_b32_e32 v221, v248
	v_mov_b32_e32 v219, v249
	v_pk_add_f32 v[242:243], v[242:243], v[244:245]
	v_pk_add_f32 v[218:219], v[220:221], v[218:219]
	s_nop 0
	v_pk_add_f32 v[218:219], v[242:243], v[218:219]
	v_mov_b32_e32 v242, v160
	v_pk_add_f32 v[218:219], v[226:227], v[218:219]
	v_mov_b32_e32 v226, v222
	v_mov_b32_e32 v222, v223
	v_mov_b32_e32 v223, v205
	v_mov_b32_e32 v160, v161
	v_mov_b32_e32 v161, v205
	v_mov_b32_e32 v227, v204
	v_mov_b32_e32 v243, v204
	v_pk_mul_f32 v[160:161], v[222:223], v[160:161]
	v_mov_b32_e32 v222, v216
	v_pk_fma_f32 v[160:161], v[226:227], v[242:243], v[160:161]
	v_mov_b32_e32 v226, v162
	v_mov_b32_e32 v216, v217
	v_mov_b32_e32 v217, v193
	v_mov_b32_e32 v162, v163
	v_mov_b32_e32 v163, v193
	v_mov_b32_e32 v223, v192
	v_mov_b32_e32 v227, v192
	v_pk_mul_f32 v[162:163], v[216:217], v[162:163]
	ds_bpermute_b32 v220, v240, v218
	v_pk_fma_f32 v[162:163], v[222:223], v[226:227], v[162:163]
	ds_bpermute_b32 v221, v240, v219
	v_pk_add_f32 v[160:161], v[160:161], v[162:163]
	v_mul_f32_e32 v162, v205, v149
	v_pk_fma_f32 v[148:149], v[204:205], v[148:149], v[162:163] op_sel_hi:[1,1,0]
	v_mul_f32_e32 v162, v193, v151
	v_pk_fma_f32 v[150:151], v[192:193], v[150:151], v[162:163] op_sel_hi:[1,1,0]
	v_mov_b32_e32 v149, v225
	v_mov_b32_e32 v151, v33
	v_pk_add_f32 v[148:149], v[148:149], v[150:151]
	v_pk_mov_b32 v[150:151], v[152:153], v[210:211] op_sel:[1,0]
	v_mov_b32_e32 v153, v211
	v_pk_mul_f32 v[152:153], v[210:211], v[152:153]
	v_mov_b32_e32 v33, v207
	v_pk_fma_f32 v[150:151], v[210:211], v[150:151], v[152:153] op_sel:[1,0,0] op_sel_hi:[0,1,1]
	v_pk_mov_b32 v[152:153], v[154:155], v[208:209] op_sel:[1,0]
	v_mov_b32_e32 v155, v209
	v_pk_mul_f32 v[154:155], v[208:209], v[154:155]
	v_pk_add_f32 v[148:149], v[148:149], v[32:33]
	v_pk_fma_f32 v[152:153], v[208:209], v[152:153], v[154:155] op_sel:[1,0,0] op_sel_hi:[0,1,1]
	v_pk_add_f32 v[148:149], v[160:161], v[148:149]
	v_pk_add_f32 v[150:151], v[150:151], v[152:153]
	s_waitcnt lgkmcnt(0)
	v_pk_add_f32 v[218:219], v[218:219], v[220:221]
	v_pk_add_f32 v[148:149], v[148:149], v[150:151]
	v_pk_mov_b32 v[150:151], v[156:157], v[214:215] op_sel:[1,0]
	v_mov_b32_e32 v157, v215
	v_pk_mul_f32 v[152:153], v[214:215], v[156:157]
	ds_bpermute_b32 v220, v239, v218
	v_pk_fma_f32 v[150:151], v[214:215], v[150:151], v[152:153] op_sel:[1,0,0] op_sel_hi:[0,1,1]
	v_pk_mov_b32 v[152:153], v[158:159], v[212:213] op_sel:[1,0]
	v_mov_b32_e32 v159, v213
	v_pk_mul_f32 v[154:155], v[212:213], v[158:159]
	ds_bpermute_b32 v221, v239, v219
	v_pk_fma_f32 v[152:153], v[212:213], v[152:153], v[154:155] op_sel:[1,0,0] op_sel_hi:[0,1,1]
	v_pk_add_f32 v[150:151], v[150:151], v[152:153]
	s_nop 0
	v_pk_add_f32 v[148:149], v[148:149], v[150:151]
	ds_bpermute_b32 v150, v240, v148
	ds_bpermute_b32 v151, v240, v149
	s_waitcnt lgkmcnt(0)
	v_pk_add_f32 v[148:149], v[148:149], v[150:151]
	ds_bpermute_b32 v150, v239, v148
	ds_bpermute_b32 v151, v239, v149
	s_and_saveexec_b64 s[6:7], vcc
	s_cbranch_execz .LBB0_1102
	v_lshl_add_u32 v33, v224, 6, s29
	s_waitcnt lgkmcnt(0)
	v_pk_add_f32 v[150:151], v[148:149], v[150:151]
	v_pk_add_f32 v[148:149], v[218:219], v[220:221]
	ds_write_b128 v33, v[148:151]
;     __device__ __forceinline__ void fused(f32x4 (&acc)[2][2][4][2], const Unit& u, int wr, int wc, int fr, int fq, PG8_LAS unsigned char* lds, int wid, int lane) const {
;     ...
;             for (int m = 0; m < 4; ++m) { const int r = ai * HALF + wr * 64 + m * 16 + fr; const size_t off = (size_t)(u.pm * BM + r) * 1024 + col0;
;                 float s0 = 0.f, s1 = 0.f, s2 = 0.f, s3 = 0.f;
; #pragma unroll
;                 for (int bj = 0; bj < 2; ++bj)
; #pragma unroll
;                     for (int n = 0; n < 2; ++n) { const f32x4 bs = *(const f32x4*)(base + off + bj * HALF + n * 16), a = acc[ai][bj][m][n], ag = a * gv[bj][n];
;                         s0 += (a[0] * a[0] + a[1] * a[1]) + (a[2] * a[2] + a[3] * a[3]); s1 += (bs[0] * bs[0] + bs[1] * bs[1]) + (bs[2] * bs[2] + bs[3] * bs[3]);
;                         s2 += (bs[0] * ag[0] + bs[1] * ag[1]) + (bs[2] * ag[2] + bs[3] * ag[3]); s3 += (ag[0] * ag[0] + ag[1] * ag[1]) + (ag[2] * ag[2] + ag[3] * ag[3]); }
;                 s0 += __shfl_xor(s0, 16); s0 += __shfl_xor(s0, 32); s1 += __shfl_xor(s1, 16); s1 += __shfl_xor(s1, 32);
;                 s2 += __shfl_xor(s2, 16); s2 += __shfl_xor(s2, 32); s3 += __shfl_xor(s3, 16); s3 += __shfl_xor(s3, 32);
;                 if (fq == 0) P[r * 4 + wc] = (f32x4){s0, s1, s2, s3};
.LBB0_1102:
	s_or_b64 exec, exec, s[6:7]
	v_add_u32_e32 v241, 0xb0, v237
	v_add_u32_e32 v204, s17, v241
	v_ashrrev_i32_e32 v205, 31, v204
	v_lshlrev_b64 v[148:149], 12, v[204:205]
	v_lshl_add_u64 v[148:149], s[30:31], 0, v[148:149]
	v_lshl_add_u64 v[192:193], v[34:35], 2, v[148:149]
	s_waitcnt lgkmcnt(0)
	s_add_i32 s98, s72, 0x1000
	s_waitcnt vmcnt(3)
	v_and_b32_e32 v148, 63, v228
	v_lshl_add_u32 v148, v148, 4, s98
	ds_read_b128 v[148:151], v148
	s_waitcnt vmcnt(2)
	v_and_b32_e32 v160, 63, v228
	v_lshl_add_u32 v160, v160, 4, s98
	ds_read_b128 v[160:163], v160 offset:1024
	v_pk_mul_f32 v[152:153], v[14:15], v[14:15]
	v_pk_mul_f32 v[154:155], v[12:13], v[12:13]
	v_pk_mul_f32 v[220:221], v[10:11], v[142:143]
	v_pk_mov_b32 v[156:157], v[154:155], v[152:153] op_sel:[1,0]
	v_mov_b32_e32 v155, v153
	v_pk_add_f32 v[222:223], v[156:157], v[154:155]
	v_pk_mul_f32 v[208:209], v[12:13], v[144:145]
	v_pk_add_f32 v[222:223], v[222:223], v[222:223] op_sel:[0,1] op_sel_hi:[1,0]
	v_pk_mul_f32 v[226:227], v[8:9], v[140:141]
	v_pk_mul_f32 v[206:207], v[14:15], v[146:147]
	v_mul_f32_e32 v242, v226, v226
	v_mul_f32_e32 v33, v227, v227
	v_pk_mul_f32 v[214:215], v[4:5], v[136:137]
	v_pk_mul_f32 v[212:213], v[6:7], v[138:139]
	v_pk_mul_f32 v[218:219], v[0:1], v[132:133]
	v_pk_mul_f32 v[216:217], v[2:3], v[134:135]
	s_waitcnt lgkmcnt(1)
	v_pk_mul_f32 v[152:153], v[150:151], v[150:151]
	v_pk_mul_f32 v[154:155], v[148:149], v[148:149]
	s_nop 0
	v_pk_mov_b32 v[156:157], v[154:155], v[152:153] op_sel:[1,0]
	v_mov_b32_e32 v155, v153
	v_pk_add_f32 v[152:153], v[156:157], v[154:155]
	v_pk_mul_f32 v[154:155], v[8:9], v[8:9]
	v_pk_add_f32 v[244:245], v[152:153], v[152:153] op_sel_hi:[0,1]
	v_pk_mul_f32 v[152:153], v[10:11], v[10:11]
	v_mul_f32_e32 v244, v0, v0
	v_pk_mov_b32 v[156:157], v[154:155], v[152:153] op_sel:[1,0]
	v_mov_b32_e32 v155, v153
	v_pk_add_f32 v[224:225], v[156:157], v[154:155]
	s_waitcnt lgkmcnt(0)
	v_pk_mul_f32 v[152:153], v[162:163], v[162:163]
	v_pk_mul_f32 v[154:155], v[160:161], v[160:161]
	v_pk_add_f32 v[224:225], v[224:225], v[224:225] op_sel:[0,1] op_sel_hi:[1,0]
	v_pk_mov_b32 v[156:157], v[154:155], v[152:153] op_sel:[1,0]
	v_mov_b32_e32 v155, v153
	v_pk_add_f32 v[152:153], v[156:157], v[154:155]
	s_nop 0
	v_pk_add_f32 v[246:247], v[152:153], v[152:153] op_sel_hi:[0,1]
	v_mul_f32_e32 v152, v220, v220
	v_pk_fma_f32 v[210:211], v[220:221], v[220:221], v[152:153] op_sel_hi:[1,1,0]
	s_waitcnt vmcnt(1)
	v_and_b32_e32 v152, 63, v228
	v_lshl_add_u32 v152, v152, 4, s98
	ds_read_b128 v[152:155], v152 offset:2048
	v_mul_f32_e32 v246, v1, v1
	v_pk_add_f32 v[244:245], v[244:245], v[246:247]
	v_mul_f32_e32 v210, v5, v5
	s_waitcnt lgkmcnt(0)
	v_mul_f32_e32 v156, v152, v152
	v_pk_fma_f32 v[248:249], v[152:153], v[152:153], v[156:157] op_sel_hi:[1,1,0]
	v_mul_f32_e32 v156, v154, v154
	v_pk_fma_f32 v[250:251], v[154:155], v[154:155], v[156:157] op_sel_hi:[1,1,0]
	s_waitcnt vmcnt(0)
	v_and_b32_e32 v156, 63, v228
	v_lshl_add_u32 v156, v156, 4, s98
	ds_read_b128 v[156:159], v156 offset:3072
	v_mul_f32_e32 v248, v2, v2
	v_mul_f32_e32 v250, v3, v3
	v_pk_add_f32 v[246:247], v[248:249], v[250:251]
	s_waitcnt lgkmcnt(0)
	v_mul_f32_e32 v230, v156, v156
	v_pk_add_f32 v[244:245], v[244:245], v[246:247]
	v_pk_fma_f32 v[246:247], v[4:5], v[4:5], v[210:211] op_sel_hi:[1,1,0]
	v_mul_f32_e32 v210, v7, v7
	v_mul_f32_e32 v243, v157, v157
	v_mul_f32_e32 v252, v158, v158
	v_mul_f32_e32 v253, v159, v159
	v_pk_fma_f32 v[248:249], v[6:7], v[6:7], v[210:211] op_sel_hi:[1,1,0]
	v_mov_b32_e32 v247, v230
	v_mov_b32_e32 v249, v243
	v_mov_b32_e32 v225, v252
	v_mov_b32_e32 v223, v253
	v_pk_add_f32 v[246:247], v[246:247], v[248:249]
	v_pk_add_f32 v[222:223], v[224:225], v[222:223]
	s_nop 0
	v_pk_add_f32 v[222:223], v[246:247], v[222:223]
	v_mov_b32_e32 v246, v160
	v_pk_add_f32 v[222:223], v[244:245], v[222:223]
	v_mov_b32_e32 v244, v226
	v_mov_b32_e32 v226, v227
	v_mov_b32_e32 v227, v209
	v_mov_b32_e32 v160, v161
	v_mov_b32_e32 v161, v209
	v_mov_b32_e32 v245, v208
	v_mov_b32_e32 v247, v208
	v_pk_mul_f32 v[160:161], v[226:227], v[160:161]
	v_mov_b32_e32 v226, v220
	v_pk_fma_f32 v[160:161], v[244:245], v[246:247], v[160:161]
	v_mov_b32_e32 v244, v162
	v_mov_b32_e32 v220, v221
	v_mov_b32_e32 v221, v207
	v_mov_b32_e32 v162, v163
	v_mov_b32_e32 v163, v207
	v_mov_b32_e32 v227, v206
	v_mov_b32_e32 v245, v206
	v_pk_mul_f32 v[162:163], v[220:221], v[162:163]
	ds_bpermute_b32 v224, v240, v222
	v_pk_fma_f32 v[162:163], v[226:227], v[244:245], v[162:163]
	ds_bpermute_b32 v225, v240, v223
	v_pk_add_f32 v[160:161], v[160:161], v[162:163]
	v_mul_f32_e32 v162, v209, v149
	v_pk_fma_f32 v[148:149], v[208:209], v[148:149], v[162:163] op_sel_hi:[1,1,0]
	v_mul_f32_e32 v162, v207, v151
	v_pk_fma_f32 v[150:151], v[206:207], v[150:151], v[162:163] op_sel_hi:[1,1,0]
	v_mov_b32_e32 v149, v242
	v_mov_b32_e32 v151, v33
	v_pk_add_f32 v[148:149], v[148:149], v[150:151]
	v_pk_mov_b32 v[150:151], v[152:153], v[214:215] op_sel:[1,0]
	v_mov_b32_e32 v153, v215
	v_pk_mul_f32 v[152:153], v[214:215], v[152:153]
	v_mov_b32_e32 v33, v211
	v_pk_fma_f32 v[150:151], v[214:215], v[150:151], v[152:153] op_sel:[1,0,0] op_sel_hi:[0,1,1]
	v_pk_mov_b32 v[152:153], v[154:155], v[212:213] op_sel:[1,0]
	v_mov_b32_e32 v155, v213
	v_pk_mul_f32 v[154:155], v[212:213], v[154:155]
	v_pk_add_f32 v[148:149], v[148:149], v[32:33]
	v_pk_fma_f32 v[152:153], v[212:213], v[152:153], v[154:155] op_sel:[1,0,0] op_sel_hi:[0,1,1]
	v_pk_add_f32 v[148:149], v[160:161], v[148:149]
	v_pk_add_f32 v[150:151], v[150:151], v[152:153]
	s_waitcnt lgkmcnt(0)
	v_pk_add_f32 v[222:223], v[222:223], v[224:225]
	v_pk_add_f32 v[148:149], v[148:149], v[150:151]
	v_pk_mov_b32 v[150:151], v[156:157], v[218:219] op_sel:[1,0]
	v_mov_b32_e32 v157, v219
	v_pk_mul_f32 v[152:153], v[218:219], v[156:157]
	ds_bpermute_b32 v224, v239, v222
	v_pk_fma_f32 v[150:151], v[218:219], v[150:151], v[152:153] op_sel:[1,0,0] op_sel_hi:[0,1,1]
	v_pk_mov_b32 v[152:153], v[158:159], v[216:217] op_sel:[1,0]
	v_mov_b32_e32 v159, v217
	v_pk_mul_f32 v[154:155], v[216:217], v[158:159]
	ds_bpermute_b32 v225, v239, v223
	v_pk_fma_f32 v[152:153], v[216:217], v[152:153], v[154:155] op_sel:[1,0,0] op_sel_hi:[0,1,1]
	v_pk_add_f32 v[150:151], v[150:151], v[152:153]
	s_nop 0
	v_pk_add_f32 v[148:149], v[148:149], v[150:151]
	ds_bpermute_b32 v150, v240, v148
	ds_bpermute_b32 v151, v240, v149
	s_waitcnt lgkmcnt(0)
	v_pk_add_f32 v[148:149], v[148:149], v[150:151]
	ds_bpermute_b32 v150, v239, v148
	ds_bpermute_b32 v151, v239, v149
	s_and_saveexec_b64 s[6:7], vcc
	s_cbranch_execz .LBB0_1104
	v_lshl_add_u32 v33, v241, 6, s29
	s_waitcnt lgkmcnt(0)
	v_pk_add_f32 v[150:151], v[148:149], v[150:151]
	v_pk_add_f32 v[148:149], v[222:223], v[224:225]
	ds_write_b128 v33, v[148:151]
